# attention: softmax scale folded into q/k producers and running max carried in the QK MFMA C operand (no per-score FMA)
# speedup vs baseline: 1.0364x; 1.0199x over previous
; template <bool MLA>
; DI void attn_phase(const int TID, const int BID, LAS unsigned char* lds, const Params& p, bool need_ctx) {
;     ...
;     const int tid = TID, wid = tid >> 6, lane = tid & 63, r = lane & 31, hh = lane >> 5;
;     const int n_items = 1024 + (need_ctx ? 128 : 0);
;     bf16_t* O = P_WSB(OFF_H);
;     for (int item = BID; item < n_items; item += gridDim.x) {
;         int b, head, row0, nk;
;         if (item < 1024) {
;             const int rnd = item >> 8, w = item & 255, xcd = w & 7, slot = w >> 3, qb = slot & 7;
;             if (MLA) { const int grp = (rnd * 8 + xcd) * 4 + (slot >> 3); b = grp >> 4; head = grp & 15; }
;             else { const int grp = rnd * 8 + xcd; b = grp >> 2; head = (grp & 3) * 4 + (slot >> 3); }
;             row0 = b * 2048 + qb * 256; nk = NKEY;
;         }
;         else { const int it = item - 1024; b = it >> 4; head = it & 15; row0 = TL + b * 256; nk = 256; }
;         const int kvh = MLA ? head : (head >> 2);
;         const bf16_t* Kb = P_WSB(OFF_K) + (size_t)(b * NKV + kvh) * NKEY * 64;
;         const bf16_t* Vb = P_WSB(OFF_VT) + (size_t)(b * NKV + kvh) * NKEY * 64;
;         const bf16_t* Pb = P_WSB(OFF_KPE) + (size_t)b * NKEY * 32;
;         bf16x8 qf[NKS];
;         {
;             const bf16_t* qp = P_WSB(OFF_Q) + (size_t)(row0 + wid * 32 + r) * QS + head * DK + hh * 8;
; #pragma unroll
;             for (int ks = 0; ks < NKS; ++ks) qf[ks] = *(const bf16x8*)(qp + ks * 16);
;         }
;         u32x4 kreg, vreg; u32x2 preg = {0u, 0u};
.LBB0_293:
	s_andn2_b64 vcc, exec, s[0:1]
	s_cbranch_vccnz .LBB0_773
	s_add_i32 s0, s23, 0x22040
	v_writelane_b32 v255, s0, 32
	s_nop 0
	v_readlane_b32 s0, v255, 21
	s_cmp_lt_i32 s0, 2
	s_mov_b64 s[0:1], -1
	s_cbranch_scc1 .LBB0_501
	v_readlane_b32 s0, v255, 21
	s_cmp_gt_i32 s0, 2
	v_readlane_b32 s0, v255, 24
	v_readlane_b32 s1, v255, 25
	s_mov_b64 s[2:3], -1
	s_nop 0
	v_cndmask_b32_e64 v0, 0, 1, s[0:1]
	v_cmp_ne_u32_e64 s[0:1], 1, v0
	s_cbranch_scc0 .LBB0_340
	v_readlane_b32 s2, v255, 27
	s_cmp_lt_i32 s2, 3
	s_movk_i32 s2, 0x480
	s_cselect_b32 s8, s2, 0x400
	v_readlane_b32 s3, v255, 28
	s_cmp_lt_i32 s83, s8
	s_cselect_b64 s[2:3], -1, 0
	v_cndmask_b32_e64 v0, 0, 1, s[2:3]
	s_mov_b64 s[4:5], -1
	s_and_b64 vcc, exec, s[0:1]
	v_cmp_ne_u32_e64 s[2:3], 1, v0
	s_cbranch_vccnz .LBB0_318
	s_and_b64 vcc, exec, s[2:3]
	s_cbranch_vccnz .LBB0_317
	v_and_b32_e32 v208, 31, v174
	v_bfe_u32 v209, v174, 5, 1
	v_lshrrev_b32_e32 v210, 6, v174
	v_lshrrev_b32_e32 v211, 3, v174
	v_and_b32_e32 v212, 7, v174
	v_mov_b32_e32 v213, s23
	s_movk_i32 s15, 0xd0
	v_mad_u32_u24 v243, v208, s15, v213
	v_lshl_add_u32 v243, v209, 4, v243
	v_mad_u32_u24 v238, v211, s15, v213
	v_lshl_add_u32 v239, v212, 3, v238
	v_add_u32_e32 v239, 0x80, v239
	v_lshl_add_u32 v238, v212, 4, v238
	s_movk_i32 s15, 0xc0
	v_bfe_u32 v214, v174, 2, 2
	v_lshl_add_u32 v214, v209, 2, v214
	v_mad_u32_u24 v240, v214, s15, v213
	v_bfe_u32 v215, v174, 4, 1
	v_and_b32_e32 v216, 3, v174
	v_lshlrev_b32_e32 v215, 5, v215
	v_lshl_add_u32 v215, v216, 3, v215
	v_add_u32_e32 v240, v240, v215
	v_add_u32_e32 v240, 0x6800, v240
	v_mad_u32_u24 v241, v211, s15, v213
	v_lshl_add_u32 v241, v212, 4, v241
	v_add_u32_e32 v241, 0x6800, v241
	v_lshlrev_b32_e32 v167, 7, v211
	v_lshl_add_u32 v167, v212, 4, v167
	v_lshlrev_b32_e32 v165, 6, v211
	v_lshl_add_u32 v165, v212, 3, v165
	v_lshl_add_u32 v217, v210, 5, v208
	s_movk_i32 s15, 0xc00
	v_mul_u32_u24_e32 v171, s15, v217
	v_lshl_add_u32 v171, v209, 4, v171
	v_lshlrev_b32_e32 v172, 11, v217
	v_lshl_add_u32 v172, v209, 4, v172
	v_and_b32_e32 v214, 15, v174
	v_bfe_u32 v215, v174, 4, 1
	v_cmp_eq_u32_e32 vcc, v214, v215
	v_mov_b32_e32 v216, 0x3f803f80
	s_nop 1
	v_cndmask_b32_e32 v246, 0, v216, vcc
	v_cndmask_b32_e32 v247, 0, v216, vcc
	v_cndmask_b32_e32 v248, 0, v216, vcc
	v_cndmask_b32_e32 v249, 0, v216, vcc
	v_lshlrev_b32_e32 v175, 2, v214
	v_readfirstlane_b32 s58, v210
	s_mov_b32 s6, s83
	s_lshr_b32 s58, s58, 2
	s_cmpk_gt_i32 s6, 0x3ff
	s_cbranch_scc0 .Lamla_mainitem_first
	s_add_i32 s21, s6, 0xfffffc00
	s_lshr_b32 s15, s21, 4
	s_and_b32 s18, s21, 15
	s_lshl_b32 s20, s15, 8
	s_add_i32 s20, s20, 0x4000
	s_mov_b32 s7, 0
	s_branch .Lamla_decoded_first

; #define AT_GLOADK(k0) do { kreg = *(const u32x4*)(Kb + (size_t)((k0) + (tid >> 3)) * 64 + (tid & 7) * 8); \
;             if (MLA) preg = *(const u32x2*)(Pb + (size_t)((k0) + (tid >> 3)) * 32 + (tid & 7) * 4); } while (0)
; #define AT_GLOADV(k0) do { vreg = *(const u32x4*)(Vb + (size_t)((k0) + (tid >> 3)) * 64 + (tid & 7) * 8); } while (0)
; #define AT_WRITEK(buf) do { *(LAS u32x4*)(lds + (buf) * KBUF + (tid >> 3) * KSTR + (tid & 7) * 16) = kreg; \
;             if (MLA) *(LAS u32x2*)(lds + (buf) * KBUF + (tid >> 3) * KSTR + 128 + (tid & 7) * 8) = preg; } while (0)
; template <bool MLA>
; DI void attn_phase(const int TID, const int BID, LAS unsigned char* lds, const Params& p, bool need_ctx) {
;     ...
;         int b, head, row0, nk;
;         if (item < 1024) {
;             const int rnd = item >> 8, w = item & 255, xcd = w & 7, slot = w >> 3, qb = slot & 7;
;             if (MLA) { const int grp = (rnd * 8 + xcd) * 4 + (slot >> 3); b = grp >> 4; head = grp & 15; }
;             else { const int grp = rnd * 8 + xcd; b = grp >> 2; head = (grp & 3) * 4 + (slot >> 3); }
;             row0 = b * 2048 + qb * 256; nk = NKEY;
;         }
;         else { const int it = item - 1024; b = it >> 4; head = it & 15; row0 = TL + b * 256; nk = 256; }
;         const int kvh = MLA ? head : (head >> 2);
;         const bf16_t* Kb = P_WSB(OFF_K) + (size_t)(b * NKV + kvh) * NKEY * 64;
;         const bf16_t* Vb = P_WSB(OFF_VT) + (size_t)(b * NKV + kvh) * NKEY * 64;
;         const bf16_t* Pb = P_WSB(OFF_KPE) + (size_t)b * NKEY * 32;
;         bf16x8 qf[NKS];
;         {
;             const bf16_t* qp = P_WSB(OFF_Q) + (size_t)(row0 + wid * 32 + r) * QS + head * DK + hh * 8;
; #pragma unroll
;             for (int ks = 0; ks < NKS; ++ks) qf[ks] = *(const bf16x8*)(qp + ks * 16);
;         }
;         u32x4 kreg, vreg; u32x2 preg = {0u, 0u};
;     ...
;         f32x16 o0, o1, sa0, sa1, sb0, sb1;
; #pragma unroll
;         for (int j = 0; j < 16; ++j) { o0[j] = 0.f; o1[j] = 0.f; }
;         float mrun = -1e30f, lsum = 0.f;
;         if (wid >= 4) __builtin_amdgcn_s_setprio(1);
;         const int ntile = nk >> 6;
;         AT_GLOADK(0); AT_GLOADV(0); AT_WRITEK(0); AT_WRITEV(0);
;         AT_GLOADK(64); AT_WRITEK(1);
;         __syncthreads();
;         AT_QK(sa0, sa1, 0);
;         __syncthreads();
.Lamla_decoded_first:
	s_mov_b32 s19, s18
	s_lshl_b32 s21, s15, 4
	s_add_i32 s21, s21, s19
	s_mul_i32 s21, s21, 0x48000
	s_add_u32 s2, s26, s21
	s_addc_u32 s3, s27, 0
	v_readlane_b32 s60, v254, 36
	v_readlane_b32 s61, v254, 37
	s_add_u32 s4, s60, s21
	s_addc_u32 s5, s61, 0
	v_readlane_b32 s60, v254, 38
	v_readlane_b32 s61, v254, 39
	s_mul_i32 s21, s15, 0x24000
	s_add_u32 s10, s60, s21
	s_addc_u32 s11, s61, 0
	v_readlane_b32 s60, v254, 27
	v_readlane_b32 s61, v254, 28
	s_mul_i32 s21, s20, 0xc00
	s_mul_i32 s55, s18, 0xc0
	s_add_i32 s21, s21, s55
	s_add_u32 s12, s60, s21
	s_addc_u32 s13, s61, 0
	v_readlane_b32 s60, v254, 34
	v_readlane_b32 s61, v254, 35
	s_lshl_b32 s21, s20, 11
	s_lshl_b32 s55, s18, 7
	s_add_i32 s21, s21, s55
	s_add_u32 s16, s60, s21
	s_addc_u32 s17, s61, 0
	global_load_dwordx4 v[112:115], v171, s[12:13]
	global_load_dwordx4 v[116:119], v171, s[12:13] offset:32
	global_load_dwordx4 v[120:123], v171, s[12:13] offset:64
	global_load_dwordx4 v[124:127], v171, s[12:13] offset:96
	global_load_dwordx4 v[128:131], v171, s[12:13] offset:128
	global_load_dwordx4 v[132:135], v171, s[12:13] offset:160
	global_load_dwordx4 v[136:139], v167, s[2:3]
	global_load_dwordx2 v[208:209], v165, s[10:11]
	s_add_u32 s2, s2, 0x2000
	s_addc_u32 s3, s3, 0
	s_add_u32 s10, s10, 0x1000
	s_addc_u32 s11, s11, 0
	global_load_dwordx4 v[140:143], v167, s[2:3]
	global_load_dwordx2 v[210:211], v165, s[10:11]
	s_add_u32 s2, s2, 0x2000
	s_addc_u32 s3, s3, 0
	s_add_u32 s10, s10, 0x1000
	s_addc_u32 s11, s11, 0
	global_load_dwordx4 v[144:147], v167, s[4:5]
	s_add_u32 s4, s4, 0x2000
	s_addc_u32 s5, s5, 0
	global_load_dwordx4 v[152:155], v167, s[2:3]
	global_load_dwordx2 v[160:161], v165, s[10:11]
	s_add_u32 s2, s2, 0x2000
	s_addc_u32 s3, s3, 0
	s_add_u32 s10, s10, 0x1000
	s_addc_u32 s11, s11, 0
	global_load_dwordx4 v[156:159], v167, s[4:5]
	s_add_u32 s4, s4, 0x2000
	s_addc_u32 s5, s5, 0
.Lamla_item:
	s_mov_b32 s52, 0x3000
	s_mov_b32 s53, 0x6000
	s_mov_b32 s54, 0
	v_mov_b64_e32 v[0:1], 0
	v_mov_b64_e32 v[2:3], 0
	v_mov_b64_e32 v[4:5], 0
	v_mov_b64_e32 v[6:7], 0
	v_mov_b64_e32 v[8:9], 0
	v_mov_b64_e32 v[10:11], 0
	v_mov_b64_e32 v[12:13], 0
	v_mov_b64_e32 v[14:15], 0
	v_mov_b64_e32 v[16:17], 0
	v_mov_b64_e32 v[18:19], 0
	v_mov_b64_e32 v[20:21], 0
	v_mov_b64_e32 v[22:23], 0
	v_mov_b64_e32 v[24:25], 0
	v_mov_b64_e32 v[26:27], 0
	v_mov_b64_e32 v[28:29], 0
	v_mov_b64_e32 v[30:31], 0
	v_mov_b64_e32 v[218:219], 0
	v_mov_b64_e32 v[220:221], 0
	v_mov_b64_e32 v[222:223], 0
	v_mov_b64_e32 v[224:225], 0
	v_mov_b64_e32 v[226:227], 0
	v_mov_b64_e32 v[228:229], 0
	v_mov_b64_e32 v[230:231], 0
	v_mov_b64_e32 v[232:233], 0
	v_mov_b64_e32 v[234:235], 0
	v_mov_b64_e32 v[236:237], 0
	s_barrier
	s_waitcnt vmcnt(7)
	ds_write_b128 v238, v[136:139]
	s_waitcnt vmcnt(6)
	ds_write_b64 v239, v[208:209]
	s_waitcnt vmcnt(5)
	ds_write_b128 v238, v[140:143] offset:13312
	s_waitcnt vmcnt(4)
	ds_write_b64 v239, v[210:211] offset:13312
	s_waitcnt vmcnt(3)
	ds_write_b128 v241, v[144:147]
	s_waitcnt lgkmcnt(0)
	s_barrier
	s_cmp_eq_u32 s58, 0
	s_cbranch_scc1 .Lamla_prio
	s_setprio 1
.Lamla_prio:
	ds_read_b128 v[136:139], v243 offset:0
	ds_read_b128 v[140:143], v243 offset:6656
	ds_read_b128 v[144:147], v243 offset:32
	ds_read_b128 v[148:151], v243 offset:6688
	s_waitcnt lgkmcnt(3)
	v_mfma_f32_32x32x16_bf16 v[32:47], v[136:139], v[112:115], 0
	ds_read_b128 v[136:139], v243 offset:64
	s_waitcnt lgkmcnt(3)
	v_mfma_f32_32x32x16_bf16 v[48:63], v[140:143], v[112:115], 0
	ds_read_b128 v[140:143], v243 offset:6720
	s_waitcnt lgkmcnt(3)
	v_mfma_f32_32x32x16_bf16 v[32:47], v[144:147], v[116:119], v[32:47]
	ds_read_b128 v[144:147], v243 offset:96
	s_waitcnt lgkmcnt(3)
	v_mfma_f32_32x32x16_bf16 v[48:63], v[148:151], v[116:119], v[48:63]
	ds_read_b128 v[148:151], v243 offset:6752
	s_waitcnt lgkmcnt(3)
	v_mfma_f32_32x32x16_bf16 v[32:47], v[136:139], v[120:123], v[32:47]
	ds_read_b128 v[136:139], v243 offset:128
	s_waitcnt lgkmcnt(3)
	v_mfma_f32_32x32x16_bf16 v[48:63], v[140:143], v[120:123], v[48:63]
	ds_read_b128 v[140:143], v243 offset:6784
	s_waitcnt lgkmcnt(3)
	v_mfma_f32_32x32x16_bf16 v[32:47], v[144:147], v[124:127], v[32:47]
	ds_read_b128 v[144:147], v243 offset:160
	s_waitcnt lgkmcnt(3)
	v_mfma_f32_32x32x16_bf16 v[48:63], v[148:151], v[124:127], v[48:63]
	ds_read_b128 v[148:151], v243 offset:6816
	s_waitcnt lgkmcnt(3)
	v_mfma_f32_32x32x16_bf16 v[32:47], v[136:139], v[128:131], v[32:47]
	s_waitcnt lgkmcnt(2)
	v_mfma_f32_32x32x16_bf16 v[48:63], v[140:143], v[128:131], v[48:63]
	s_waitcnt lgkmcnt(1)
	v_mfma_f32_32x32x16_bf16 v[32:47], v[144:147], v[132:135], v[32:47]
	s_waitcnt lgkmcnt(0)
	v_mfma_f32_32x32x16_bf16 v[48:63], v[148:151], v[132:135], v[48:63]
	s_waitcnt lgkmcnt(0)
	s_nop 7
	s_barrier
	ds_read_b128 v[136:139], v243 offset:13312
	ds_read_b128 v[140:143], v243 offset:19968
	ds_read_b128 v[144:147], v243 offset:13344
	ds_read_b128 v[148:151], v243 offset:20000
	v_max3_f32 v168, v32, v33, v34
	v_max3_f32 v170, v48, v49, v50
	v_max3_f32 v168, v168, v35, v36
	v_max3_f32 v170, v170, v51, v52
	v_max3_f32 v168, v168, v37, v38
	v_max3_f32 v170, v170, v53, v54
	v_max3_f32 v168, v168, v39, v40
	v_max3_f32 v170, v170, v55, v56
	v_max3_f32 v168, v168, v41, v42
	v_max3_f32 v170, v170, v57, v58
	v_max3_f32 v168, v168, v43, v44
	v_max3_f32 v170, v170, v59, v60
	v_max3_f32 v168, v168, v45, v46
	v_max3_f32 v170, v170, v61, v62
	v_max_f32_e32 v168, v168, v47
	v_max_f32_e32 v170, v170, v63
	v_max_f32_e32 v168, v168, v170
	v_mov_b32_e32 v170, v168
	s_nop 1
	v_permlane32_swap_b32_e32 v168, v170
	v_max_f32_e32 v168, v168, v170
	v_mov_b32_e32 v170, v168
	v_sub_f32_e32 v218, v218, v170
	v_sub_f32_e32 v219, v219, v170
	v_sub_f32_e32 v220, v220, v170
	v_sub_f32_e32 v221, v221, v170
	v_sub_f32_e32 v222, v222, v170
	v_sub_f32_e32 v223, v223, v170
	v_sub_f32_e32 v224, v224, v170
	v_sub_f32_e32 v225, v225, v170
	v_sub_f32_e32 v226, v226, v170
	v_sub_f32_e32 v227, v227, v170
	v_sub_f32_e32 v228, v228, v170
	v_sub_f32_e32 v229, v229, v170
	v_sub_f32_e32 v230, v230, v170
	v_sub_f32_e32 v231, v231, v170
	v_sub_f32_e32 v232, v232, v170
	v_sub_f32_e32 v233, v233, v170
	v_sub_f32_e32 v32, v32, v170
	v_sub_f32_e32 v33, v33, v170
	v_sub_f32_e32 v34, v34, v170
	v_sub_f32_e32 v35, v35, v170
	v_sub_f32_e32 v36, v36, v170
	v_sub_f32_e32 v37, v37, v170
	v_sub_f32_e32 v38, v38, v170
	v_sub_f32_e32 v39, v39, v170
	v_sub_f32_e32 v40, v40, v170
	v_sub_f32_e32 v41, v41, v170
	v_sub_f32_e32 v42, v42, v170
	v_sub_f32_e32 v43, v43, v170
	v_sub_f32_e32 v44, v44, v170
	v_sub_f32_e32 v45, v45, v170
	v_sub_f32_e32 v46, v46, v170
	v_sub_f32_e32 v47, v47, v170
	v_sub_f32_e32 v48, v48, v170
	v_sub_f32_e32 v49, v49, v170
	v_sub_f32_e32 v50, v50, v170
	v_sub_f32_e32 v51, v51, v170
	v_sub_f32_e32 v52, v52, v170
	v_sub_f32_e32 v53, v53, v170
	v_sub_f32_e32 v54, v54, v170
	v_sub_f32_e32 v55, v55, v170
	v_sub_f32_e32 v56, v56, v170
	v_sub_f32_e32 v57, v57, v170
	v_sub_f32_e32 v58, v58, v170
	v_sub_f32_e32 v59, v59, v170
	v_sub_f32_e32 v60, v60, v170
	v_sub_f32_e32 v61, v61, v170
	v_sub_f32_e32 v62, v62, v170
	v_sub_f32_e32 v63, v63, v170
	s_waitcnt lgkmcnt(3)
	v_mfma_f32_32x32x16_bf16 v[64:79], v[136:139], v[112:115], v[218:233]
	v_exp_f32_e32 v32, v32
	v_exp_f32_e32 v48, v48
	v_exp_f32_e32 v33, v33
	v_exp_f32_e32 v49, v49
	v_exp_f32_e32 v34, v34
	ds_read_b128 v[136:139], v243 offset:13376
	s_mov_b32 s55, s52
	s_mov_b32 s52, s53
	s_mov_b32 s53, s54
	s_mov_b32 s54, s55
	s_mov_b32 s9, 0
	s_waitcnt lgkmcnt(3)
	v_mfma_f32_32x32x16_bf16 v[80:95], v[140:143], v[112:115], v[218:233]
	v_exp_f32_e32 v50, v50
	v_cvt_pk_bf16_f32 v96, v32, v33
	v_cvt_pk_bf16_f32 v104, v48, v49
	v_exp_f32_e32 v35, v35
	v_exp_f32_e32 v51, v51
	ds_read_b128 v[140:143], v243 offset:20032
	global_load_dwordx4 v[208:211], v167, s[2:3]
	global_load_dwordx2 v[216:217], v165, s[10:11]
	global_load_dwordx4 v[212:215], v167, s[4:5]
	s_add_u32 s2, s2, 0x2000
	s_addc_u32 s3, s3, 0
	s_add_u32 s10, s10, 0x1000
	s_addc_u32 s11, s11, 0
	s_add_u32 s4, s4, 0x2000
	s_addc_u32 s5, s5, 0
	v_add_u32_e32 v163, s53, v240
	v_add_u32_e32 v164, s54, v241
	s_waitcnt lgkmcnt(3)
	v_mfma_f32_32x32x16_bf16 v[64:79], v[144:147], v[116:119], v[64:79]
	v_exp_f32_e32 v36, v36
	v_exp_f32_e32 v52, v52
	v_cvt_pk_bf16_f32 v97, v34, v35
	v_cvt_pk_bf16_f32 v105, v50, v51
	v_exp_f32_e32 v37, v37
	ds_read_b128 v[144:147], v243 offset:13408
	s_waitcnt lgkmcnt(3)
	v_mfma_f32_32x32x16_bf16 v[80:95], v[148:151], v[116:119], v[80:95]
	v_exp_f32_e32 v53, v53
	v_exp_f32_e32 v38, v38
	v_exp_f32_e32 v54, v54
	v_cvt_pk_bf16_f32 v98, v36, v37
	v_cvt_pk_bf16_f32 v106, v52, v53
	ds_read_b128 v[148:151], v243 offset:20064
	s_waitcnt lgkmcnt(3)
	v_mfma_f32_32x32x16_bf16 v[64:79], v[136:139], v[120:123], v[64:79]
	v_exp_f32_e32 v39, v39
	v_exp_f32_e32 v55, v55
	v_exp_f32_e32 v40, v40
	v_exp_f32_e32 v56, v56
	v_cvt_pk_bf16_f32 v99, v38, v39
	ds_read_b128 v[136:139], v243 offset:13440
	s_waitcnt lgkmcnt(3)
	v_mfma_f32_32x32x16_bf16 v[80:95], v[140:143], v[120:123], v[80:95]
	v_cvt_pk_bf16_f32 v107, v54, v55
	v_exp_f32_e32 v41, v41
	v_exp_f32_e32 v57, v57
	v_exp_f32_e32 v42, v42
	v_exp_f32_e32 v58, v58
	ds_read_b128 v[140:143], v243 offset:20096
	s_waitcnt lgkmcnt(3)
	v_mfma_f32_32x32x16_bf16 v[64:79], v[144:147], v[124:127], v[64:79]
	v_cvt_pk_bf16_f32 v100, v40, v41
	v_cvt_pk_bf16_f32 v108, v56, v57
	v_exp_f32_e32 v43, v43
	v_exp_f32_e32 v59, v59
	v_exp_f32_e32 v44, v44
	ds_read_b128 v[144:147], v243 offset:13472
	ds_read_b64_tr_b16 v[176:177], v163 offset:0
	ds_read_b64_tr_b16 v[178:179], v163 offset:1536
	s_waitcnt vmcnt(5)
	ds_write_b128 v238, v[152:155]
	s_waitcnt vmcnt(4)
	ds_write_b64 v239, v[160:161]
	s_waitcnt vmcnt(3)
	ds_write_b128 v164, v[156:159]
	s_waitcnt lgkmcnt(8)
	v_mfma_f32_32x32x16_bf16 v[80:95], v[148:151], v[124:127], v[80:95]
	v_exp_f32_e32 v60, v60
	v_cvt_pk_bf16_f32 v101, v42, v43
	v_cvt_pk_bf16_f32 v109, v58, v59
	v_exp_f32_e32 v45, v45
	v_exp_f32_e32 v61, v61
	ds_read_b128 v[148:151], v243 offset:20128
	ds_read_b64_tr_b16 v[180:181], v163 offset:64
	ds_read_b64_tr_b16 v[182:183], v163 offset:1600
	s_waitcnt lgkmcnt(10)
	v_mfma_f32_32x32x16_bf16 v[64:79], v[136:139], v[128:131], v[64:79]
	v_exp_f32_e32 v46, v46
	v_exp_f32_e32 v62, v62
	v_cvt_pk_bf16_f32 v102, v44, v45
	v_cvt_pk_bf16_f32 v110, v60, v61
	v_exp_f32_e32 v47, v47
	v_exp_f32_e32 v63, v63
	ds_read_b64_tr_b16 v[184:185], v163 offset:6144
	ds_read_b64_tr_b16 v[186:187], v163 offset:7680
	s_waitcnt lgkmcnt(11)
	v_mfma_f32_32x32x16_bf16 v[80:95], v[140:143], v[128:131], v[80:95]
	v_cvt_pk_bf16_f32 v103, v46, v47
	v_cvt_pk_bf16_f32 v111, v62, v63
	ds_read_b64_tr_b16 v[188:189], v163 offset:6208
	ds_read_b64_tr_b16 v[190:191], v163 offset:7744
	s_waitcnt lgkmcnt(12)
	v_mfma_f32_32x32x16_bf16 v[64:79], v[144:147], v[132:135], v[64:79]
	s_waitcnt lgkmcnt(6)
	v_mfma_f32_32x32x16_bf16 v[80:95], v[148:151], v[132:135], v[80:95]
	s_nop 13
	s_waitcnt lgkmcnt(0)
	s_barrier
	s_cmp_eq_u32 s7, 0
	s_cbranch_scc1 .Lamla_tail
.Lamla_loop:
	ds_read_b128 v[136:139], v243 offset:0
	ds_read_b128 v[140:143], v243 offset:6656
	ds_read_b128 v[144:147], v243 offset:32
	ds_read_b128 v[148:151], v243 offset:6688
	s_waitcnt lgkmcnt(10)
	v_mfma_f32_32x32x16_bf16 v[0:15], v[176:179], v[96:99], v[0:15]
	v_max3_f32 v168, v64, v65, v66
	v_max3_f32 v170, v80, v81, v82
	v_max3_f32 v168, v168, v67, v68
	v_max3_f32 v170, v170, v83, v84
	v_max3_f32 v168, v168, v69, v70
	s_mov_b32 s55, s52
	s_mov_b32 s52, s53
	s_mov_b32 s53, s54
	s_mov_b32 s54, s55
	s_mov_b32 s9, 0
	s_waitcnt lgkmcnt(8)
	v_mfma_f32_32x32x16_bf16 v[16:31], v[180:183], v[96:99], v[16:31]
	v_max3_f32 v170, v170, v85, v86
	v_max3_f32 v168, v168, v71, v72
	v_max3_f32 v170, v170, v87, v88
	v_max3_f32 v168, v168, v73, v74
	global_load_dwordx4 v[152:155], v167, s[2:3]
	global_load_dwordx2 v[160:161], v165, s[10:11]
	global_load_dwordx4 v[156:159], v167, s[4:5]
	s_add_u32 s2, s2, 0x2000
	s_addc_u32 s3, s3, 0
	s_add_u32 s10, s10, 0x1000
	s_addc_u32 s11, s11, 0
	s_add_u32 s4, s4, 0x2000
	s_addc_u32 s5, s5, 0
	v_add_u32_e32 v162, s53, v240
	v_add_u32_e32 v164, s54, v241
	v_mfma_f32_16x16x32_bf16 v[234:237], v[246:249], v[96:99], v[234:237]
	v_max3_f32 v170, v170, v89, v90
	v_max3_f32 v168, v168, v75, v76
	v_max3_f32 v170, v170, v91, v92
	v_max3_f32 v168, v168, v77, v78
	v_max3_f32 v170, v170, v93, v94
	v_max_f32_e32 v168, v168, v79
	v_max_f32_e32 v170, v170, v95
	v_max_f32_e32 v168, v168, v170
	v_mov_b32_e32 v170, v168
	s_nop 1
	v_permlane32_swap_b32_e32 v168, v170
	v_max_f32_e32 v168, v168, v170
	v_cmp_lt_f32_e32 vcc, 0x41000000, v168
	s_cbranch_vccz .Lamla_nors_2
	v_max_f32_e32 v170, 0, v168
	v_exp_f32_e64 v166, -v170
	v_sub_f32_e32 v218, v218, v170
	v_sub_f32_e32 v219, v219, v170
	v_sub_f32_e32 v220, v220, v170
	v_sub_f32_e32 v221, v221, v170
	v_sub_f32_e32 v222, v222, v170
	v_sub_f32_e32 v223, v223, v170
	v_sub_f32_e32 v224, v224, v170
	v_sub_f32_e32 v225, v225, v170
	v_sub_f32_e32 v226, v226, v170
	v_sub_f32_e32 v227, v227, v170
	v_sub_f32_e32 v228, v228, v170
	v_sub_f32_e32 v229, v229, v170
	v_sub_f32_e32 v230, v230, v170
	v_sub_f32_e32 v231, v231, v170
	v_sub_f32_e32 v232, v232, v170
	v_sub_f32_e32 v233, v233, v170
	v_sub_f32_e32 v64, v64, v170
	v_sub_f32_e32 v65, v65, v170
	v_sub_f32_e32 v66, v66, v170
	v_sub_f32_e32 v67, v67, v170
	v_sub_f32_e32 v68, v68, v170
	v_sub_f32_e32 v69, v69, v170
	v_sub_f32_e32 v70, v70, v170
	v_sub_f32_e32 v71, v71, v170
	v_sub_f32_e32 v72, v72, v170
	v_sub_f32_e32 v73, v73, v170
	v_sub_f32_e32 v74, v74, v170
	v_sub_f32_e32 v75, v75, v170
	v_sub_f32_e32 v76, v76, v170
	v_sub_f32_e32 v77, v77, v170
	v_sub_f32_e32 v78, v78, v170
	v_sub_f32_e32 v79, v79, v170
	v_sub_f32_e32 v80, v80, v170
	v_sub_f32_e32 v81, v81, v170
	v_sub_f32_e32 v82, v82, v170
	v_sub_f32_e32 v83, v83, v170
	v_sub_f32_e32 v84, v84, v170
	v_sub_f32_e32 v85, v85, v170
	v_sub_f32_e32 v86, v86, v170
	v_sub_f32_e32 v87, v87, v170
	v_sub_f32_e32 v88, v88, v170
	v_sub_f32_e32 v89, v89, v170
	v_sub_f32_e32 v90, v90, v170
	v_sub_f32_e32 v91, v91, v170
	v_sub_f32_e32 v92, v92, v170
	v_sub_f32_e32 v93, v93, v170
	v_sub_f32_e32 v94, v94, v170
	v_sub_f32_e32 v95, v95, v170
	s_mov_b32 s9, 1
.Lamla_nors_2:
	s_waitcnt lgkmcnt(3)
	v_mfma_f32_32x32x16_bf16 v[32:47], v[136:139], v[112:115], v[218:233]
	v_exp_f32_e32 v64, v64
	v_exp_f32_e32 v80, v80
	ds_read_b128 v[136:139], v243 offset:64
	ds_read_b64_tr_b16 v[192:193], v163 offset:3072
	ds_read_b64_tr_b16 v[194:195], v163 offset:4608
	s_waitcnt lgkmcnt(5)
	v_mfma_f32_32x32x16_bf16 v[48:63], v[140:143], v[112:115], v[218:233]
	v_exp_f32_e32 v65, v65
	v_exp_f32_e32 v81, v81
	v_exp_f32_e32 v66, v66
	ds_read_b128 v[140:143], v243 offset:6720
	ds_read_b64_tr_b16 v[196:197], v163 offset:3136
	ds_read_b64_tr_b16 v[198:199], v163 offset:4672
	v_mfma_f32_32x32x16_bf16 v[0:15], v[184:187], v[104:107], v[0:15]
	v_exp_f32_e32 v82, v82
	v_cvt_pk_bf16_f32 v96, v64, v65
	ds_read_b64_tr_b16 v[200:201], v163 offset:9216
	ds_read_b64_tr_b16 v[202:203], v163 offset:10752
	s_waitcnt lgkmcnt(9)
	v_mfma_f32_32x32x16_bf16 v[32:47], v[144:147], v[116:119], v[32:47]
	v_exp_f32_e32 v67, v67
	v_exp_f32_e32 v83, v83
	ds_read_b128 v[144:147], v243 offset:96
	ds_read_b64_tr_b16 v[204:205], v163 offset:9280
	ds_read_b64_tr_b16 v[206:207], v163 offset:10816
	v_mfma_f32_32x32x16_bf16 v[16:31], v[188:191], v[104:107], v[16:31]
	v_exp_f32_e32 v68, v68
	v_exp_f32_e32 v84, v84
	s_waitcnt lgkmcnt(11)
	v_mfma_f32_32x32x16_bf16 v[48:63], v[148:151], v[116:119], v[48:63]
	v_cvt_pk_bf16_f32 v97, v66, v67
	v_exp_f32_e32 v69, v69
	v_exp_f32_e32 v85, v85
	ds_read_b128 v[148:151], v243 offset:6752
	v_mfma_f32_16x16x32_bf16 v[234:237], v[246:249], v[104:107], v[234:237]
	v_cvt_pk_bf16_f32 v104, v80, v81
	v_cvt_pk_bf16_f32 v105, v82, v83
	v_exp_f32_e32 v70, v70
	v_exp_f32_e32 v86, v86
	s_waitcnt lgkmcnt(11)
	v_mfma_f32_32x32x16_bf16 v[32:47], v[136:139], v[120:123], v[32:47]
	v_cvt_pk_bf16_f32 v98, v68, v69
	v_cvt_pk_bf16_f32 v106, v84, v85
	v_exp_f32_e32 v71, v71
	ds_read_b128 v[136:139], v243 offset:128
	s_waitcnt lgkmcnt(9)
	v_mfma_f32_32x32x16_bf16 v[48:63], v[140:143], v[120:123], v[48:63]
	v_exp_f32_e32 v87, v87
	v_exp_f32_e32 v72, v72
	ds_read_b128 v[140:143], v243 offset:6784
	v_mfma_f32_32x32x16_bf16 v[0:15], v[192:195], v[100:103], v[0:15]
	v_exp_f32_e32 v88, v88
	v_cvt_pk_bf16_f32 v99, v70, v71
	v_cvt_pk_bf16_f32 v107, v86, v87
	v_exp_f32_e32 v73, v73
	s_waitcnt lgkmcnt(5)
	v_mfma_f32_32x32x16_bf16 v[32:47], v[144:147], v[124:127], v[32:47]
	v_exp_f32_e32 v89, v89
	v_exp_f32_e32 v74, v74
	ds_read_b128 v[144:147], v243 offset:160
	v_mfma_f32_32x32x16_bf16 v[16:31], v[196:199], v[100:103], v[16:31]
	v_exp_f32_e32 v90, v90
	v_exp_f32_e32 v75, v75
	s_waitcnt vmcnt(5)
	ds_write_b128 v238, v[208:211] offset:13312
	s_waitcnt vmcnt(4)
	ds_write_b64 v239, v[216:217] offset:13312
	s_waitcnt vmcnt(3)
	ds_write_b128 v164, v[212:215]
	s_waitcnt lgkmcnt(6)
	v_mfma_f32_32x32x16_bf16 v[48:63], v[148:151], v[124:127], v[48:63]
	v_exp_f32_e32 v91, v91
	v_exp_f32_e32 v76, v76
	ds_read_b128 v[148:151], v243 offset:6816
	v_mfma_f32_16x16x32_bf16 v[234:237], v[246:249], v[100:103], v[234:237]
	v_cvt_pk_bf16_f32 v100, v72, v73
	v_exp_f32_e32 v92, v92
	v_cvt_pk_bf16_f32 v101, v74, v75
	v_exp_f32_e32 v77, v77
	s_waitcnt lgkmcnt(6)
	v_mfma_f32_32x32x16_bf16 v[32:47], v[136:139], v[128:131], v[32:47]
	v_exp_f32_e32 v93, v93
	v_exp_f32_e32 v78, v78
	s_waitcnt lgkmcnt(5)
	v_mfma_f32_32x32x16_bf16 v[48:63], v[140:143], v[128:131], v[48:63]
	v_exp_f32_e32 v94, v94
	v_cvt_pk_bf16_f32 v102, v76, v77
	ds_read_b64_tr_b16 v[176:177], v162 offset:0
	ds_read_b64_tr_b16 v[178:179], v162 offset:1536
	v_mfma_f32_32x32x16_bf16 v[0:15], v[200:203], v[108:111], v[0:15]
	v_exp_f32_e32 v79, v79
	v_exp_f32_e32 v95, v95
	ds_read_b64_tr_b16 v[180:181], v162 offset:64
	ds_read_b64_tr_b16 v[182:183], v162 offset:1600
	s_waitcnt lgkmcnt(8)
	v_mfma_f32_32x32x16_bf16 v[32:47], v[144:147], v[132:135], v[32:47]
	v_cvt_pk_bf16_f32 v103, v78, v79
	ds_read_b64_tr_b16 v[184:185], v162 offset:6144
	ds_read_b64_tr_b16 v[186:187], v162 offset:7680
	v_mfma_f32_32x32x16_bf16 v[16:31], v[204:207], v[108:111], v[16:31]
	ds_read_b64_tr_b16 v[188:189], v162 offset:6208
	ds_read_b64_tr_b16 v[190:191], v162 offset:7744
	s_waitcnt lgkmcnt(8)
	v_mfma_f32_32x32x16_bf16 v[48:63], v[148:151], v[132:135], v[48:63]
	v_mfma_f32_16x16x32_bf16 v[234:237], v[246:249], v[108:111], v[234:237]
	v_cvt_pk_bf16_f32 v108, v88, v89
	v_cvt_pk_bf16_f32 v109, v90, v91
	v_cvt_pk_bf16_f32 v110, v92, v93
	v_cvt_pk_bf16_f32 v111, v94, v95
	s_cmp_lg_u32 s9, 0
	s_cbranch_scc0 .Lamla_noresc_3
	s_nop 15
	v_mul_f32_e32 v0, v0, v166
	v_mul_f32_e32 v1, v1, v166
	v_mul_f32_e32 v2, v2, v166
	v_mul_f32_e32 v3, v3, v166
	v_mul_f32_e32 v4, v4, v166
	v_mul_f32_e32 v5, v5, v166
	v_mul_f32_e32 v6, v6, v166
	v_mul_f32_e32 v7, v7, v166
	v_mul_f32_e32 v8, v8, v166
	v_mul_f32_e32 v9, v9, v166
	v_mul_f32_e32 v10, v10, v166
	v_mul_f32_e32 v11, v11, v166
	v_mul_f32_e32 v12, v12, v166
	v_mul_f32_e32 v13, v13, v166
	v_mul_f32_e32 v14, v14, v166
	v_mul_f32_e32 v15, v15, v166
	v_mul_f32_e32 v16, v16, v166
	v_mul_f32_e32 v17, v17, v166
	v_mul_f32_e32 v18, v18, v166
	v_mul_f32_e32 v19, v19, v166
	v_mul_f32_e32 v20, v20, v166
	v_mul_f32_e32 v21, v21, v166
	v_mul_f32_e32 v22, v22, v166
	v_mul_f32_e32 v23, v23, v166
	v_mul_f32_e32 v24, v24, v166
	v_mul_f32_e32 v25, v25, v166
	v_mul_f32_e32 v26, v26, v166
	v_mul_f32_e32 v27, v27, v166
	v_mul_f32_e32 v28, v28, v166
	v_mul_f32_e32 v29, v29, v166
	v_mul_f32_e32 v30, v30, v166
	v_mul_f32_e32 v31, v31, v166
	v_add_u32_e32 v170, 64, v175
	ds_bpermute_b32 v173, v170, v166
	v_mul_f32_e32 v234, v234, v166
	s_waitcnt lgkmcnt(0)
	v_mul_f32_e32 v235, v235, v173
.Lamla_noresc_3:
	s_nop 6
	s_barrier
	ds_read_b128 v[136:139], v243 offset:13312
	ds_read_b128 v[140:143], v243 offset:19968
	ds_read_b128 v[144:147], v243 offset:13344
	ds_read_b128 v[148:151], v243 offset:20000
	s_waitcnt lgkmcnt(10)
	v_mfma_f32_32x32x16_bf16 v[0:15], v[176:179], v[96:99], v[0:15]
	v_max3_f32 v168, v32, v33, v34
	v_max3_f32 v170, v48, v49, v50
	v_max3_f32 v168, v168, v35, v36
	v_max3_f32 v170, v170, v51, v52
	v_max3_f32 v168, v168, v37, v38
	s_mov_b32 s55, s52
	s_mov_b32 s52, s53
	s_mov_b32 s53, s54
	s_mov_b32 s54, s55
	s_mov_b32 s9, 0
	s_waitcnt lgkmcnt(8)
	v_mfma_f32_32x32x16_bf16 v[16:31], v[180:183], v[96:99], v[16:31]
	v_max3_f32 v170, v170, v53, v54
	v_max3_f32 v168, v168, v39, v40
	v_max3_f32 v170, v170, v55, v56
	v_max3_f32 v168, v168, v41, v42
	global_load_dwordx4 v[208:211], v167, s[2:3]
	global_load_dwordx2 v[216:217], v165, s[10:11]
	global_load_dwordx4 v[212:215], v167, s[4:5]
	s_add_u32 s2, s2, 0x2000
	s_addc_u32 s3, s3, 0
	s_add_u32 s10, s10, 0x1000
	s_addc_u32 s11, s11, 0
	s_add_u32 s4, s4, 0x2000
	s_addc_u32 s5, s5, 0
	v_add_u32_e32 v163, s53, v240
	v_add_u32_e32 v164, s54, v241
	v_mfma_f32_16x16x32_bf16 v[234:237], v[246:249], v[96:99], v[234:237]
	v_max3_f32 v170, v170, v57, v58
	v_max3_f32 v168, v168, v43, v44
	v_max3_f32 v170, v170, v59, v60
	v_max3_f32 v168, v168, v45, v46
	v_max3_f32 v170, v170, v61, v62
	v_max_f32_e32 v168, v168, v47
	v_max_f32_e32 v170, v170, v63
	v_max_f32_e32 v168, v168, v170
	v_mov_b32_e32 v170, v168
	s_nop 1
	v_permlane32_swap_b32_e32 v168, v170
	v_max_f32_e32 v168, v168, v170
	v_cmp_lt_f32_e32 vcc, 0x41000000, v168
	s_cbranch_vccz .Lamla_nors_4
	v_max_f32_e32 v170, 0, v168
	v_exp_f32_e64 v166, -v170
	v_sub_f32_e32 v218, v218, v170
	v_sub_f32_e32 v219, v219, v170
	v_sub_f32_e32 v220, v220, v170
	v_sub_f32_e32 v221, v221, v170
	v_sub_f32_e32 v222, v222, v170
	v_sub_f32_e32 v223, v223, v170
	v_sub_f32_e32 v224, v224, v170
	v_sub_f32_e32 v225, v225, v170
	v_sub_f32_e32 v226, v226, v170
	v_sub_f32_e32 v227, v227, v170
	v_sub_f32_e32 v228, v228, v170
	v_sub_f32_e32 v229, v229, v170
	v_sub_f32_e32 v230, v230, v170
	v_sub_f32_e32 v231, v231, v170
	v_sub_f32_e32 v232, v232, v170
	v_sub_f32_e32 v233, v233, v170
	v_sub_f32_e32 v32, v32, v170
	v_sub_f32_e32 v33, v33, v170
	v_sub_f32_e32 v34, v34, v170
	v_sub_f32_e32 v35, v35, v170
	v_sub_f32_e32 v36, v36, v170
	v_sub_f32_e32 v37, v37, v170
	v_sub_f32_e32 v38, v38, v170
	v_sub_f32_e32 v39, v39, v170
	v_sub_f32_e32 v40, v40, v170
	v_sub_f32_e32 v41, v41, v170
	v_sub_f32_e32 v42, v42, v170
	v_sub_f32_e32 v43, v43, v170
	v_sub_f32_e32 v44, v44, v170
	v_sub_f32_e32 v45, v45, v170
	v_sub_f32_e32 v46, v46, v170
	v_sub_f32_e32 v47, v47, v170
	v_sub_f32_e32 v48, v48, v170
	v_sub_f32_e32 v49, v49, v170
	v_sub_f32_e32 v50, v50, v170
	v_sub_f32_e32 v51, v51, v170
	v_sub_f32_e32 v52, v52, v170
	v_sub_f32_e32 v53, v53, v170
	v_sub_f32_e32 v54, v54, v170
	v_sub_f32_e32 v55, v55, v170
	v_sub_f32_e32 v56, v56, v170
	v_sub_f32_e32 v57, v57, v170
	v_sub_f32_e32 v58, v58, v170
	v_sub_f32_e32 v59, v59, v170
	v_sub_f32_e32 v60, v60, v170
	v_sub_f32_e32 v61, v61, v170
	v_sub_f32_e32 v62, v62, v170
	v_sub_f32_e32 v63, v63, v170
	s_mov_b32 s9, 1
.Lamla_nors_4:
	s_waitcnt lgkmcnt(3)
	v_mfma_f32_32x32x16_bf16 v[64:79], v[136:139], v[112:115], v[218:233]
	v_exp_f32_e32 v32, v32
	v_exp_f32_e32 v48, v48
	ds_read_b128 v[136:139], v243 offset:13376
	ds_read_b64_tr_b16 v[192:193], v162 offset:3072
	ds_read_b64_tr_b16 v[194:195], v162 offset:4608
	s_waitcnt lgkmcnt(5)
	v_mfma_f32_32x32x16_bf16 v[80:95], v[140:143], v[112:115], v[218:233]
	v_exp_f32_e32 v33, v33
	v_exp_f32_e32 v49, v49
	v_exp_f32_e32 v34, v34
	ds_read_b128 v[140:143], v243 offset:20032
	ds_read_b64_tr_b16 v[196:197], v162 offset:3136
	ds_read_b64_tr_b16 v[198:199], v162 offset:4672
	v_mfma_f32_32x32x16_bf16 v[0:15], v[184:187], v[104:107], v[0:15]
	v_exp_f32_e32 v50, v50
	v_cvt_pk_bf16_f32 v96, v32, v33
	ds_read_b64_tr_b16 v[200:201], v162 offset:9216
	ds_read_b64_tr_b16 v[202:203], v162 offset:10752
	s_waitcnt lgkmcnt(9)
	v_mfma_f32_32x32x16_bf16 v[64:79], v[144:147], v[116:119], v[64:79]
	v_exp_f32_e32 v35, v35
	v_exp_f32_e32 v51, v51
	ds_read_b128 v[144:147], v243 offset:13408
	ds_read_b64_tr_b16 v[204:205], v162 offset:9280
	ds_read_b64_tr_b16 v[206:207], v162 offset:10816
	v_mfma_f32_32x32x16_bf16 v[16:31], v[188:191], v[104:107], v[16:31]
	v_exp_f32_e32 v36, v36
	v_exp_f32_e32 v52, v52
	s_waitcnt lgkmcnt(11)
	v_mfma_f32_32x32x16_bf16 v[80:95], v[148:151], v[116:119], v[80:95]
	v_cvt_pk_bf16_f32 v97, v34, v35
	v_exp_f32_e32 v37, v37
	v_exp_f32_e32 v53, v53
	ds_read_b128 v[148:151], v243 offset:20064
	v_mfma_f32_16x16x32_bf16 v[234:237], v[246:249], v[104:107], v[234:237]
	v_cvt_pk_bf16_f32 v104, v48, v49
	v_cvt_pk_bf16_f32 v105, v50, v51
	v_exp_f32_e32 v38, v38
	v_exp_f32_e32 v54, v54
	s_waitcnt lgkmcnt(11)
	v_mfma_f32_32x32x16_bf16 v[64:79], v[136:139], v[120:123], v[64:79]
	v_cvt_pk_bf16_f32 v98, v36, v37
	v_cvt_pk_bf16_f32 v106, v52, v53
	v_exp_f32_e32 v39, v39
	ds_read_b128 v[136:139], v243 offset:13440
	s_waitcnt lgkmcnt(9)
	v_mfma_f32_32x32x16_bf16 v[80:95], v[140:143], v[120:123], v[80:95]
	v_exp_f32_e32 v55, v55
	v_exp_f32_e32 v40, v40
	ds_read_b128 v[140:143], v243 offset:20096
	v_mfma_f32_32x32x16_bf16 v[0:15], v[192:195], v[100:103], v[0:15]
	v_exp_f32_e32 v56, v56
	v_cvt_pk_bf16_f32 v99, v38, v39
	v_cvt_pk_bf16_f32 v107, v54, v55
	v_exp_f32_e32 v41, v41
	s_waitcnt lgkmcnt(5)
	v_mfma_f32_32x32x16_bf16 v[64:79], v[144:147], v[124:127], v[64:79]
	v_exp_f32_e32 v57, v57
	v_exp_f32_e32 v42, v42
	ds_read_b128 v[144:147], v243 offset:13472
	v_mfma_f32_32x32x16_bf16 v[16:31], v[196:199], v[100:103], v[16:31]
	v_exp_f32_e32 v58, v58
	v_exp_f32_e32 v43, v43
	s_waitcnt vmcnt(5)
	ds_write_b128 v238, v[152:155]
	s_waitcnt vmcnt(4)
	ds_write_b64 v239, v[160:161]
	s_waitcnt vmcnt(3)
	ds_write_b128 v164, v[156:159]
	s_waitcnt lgkmcnt(6)
	v_mfma_f32_32x32x16_bf16 v[80:95], v[148:151], v[124:127], v[80:95]
	v_exp_f32_e32 v59, v59
	v_exp_f32_e32 v44, v44
	ds_read_b128 v[148:151], v243 offset:20128
	v_mfma_f32_16x16x32_bf16 v[234:237], v[246:249], v[100:103], v[234:237]
	v_cvt_pk_bf16_f32 v100, v40, v41
	v_exp_f32_e32 v60, v60
	v_cvt_pk_bf16_f32 v101, v42, v43
	v_exp_f32_e32 v45, v45
	s_waitcnt lgkmcnt(6)
	v_mfma_f32_32x32x16_bf16 v[64:79], v[136:139], v[128:131], v[64:79]
	v_exp_f32_e32 v61, v61
	v_exp_f32_e32 v46, v46
	s_waitcnt lgkmcnt(5)
	v_mfma_f32_32x32x16_bf16 v[80:95], v[140:143], v[128:131], v[80:95]
	v_exp_f32_e32 v62, v62
	v_cvt_pk_bf16_f32 v102, v44, v45
	ds_read_b64_tr_b16 v[176:177], v163 offset:0
	ds_read_b64_tr_b16 v[178:179], v163 offset:1536
	v_mfma_f32_32x32x16_bf16 v[0:15], v[200:203], v[108:111], v[0:15]
	v_exp_f32_e32 v47, v47
	v_exp_f32_e32 v63, v63
	ds_read_b64_tr_b16 v[180:181], v163 offset:64
	ds_read_b64_tr_b16 v[182:183], v163 offset:1600
	s_waitcnt lgkmcnt(8)
	v_mfma_f32_32x32x16_bf16 v[64:79], v[144:147], v[132:135], v[64:79]
	v_cvt_pk_bf16_f32 v103, v46, v47
	ds_read_b64_tr_b16 v[184:185], v163 offset:6144
	ds_read_b64_tr_b16 v[186:187], v163 offset:7680
	v_mfma_f32_32x32x16_bf16 v[16:31], v[204:207], v[108:111], v[16:31]
	ds_read_b64_tr_b16 v[188:189], v163 offset:6208
	ds_read_b64_tr_b16 v[190:191], v163 offset:7744
	s_waitcnt lgkmcnt(8)
	v_mfma_f32_32x32x16_bf16 v[80:95], v[148:151], v[132:135], v[80:95]
	v_mfma_f32_16x16x32_bf16 v[234:237], v[246:249], v[108:111], v[234:237]
	v_cvt_pk_bf16_f32 v108, v56, v57
	v_cvt_pk_bf16_f32 v109, v58, v59
	v_cvt_pk_bf16_f32 v110, v60, v61
	v_cvt_pk_bf16_f32 v111, v62, v63
	s_cmp_lg_u32 s9, 0
	s_cbranch_scc0 .Lamla_noresc_5
	s_nop 15
	v_mul_f32_e32 v0, v0, v166
	v_mul_f32_e32 v1, v1, v166
	v_mul_f32_e32 v2, v2, v166
	v_mul_f32_e32 v3, v3, v166
	v_mul_f32_e32 v4, v4, v166
	v_mul_f32_e32 v5, v5, v166
	v_mul_f32_e32 v6, v6, v166
	v_mul_f32_e32 v7, v7, v166
	v_mul_f32_e32 v8, v8, v166
	v_mul_f32_e32 v9, v9, v166
	v_mul_f32_e32 v10, v10, v166
	v_mul_f32_e32 v11, v11, v166
	v_mul_f32_e32 v12, v12, v166
	v_mul_f32_e32 v13, v13, v166
	v_mul_f32_e32 v14, v14, v166
	v_mul_f32_e32 v15, v15, v166
	v_mul_f32_e32 v16, v16, v166
	v_mul_f32_e32 v17, v17, v166
	v_mul_f32_e32 v18, v18, v166
	v_mul_f32_e32 v19, v19, v166
	v_mul_f32_e32 v20, v20, v166
	v_mul_f32_e32 v21, v21, v166
	v_mul_f32_e32 v22, v22, v166
	v_mul_f32_e32 v23, v23, v166
	v_mul_f32_e32 v24, v24, v166
	v_mul_f32_e32 v25, v25, v166
	v_mul_f32_e32 v26, v26, v166
	v_mul_f32_e32 v27, v27, v166
	v_mul_f32_e32 v28, v28, v166
	v_mul_f32_e32 v29, v29, v166
	v_mul_f32_e32 v30, v30, v166
	v_mul_f32_e32 v31, v31, v166
	v_add_u32_e32 v170, 64, v175
	ds_bpermute_b32 v173, v170, v166
	v_mul_f32_e32 v234, v234, v166
	s_waitcnt lgkmcnt(0)
	v_mul_f32_e32 v235, v235, v173
.Lamla_noresc_5:
	s_nop 6
	s_barrier
	s_add_i32 s7, s7, -1
	s_cmp_lg_u32 s7, 0
	s_cbranch_scc1 .Lamla_loop
.Lamla_tail:
	ds_read_b128 v[136:139], v243 offset:0
	ds_read_b128 v[140:143], v243 offset:6656
	ds_read_b128 v[144:147], v243 offset:32
	ds_read_b128 v[148:151], v243 offset:6688
	s_waitcnt lgkmcnt(10)
	v_mfma_f32_32x32x16_bf16 v[0:15], v[176:179], v[96:99], v[0:15]
	v_max3_f32 v168, v64, v65, v66
	v_max3_f32 v170, v80, v81, v82
	v_max3_f32 v168, v168, v67, v68
	v_max3_f32 v170, v170, v83, v84
	v_max3_f32 v168, v168, v69, v70
	s_mov_b32 s55, s52
	s_mov_b32 s52, s53
	s_mov_b32 s53, s54
	s_mov_b32 s54, s55
	s_mov_b32 s9, 0
	s_waitcnt lgkmcnt(8)
	v_mfma_f32_32x32x16_bf16 v[16:31], v[180:183], v[96:99], v[16:31]
	v_max3_f32 v170, v170, v85, v86
	v_max3_f32 v168, v168, v71, v72
	v_max3_f32 v170, v170, v87, v88
	v_max3_f32 v168, v168, v73, v74
	global_load_dwordx4 v[156:159], v167, s[4:5]
	s_add_u32 s4, s4, 0x2000
	s_addc_u32 s5, s5, 0
	v_add_u32_e32 v162, s53, v240
	v_add_u32_e32 v164, s54, v241
	v_mfma_f32_16x16x32_bf16 v[234:237], v[246:249], v[96:99], v[234:237]
	v_max3_f32 v170, v170, v89, v90
	v_max3_f32 v168, v168, v75, v76
	v_max3_f32 v170, v170, v91, v92
	v_max3_f32 v168, v168, v77, v78
	v_max3_f32 v170, v170, v93, v94
	v_max_f32_e32 v168, v168, v79
	v_max_f32_e32 v170, v170, v95
	v_max_f32_e32 v168, v168, v170
	v_mov_b32_e32 v170, v168
	s_nop 1
	v_permlane32_swap_b32_e32 v168, v170
	v_max_f32_e32 v168, v168, v170
	v_cmp_lt_f32_e32 vcc, 0x41000000, v168
	s_cbranch_vccz .Lamla_nors_6
	v_max_f32_e32 v170, 0, v168
	v_exp_f32_e64 v166, -v170
	v_sub_f32_e32 v218, v218, v170
	v_sub_f32_e32 v219, v219, v170
	v_sub_f32_e32 v220, v220, v170
	v_sub_f32_e32 v221, v221, v170
	v_sub_f32_e32 v222, v222, v170
	v_sub_f32_e32 v223, v223, v170
	v_sub_f32_e32 v224, v224, v170
	v_sub_f32_e32 v225, v225, v170
	v_sub_f32_e32 v226, v226, v170
	v_sub_f32_e32 v227, v227, v170
	v_sub_f32_e32 v228, v228, v170
	v_sub_f32_e32 v229, v229, v170
	v_sub_f32_e32 v230, v230, v170
	v_sub_f32_e32 v231, v231, v170
	v_sub_f32_e32 v232, v232, v170
	v_sub_f32_e32 v233, v233, v170
	v_sub_f32_e32 v64, v64, v170
	v_sub_f32_e32 v65, v65, v170
	v_sub_f32_e32 v66, v66, v170
	v_sub_f32_e32 v67, v67, v170
	v_sub_f32_e32 v68, v68, v170
	v_sub_f32_e32 v69, v69, v170
	v_sub_f32_e32 v70, v70, v170
	v_sub_f32_e32 v71, v71, v170
	v_sub_f32_e32 v72, v72, v170
	v_sub_f32_e32 v73, v73, v170
	v_sub_f32_e32 v74, v74, v170
	v_sub_f32_e32 v75, v75, v170
	v_sub_f32_e32 v76, v76, v170
	v_sub_f32_e32 v77, v77, v170
	v_sub_f32_e32 v78, v78, v170
	v_sub_f32_e32 v79, v79, v170
	v_sub_f32_e32 v80, v80, v170
	v_sub_f32_e32 v81, v81, v170
	v_sub_f32_e32 v82, v82, v170
	v_sub_f32_e32 v83, v83, v170
	v_sub_f32_e32 v84, v84, v170
	v_sub_f32_e32 v85, v85, v170
	v_sub_f32_e32 v86, v86, v170
	v_sub_f32_e32 v87, v87, v170
	v_sub_f32_e32 v88, v88, v170
	v_sub_f32_e32 v89, v89, v170
	v_sub_f32_e32 v90, v90, v170
	v_sub_f32_e32 v91, v91, v170
	v_sub_f32_e32 v92, v92, v170
	v_sub_f32_e32 v93, v93, v170
	v_sub_f32_e32 v94, v94, v170
	v_sub_f32_e32 v95, v95, v170
	s_mov_b32 s9, 1
.Lamla_nors_6:
	s_waitcnt lgkmcnt(3)
	v_mfma_f32_32x32x16_bf16 v[32:47], v[136:139], v[112:115], v[218:233]
	v_exp_f32_e32 v64, v64
	v_exp_f32_e32 v80, v80
	ds_read_b128 v[136:139], v243 offset:64
	ds_read_b64_tr_b16 v[192:193], v163 offset:3072
	ds_read_b64_tr_b16 v[194:195], v163 offset:4608
	s_waitcnt lgkmcnt(5)
	v_mfma_f32_32x32x16_bf16 v[48:63], v[140:143], v[112:115], v[218:233]
	v_exp_f32_e32 v65, v65
	v_exp_f32_e32 v81, v81
	v_exp_f32_e32 v66, v66
	ds_read_b128 v[140:143], v243 offset:6720
	ds_read_b64_tr_b16 v[196:197], v163 offset:3136
	ds_read_b64_tr_b16 v[198:199], v163 offset:4672
	v_mfma_f32_32x32x16_bf16 v[0:15], v[184:187], v[104:107], v[0:15]
	v_exp_f32_e32 v82, v82
	v_cvt_pk_bf16_f32 v96, v64, v65
	ds_read_b64_tr_b16 v[200:201], v163 offset:9216
	ds_read_b64_tr_b16 v[202:203], v163 offset:10752
	s_waitcnt lgkmcnt(9)
	v_mfma_f32_32x32x16_bf16 v[32:47], v[144:147], v[116:119], v[32:47]
	v_exp_f32_e32 v67, v67
	v_exp_f32_e32 v83, v83
	ds_read_b128 v[144:147], v243 offset:96
	ds_read_b64_tr_b16 v[204:205], v163 offset:9280
	ds_read_b64_tr_b16 v[206:207], v163 offset:10816
	v_mfma_f32_32x32x16_bf16 v[16:31], v[188:191], v[104:107], v[16:31]
	v_exp_f32_e32 v68, v68
	v_exp_f32_e32 v84, v84
	s_waitcnt lgkmcnt(11)
	v_mfma_f32_32x32x16_bf16 v[48:63], v[148:151], v[116:119], v[48:63]
	v_cvt_pk_bf16_f32 v97, v66, v67
	v_exp_f32_e32 v69, v69
	v_exp_f32_e32 v85, v85
	ds_read_b128 v[148:151], v243 offset:6752
	v_mfma_f32_16x16x32_bf16 v[234:237], v[246:249], v[104:107], v[234:237]
	v_cvt_pk_bf16_f32 v104, v80, v81
	v_cvt_pk_bf16_f32 v105, v82, v83
	v_exp_f32_e32 v70, v70
	v_exp_f32_e32 v86, v86
	s_waitcnt lgkmcnt(11)
	v_mfma_f32_32x32x16_bf16 v[32:47], v[136:139], v[120:123], v[32:47]
	v_cvt_pk_bf16_f32 v98, v68, v69
	v_cvt_pk_bf16_f32 v106, v84, v85
	v_exp_f32_e32 v71, v71
	ds_read_b128 v[136:139], v243 offset:128
	s_waitcnt lgkmcnt(9)
	v_mfma_f32_32x32x16_bf16 v[48:63], v[140:143], v[120:123], v[48:63]
	v_exp_f32_e32 v87, v87
	v_exp_f32_e32 v72, v72
	ds_read_b128 v[140:143], v243 offset:6784
	v_mfma_f32_32x32x16_bf16 v[0:15], v[192:195], v[100:103], v[0:15]
	v_exp_f32_e32 v88, v88
	v_cvt_pk_bf16_f32 v99, v70, v71
	v_cvt_pk_bf16_f32 v107, v86, v87
	v_exp_f32_e32 v73, v73
	s_waitcnt lgkmcnt(5)
	v_mfma_f32_32x32x16_bf16 v[32:47], v[144:147], v[124:127], v[32:47]
	v_exp_f32_e32 v89, v89
	v_exp_f32_e32 v74, v74
	ds_read_b128 v[144:147], v243 offset:160
	v_mfma_f32_32x32x16_bf16 v[16:31], v[196:199], v[100:103], v[16:31]
	v_exp_f32_e32 v90, v90
	v_exp_f32_e32 v75, v75
	s_waitcnt vmcnt(3)
	ds_write_b128 v238, v[208:211] offset:13312
	s_waitcnt vmcnt(2)
	ds_write_b64 v239, v[216:217] offset:13312
	s_waitcnt vmcnt(1)
	ds_write_b128 v164, v[212:215]
	s_waitcnt lgkmcnt(6)
	v_mfma_f32_32x32x16_bf16 v[48:63], v[148:151], v[124:127], v[48:63]
	v_exp_f32_e32 v91, v91
	v_exp_f32_e32 v76, v76
	ds_read_b128 v[148:151], v243 offset:6816
	v_mfma_f32_16x16x32_bf16 v[234:237], v[246:249], v[100:103], v[234:237]
	v_cvt_pk_bf16_f32 v100, v72, v73
	v_exp_f32_e32 v92, v92
	v_cvt_pk_bf16_f32 v101, v74, v75
	v_exp_f32_e32 v77, v77
	s_waitcnt lgkmcnt(6)
	v_mfma_f32_32x32x16_bf16 v[32:47], v[136:139], v[128:131], v[32:47]
	v_exp_f32_e32 v93, v93
	v_exp_f32_e32 v78, v78
	s_waitcnt lgkmcnt(5)
	v_mfma_f32_32x32x16_bf16 v[48:63], v[140:143], v[128:131], v[48:63]
	v_exp_f32_e32 v94, v94
	v_cvt_pk_bf16_f32 v102, v76, v77
	ds_read_b64_tr_b16 v[176:177], v162 offset:0
	ds_read_b64_tr_b16 v[178:179], v162 offset:1536
	v_mfma_f32_32x32x16_bf16 v[0:15], v[200:203], v[108:111], v[0:15]
	v_exp_f32_e32 v79, v79
	v_exp_f32_e32 v95, v95
	ds_read_b64_tr_b16 v[180:181], v162 offset:64
	ds_read_b64_tr_b16 v[182:183], v162 offset:1600
	s_waitcnt lgkmcnt(8)
	v_mfma_f32_32x32x16_bf16 v[32:47], v[144:147], v[132:135], v[32:47]
	v_cvt_pk_bf16_f32 v103, v78, v79
	ds_read_b64_tr_b16 v[184:185], v162 offset:6144
	ds_read_b64_tr_b16 v[186:187], v162 offset:7680
	v_mfma_f32_32x32x16_bf16 v[16:31], v[204:207], v[108:111], v[16:31]
	ds_read_b64_tr_b16 v[188:189], v162 offset:6208
	ds_read_b64_tr_b16 v[190:191], v162 offset:7744
	s_waitcnt lgkmcnt(8)
	v_mfma_f32_32x32x16_bf16 v[48:63], v[148:151], v[132:135], v[48:63]
	v_mfma_f32_16x16x32_bf16 v[234:237], v[246:249], v[108:111], v[234:237]
	v_cvt_pk_bf16_f32 v108, v88, v89
	v_cvt_pk_bf16_f32 v109, v90, v91
	v_cvt_pk_bf16_f32 v110, v92, v93
	v_cvt_pk_bf16_f32 v111, v94, v95
	s_cmp_lg_u32 s9, 0
	s_cbranch_scc0 .Lamla_noresc_7
	s_nop 15
	v_mul_f32_e32 v0, v0, v166
	v_mul_f32_e32 v1, v1, v166
	v_mul_f32_e32 v2, v2, v166
	v_mul_f32_e32 v3, v3, v166
	v_mul_f32_e32 v4, v4, v166
	v_mul_f32_e32 v5, v5, v166
	v_mul_f32_e32 v6, v6, v166
	v_mul_f32_e32 v7, v7, v166
	v_mul_f32_e32 v8, v8, v166
	v_mul_f32_e32 v9, v9, v166
	v_mul_f32_e32 v10, v10, v166
	v_mul_f32_e32 v11, v11, v166
	v_mul_f32_e32 v12, v12, v166
	v_mul_f32_e32 v13, v13, v166
	v_mul_f32_e32 v14, v14, v166
	v_mul_f32_e32 v15, v15, v166
	v_mul_f32_e32 v16, v16, v166
	v_mul_f32_e32 v17, v17, v166
	v_mul_f32_e32 v18, v18, v166
	v_mul_f32_e32 v19, v19, v166
	v_mul_f32_e32 v20, v20, v166
	v_mul_f32_e32 v21, v21, v166
	v_mul_f32_e32 v22, v22, v166
	v_mul_f32_e32 v23, v23, v166
	v_mul_f32_e32 v24, v24, v166
	v_mul_f32_e32 v25, v25, v166
	v_mul_f32_e32 v26, v26, v166
	v_mul_f32_e32 v27, v27, v166
	v_mul_f32_e32 v28, v28, v166
	v_mul_f32_e32 v29, v29, v166
	v_mul_f32_e32 v30, v30, v166
	v_mul_f32_e32 v31, v31, v166
	v_add_u32_e32 v170, 64, v175
	ds_bpermute_b32 v173, v170, v166
	v_mul_f32_e32 v234, v234, v166
	s_waitcnt lgkmcnt(0)
	v_mul_f32_e32 v235, v235, v173
.Lamla_noresc_7:
	s_nop 6
	s_barrier
	ds_read_b128 v[136:139], v243 offset:13312
	ds_read_b128 v[140:143], v243 offset:19968
	ds_read_b128 v[144:147], v243 offset:13344
	ds_read_b128 v[148:151], v243 offset:20000
	s_waitcnt lgkmcnt(10)
	v_mfma_f32_32x32x16_bf16 v[0:15], v[176:179], v[96:99], v[0:15]
	v_max3_f32 v168, v32, v33, v34
	v_max3_f32 v170, v48, v49, v50
	v_max3_f32 v168, v168, v35, v36
	v_max3_f32 v170, v170, v51, v52
	v_max3_f32 v168, v168, v37, v38
	s_mov_b32 s55, s52
	s_mov_b32 s52, s53
	s_mov_b32 s53, s54
	s_mov_b32 s54, s55
	s_mov_b32 s9, 0
	s_waitcnt lgkmcnt(8)
	v_mfma_f32_32x32x16_bf16 v[16:31], v[180:183], v[96:99], v[16:31]
	v_max3_f32 v170, v170, v53, v54
	v_max3_f32 v168, v168, v39, v40
	v_max3_f32 v170, v170, v55, v56
	v_max3_f32 v168, v168, v41, v42
	v_add_u32_e32 v163, s53, v240
	v_add_u32_e32 v164, s54, v241
	v_mfma_f32_16x16x32_bf16 v[234:237], v[246:249], v[96:99], v[234:237]
	v_max3_f32 v170, v170, v57, v58
	v_max3_f32 v168, v168, v43, v44
	v_max3_f32 v170, v170, v59, v60
	v_max3_f32 v168, v168, v45, v46
	v_max3_f32 v170, v170, v61, v62
	v_max_f32_e32 v168, v168, v47
	v_max_f32_e32 v170, v170, v63
	v_max_f32_e32 v168, v168, v170
	v_mov_b32_e32 v170, v168
	s_nop 1
	v_permlane32_swap_b32_e32 v168, v170
	v_max_f32_e32 v168, v168, v170
	v_cmp_lt_f32_e32 vcc, 0x41000000, v168
	s_cbranch_vccz .Lamla_nors_8
	v_max_f32_e32 v170, 0, v168
	v_exp_f32_e64 v166, -v170
	v_sub_f32_e32 v218, v218, v170
	v_sub_f32_e32 v219, v219, v170
	v_sub_f32_e32 v220, v220, v170
	v_sub_f32_e32 v221, v221, v170
	v_sub_f32_e32 v222, v222, v170
	v_sub_f32_e32 v223, v223, v170
	v_sub_f32_e32 v224, v224, v170
	v_sub_f32_e32 v225, v225, v170
	v_sub_f32_e32 v226, v226, v170
	v_sub_f32_e32 v227, v227, v170
	v_sub_f32_e32 v228, v228, v170
	v_sub_f32_e32 v229, v229, v170
	v_sub_f32_e32 v230, v230, v170
	v_sub_f32_e32 v231, v231, v170
	v_sub_f32_e32 v232, v232, v170
	v_sub_f32_e32 v233, v233, v170
	v_sub_f32_e32 v32, v32, v170
	v_sub_f32_e32 v33, v33, v170
	v_sub_f32_e32 v34, v34, v170
	v_sub_f32_e32 v35, v35, v170
	v_sub_f32_e32 v36, v36, v170
	v_sub_f32_e32 v37, v37, v170
	v_sub_f32_e32 v38, v38, v170
	v_sub_f32_e32 v39, v39, v170
	v_sub_f32_e32 v40, v40, v170
	v_sub_f32_e32 v41, v41, v170
	v_sub_f32_e32 v42, v42, v170
	v_sub_f32_e32 v43, v43, v170
	v_sub_f32_e32 v44, v44, v170
	v_sub_f32_e32 v45, v45, v170
	v_sub_f32_e32 v46, v46, v170
	v_sub_f32_e32 v47, v47, v170
	v_sub_f32_e32 v48, v48, v170
	v_sub_f32_e32 v49, v49, v170
	v_sub_f32_e32 v50, v50, v170
	v_sub_f32_e32 v51, v51, v170
	v_sub_f32_e32 v52, v52, v170
	v_sub_f32_e32 v53, v53, v170
	v_sub_f32_e32 v54, v54, v170
	v_sub_f32_e32 v55, v55, v170
	v_sub_f32_e32 v56, v56, v170
	v_sub_f32_e32 v57, v57, v170
	v_sub_f32_e32 v58, v58, v170
	v_sub_f32_e32 v59, v59, v170
	v_sub_f32_e32 v60, v60, v170
	v_sub_f32_e32 v61, v61, v170
	v_sub_f32_e32 v62, v62, v170
	v_sub_f32_e32 v63, v63, v170
	s_mov_b32 s9, 1
.Lamla_nors_8:
	s_waitcnt lgkmcnt(3)
	v_mfma_f32_32x32x16_bf16 v[64:79], v[136:139], v[112:115], v[218:233]
	v_exp_f32_e32 v32, v32
	v_exp_f32_e32 v48, v48
	ds_read_b128 v[136:139], v243 offset:13376
	ds_read_b64_tr_b16 v[192:193], v162 offset:3072
	ds_read_b64_tr_b16 v[194:195], v162 offset:4608
	s_waitcnt lgkmcnt(5)
	v_mfma_f32_32x32x16_bf16 v[80:95], v[140:143], v[112:115], v[218:233]
	v_exp_f32_e32 v33, v33
	v_exp_f32_e32 v49, v49
	v_exp_f32_e32 v34, v34
	ds_read_b128 v[140:143], v243 offset:20032
	ds_read_b64_tr_b16 v[196:197], v162 offset:3136
	ds_read_b64_tr_b16 v[198:199], v162 offset:4672
	v_mfma_f32_32x32x16_bf16 v[0:15], v[184:187], v[104:107], v[0:15]
	v_exp_f32_e32 v50, v50
	v_cvt_pk_bf16_f32 v96, v32, v33
	ds_read_b64_tr_b16 v[200:201], v162 offset:9216
	ds_read_b64_tr_b16 v[202:203], v162 offset:10752
	s_waitcnt lgkmcnt(9)
	v_mfma_f32_32x32x16_bf16 v[64:79], v[144:147], v[116:119], v[64:79]
	v_exp_f32_e32 v35, v35
	v_exp_f32_e32 v51, v51
	ds_read_b128 v[144:147], v243 offset:13408
	ds_read_b64_tr_b16 v[204:205], v162 offset:9280
	ds_read_b64_tr_b16 v[206:207], v162 offset:10816
	v_mfma_f32_32x32x16_bf16 v[16:31], v[188:191], v[104:107], v[16:31]
	v_exp_f32_e32 v36, v36
	v_exp_f32_e32 v52, v52
	s_waitcnt lgkmcnt(11)
	v_mfma_f32_32x32x16_bf16 v[80:95], v[148:151], v[116:119], v[80:95]
	v_cvt_pk_bf16_f32 v97, v34, v35
	v_exp_f32_e32 v37, v37
	v_exp_f32_e32 v53, v53
	ds_read_b128 v[148:151], v243 offset:20064
	v_mfma_f32_16x16x32_bf16 v[234:237], v[246:249], v[104:107], v[234:237]
	v_cvt_pk_bf16_f32 v104, v48, v49
	v_cvt_pk_bf16_f32 v105, v50, v51
	v_exp_f32_e32 v38, v38
	v_exp_f32_e32 v54, v54
	s_waitcnt lgkmcnt(11)
	v_mfma_f32_32x32x16_bf16 v[64:79], v[136:139], v[120:123], v[64:79]
	v_cvt_pk_bf16_f32 v98, v36, v37
	v_cvt_pk_bf16_f32 v106, v52, v53
	v_exp_f32_e32 v39, v39
	ds_read_b128 v[136:139], v243 offset:13440
	s_waitcnt lgkmcnt(9)
	v_mfma_f32_32x32x16_bf16 v[80:95], v[140:143], v[120:123], v[80:95]
	v_exp_f32_e32 v55, v55
	v_exp_f32_e32 v40, v40
	ds_read_b128 v[140:143], v243 offset:20096
	v_mfma_f32_32x32x16_bf16 v[0:15], v[192:195], v[100:103], v[0:15]
	v_exp_f32_e32 v56, v56
	v_cvt_pk_bf16_f32 v99, v38, v39
	v_cvt_pk_bf16_f32 v107, v54, v55
	v_exp_f32_e32 v41, v41
	s_waitcnt lgkmcnt(5)
	v_mfma_f32_32x32x16_bf16 v[64:79], v[144:147], v[124:127], v[64:79]
	v_exp_f32_e32 v57, v57
	v_exp_f32_e32 v42, v42
	ds_read_b128 v[144:147], v243 offset:13472
	v_mfma_f32_32x32x16_bf16 v[16:31], v[196:199], v[100:103], v[16:31]
	v_exp_f32_e32 v58, v58
	v_exp_f32_e32 v43, v43
	s_waitcnt vmcnt(0)
	ds_write_b128 v164, v[156:159]
	s_waitcnt lgkmcnt(4)
	v_mfma_f32_32x32x16_bf16 v[80:95], v[148:151], v[124:127], v[80:95]
	v_exp_f32_e32 v59, v59
	v_exp_f32_e32 v44, v44
	ds_read_b128 v[148:151], v243 offset:20128
	v_mfma_f32_16x16x32_bf16 v[234:237], v[246:249], v[100:103], v[234:237]
	v_cvt_pk_bf16_f32 v100, v40, v41
	v_exp_f32_e32 v60, v60
	v_cvt_pk_bf16_f32 v101, v42, v43
	v_exp_f32_e32 v45, v45
	s_waitcnt lgkmcnt(4)
	v_mfma_f32_32x32x16_bf16 v[64:79], v[136:139], v[128:131], v[64:79]
	v_exp_f32_e32 v61, v61
	v_exp_f32_e32 v46, v46
	s_waitcnt lgkmcnt(3)
	v_mfma_f32_32x32x16_bf16 v[80:95], v[140:143], v[128:131], v[80:95]
	v_exp_f32_e32 v62, v62
	v_cvt_pk_bf16_f32 v102, v44, v45
	ds_read_b64_tr_b16 v[176:177], v163 offset:0
	ds_read_b64_tr_b16 v[178:179], v163 offset:1536
	v_mfma_f32_32x32x16_bf16 v[0:15], v[200:203], v[108:111], v[0:15]
	v_exp_f32_e32 v47, v47
	v_exp_f32_e32 v63, v63
	ds_read_b64_tr_b16 v[180:181], v163 offset:64
	ds_read_b64_tr_b16 v[182:183], v163 offset:1600
	s_waitcnt lgkmcnt(6)
	v_mfma_f32_32x32x16_bf16 v[64:79], v[144:147], v[132:135], v[64:79]
	v_cvt_pk_bf16_f32 v103, v46, v47
	ds_read_b64_tr_b16 v[184:185], v163 offset:6144
	ds_read_b64_tr_b16 v[186:187], v163 offset:7680
	v_mfma_f32_32x32x16_bf16 v[16:31], v[204:207], v[108:111], v[16:31]
	ds_read_b64_tr_b16 v[188:189], v163 offset:6208
	ds_read_b64_tr_b16 v[190:191], v163 offset:7744
	s_waitcnt lgkmcnt(8)
	v_mfma_f32_32x32x16_bf16 v[80:95], v[148:151], v[132:135], v[80:95]
	v_mfma_f32_16x16x32_bf16 v[234:237], v[246:249], v[108:111], v[234:237]
	v_cvt_pk_bf16_f32 v108, v56, v57
	v_cvt_pk_bf16_f32 v109, v58, v59
	v_cvt_pk_bf16_f32 v110, v60, v61
	v_cvt_pk_bf16_f32 v111, v62, v63
	s_cmp_lg_u32 s9, 0
	s_cbranch_scc0 .Lamla_noresc_9
	s_nop 15
	v_mul_f32_e32 v0, v0, v166
	v_mul_f32_e32 v1, v1, v166
	v_mul_f32_e32 v2, v2, v166
	v_mul_f32_e32 v3, v3, v166
	v_mul_f32_e32 v4, v4, v166
	v_mul_f32_e32 v5, v5, v166
	v_mul_f32_e32 v6, v6, v166
	v_mul_f32_e32 v7, v7, v166
	v_mul_f32_e32 v8, v8, v166
	v_mul_f32_e32 v9, v9, v166
	v_mul_f32_e32 v10, v10, v166
	v_mul_f32_e32 v11, v11, v166
	v_mul_f32_e32 v12, v12, v166
	v_mul_f32_e32 v13, v13, v166
	v_mul_f32_e32 v14, v14, v166
	v_mul_f32_e32 v15, v15, v166
	v_mul_f32_e32 v16, v16, v166
	v_mul_f32_e32 v17, v17, v166
	v_mul_f32_e32 v18, v18, v166
	v_mul_f32_e32 v19, v19, v166
	v_mul_f32_e32 v20, v20, v166
	v_mul_f32_e32 v21, v21, v166
	v_mul_f32_e32 v22, v22, v166
	v_mul_f32_e32 v23, v23, v166
	v_mul_f32_e32 v24, v24, v166
	v_mul_f32_e32 v25, v25, v166
	v_mul_f32_e32 v26, v26, v166
	v_mul_f32_e32 v27, v27, v166
	v_mul_f32_e32 v28, v28, v166
	v_mul_f32_e32 v29, v29, v166
	v_mul_f32_e32 v30, v30, v166
	v_mul_f32_e32 v31, v31, v166
	v_add_u32_e32 v170, 64, v175
	ds_bpermute_b32 v173, v170, v166
	v_mul_f32_e32 v234, v234, v166
	s_waitcnt lgkmcnt(0)
	v_mul_f32_e32 v235, v235, v173
.Lamla_noresc_9:
	s_nop 6
	s_barrier
	s_add_i32 s59, s6, s31
	s_cmp_ge_i32 s59, s8
	s_cbranch_scc1 .Lamla_nonext
	s_cmpk_gt_i32 s59, 0x3ff
	s_cbranch_scc0 .Lamla_mainitem_next
	s_add_i32 s21, s59, 0xfffffc00
	s_lshr_b32 s15, s21, 4
	s_and_b32 s18, s21, 15
	s_lshl_b32 s20, s15, 8
	s_add_i32 s20, s20, 0x4000
	s_mov_b32 s7, 0
	s_branch .Lamla_decoded_next

; template <bool MLA>
; DI void attn_phase(const int TID, const int BID, LAS unsigned char* lds, const Params& p, bool need_ctx) {
;     ...
;         int b, head, row0, nk;
;         if (item < 1024) {
;             const int rnd = item >> 8, w = item & 255, xcd = w & 7, slot = w >> 3, qb = slot & 7;
;             if (MLA) { const int grp = (rnd * 8 + xcd) * 4 + (slot >> 3); b = grp >> 4; head = grp & 15; }
;             else { const int grp = rnd * 8 + xcd; b = grp >> 2; head = (grp & 3) * 4 + (slot >> 3); }
;             row0 = b * 2048 + qb * 256; nk = NKEY;
;         }
;         else { const int it = item - 1024; b = it >> 4; head = it & 15; row0 = TL + b * 256; nk = 256; }
;         const int kvh = MLA ? head : (head >> 2);
;         const bf16_t* Kb = P_WSB(OFF_K) + (size_t)(b * NKV + kvh) * NKEY * 64;
;         const bf16_t* Vb = P_WSB(OFF_VT) + (size_t)(b * NKV + kvh) * NKEY * 64;
;         const bf16_t* Pb = P_WSB(OFF_KPE) + (size_t)b * NKEY * 32;
;         bf16x8 qf[NKS];
;         {
;             const bf16_t* qp = P_WSB(OFF_Q) + (size_t)(row0 + wid * 32 + r) * QS + head * DK + hh * 8;
; #pragma unroll
;             for (int ks = 0; ks < NKS; ++ks) qf[ks] = *(const bf16x8*)(qp + ks * 16);
;         }
;         u32x4 kreg, vreg; u32x2 preg = {0u, 0u};
.Lamla_decoded_next:
	s_mov_b32 s19, s18
	s_lshl_b32 s21, s15, 4
	s_add_i32 s21, s21, s19
	s_mul_i32 s21, s21, 0x48000
	s_add_u32 s2, s26, s21
	s_addc_u32 s3, s27, 0
	v_readlane_b32 s60, v254, 36
	v_readlane_b32 s61, v254, 37
	s_add_u32 s4, s60, s21
	s_addc_u32 s5, s61, 0
	v_readlane_b32 s60, v254, 38
	v_readlane_b32 s61, v254, 39
	s_mul_i32 s21, s15, 0x24000
	s_add_u32 s10, s60, s21
	s_addc_u32 s11, s61, 0
	v_readlane_b32 s60, v254, 27
	v_readlane_b32 s61, v254, 28
	s_mul_i32 s21, s20, 0xc00
	s_mul_i32 s55, s18, 0xc0
	s_add_i32 s21, s21, s55
	s_add_u32 s12, s60, s21
	s_addc_u32 s13, s61, 0
	v_readlane_b32 s60, v254, 34
	v_readlane_b32 s61, v254, 35
	s_lshl_b32 s21, s20, 11
	s_lshl_b32 s55, s18, 7
	s_add_i32 s21, s21, s55
	s_add_u32 s62, s60, s21
	s_addc_u32 s63, s61, 0
	global_load_dwordx4 v[112:115], v171, s[12:13]
	global_load_dwordx4 v[116:119], v171, s[12:13] offset:32
	global_load_dwordx4 v[120:123], v171, s[12:13] offset:64
	global_load_dwordx4 v[124:127], v171, s[12:13] offset:96
	global_load_dwordx4 v[128:131], v171, s[12:13] offset:128
	global_load_dwordx4 v[132:135], v171, s[12:13] offset:160
	global_load_dwordx4 v[136:139], v167, s[2:3]
	global_load_dwordx2 v[208:209], v165, s[10:11]
	s_add_u32 s2, s2, 0x2000
	s_addc_u32 s3, s3, 0
	s_add_u32 s10, s10, 0x1000
	s_addc_u32 s11, s11, 0
	global_load_dwordx4 v[140:143], v167, s[2:3]
	global_load_dwordx2 v[210:211], v165, s[10:11]
	s_add_u32 s2, s2, 0x2000
	s_addc_u32 s3, s3, 0
	s_add_u32 s10, s10, 0x1000
	s_addc_u32 s11, s11, 0
	global_load_dwordx4 v[144:147], v167, s[4:5]
	s_add_u32 s4, s4, 0x2000
	s_addc_u32 s5, s5, 0
	global_load_dwordx4 v[152:155], v167, s[2:3]
	global_load_dwordx2 v[160:161], v165, s[10:11]
	s_add_u32 s2, s2, 0x2000
	s_addc_u32 s3, s3, 0
	s_add_u32 s10, s10, 0x1000
	s_addc_u32 s11, s11, 0
	global_load_dwordx4 v[156:159], v167, s[4:5]
	s_add_u32 s4, s4, 0x2000
	s_addc_u32 s5, s5, 0
.Lamla_nonext:
	ds_read_b64_tr_b16 v[192:193], v163 offset:3072
	ds_read_b64_tr_b16 v[194:195], v163 offset:4608
	ds_read_b64_tr_b16 v[196:197], v163 offset:3136
	ds_read_b64_tr_b16 v[198:199], v163 offset:4672
	s_waitcnt lgkmcnt(10)
	v_mfma_f32_32x32x16_bf16 v[0:15], v[176:179], v[96:99], v[0:15]
	v_max3_f32 v168, v64, v65, v66
	v_max3_f32 v170, v80, v81, v82
	v_max3_f32 v168, v168, v67, v68
	v_max3_f32 v170, v170, v83, v84
	v_max3_f32 v168, v168, v69, v70
	v_max3_f32 v170, v170, v85, v86
	v_max3_f32 v168, v168, v71, v72
	v_max3_f32 v170, v170, v87, v88
	v_max3_f32 v168, v168, v73, v74
	s_mov_b32 s55, s52
	s_mov_b32 s52, s53
	s_mov_b32 s53, s54
	s_mov_b32 s54, s55
	s_mov_b32 s9, 0
	ds_read_b64_tr_b16 v[200:201], v163 offset:9216
	ds_read_b64_tr_b16 v[202:203], v163 offset:10752
	ds_read_b64_tr_b16 v[204:205], v163 offset:9280
	ds_read_b64_tr_b16 v[206:207], v163 offset:10816
	s_waitcnt lgkmcnt(12)
	v_mfma_f32_32x32x16_bf16 v[16:31], v[180:183], v[96:99], v[16:31]
	v_max3_f32 v170, v170, v89, v90
	v_max3_f32 v168, v168, v75, v76
	v_max3_f32 v170, v170, v91, v92
	v_max3_f32 v168, v168, v77, v78
	v_max3_f32 v170, v170, v93, v94
	v_max_f32_e32 v168, v168, v79
	v_max_f32_e32 v170, v170, v95
	v_max_f32_e32 v168, v168, v170
	v_add_u32_e32 v162, s53, v240
	v_mfma_f32_16x16x32_bf16 v[234:237], v[246:249], v[96:99], v[234:237]
	v_mov_b32_e32 v170, v168
	s_nop 1
	v_permlane32_swap_b32_e32 v168, v170
	v_max_f32_e32 v168, v168, v170
	v_cmp_lt_f32_e32 vcc, 0x41000000, v168
	s_cbranch_vccz .Lamla_nors_10
	v_max_f32_e32 v170, 0, v168
	v_exp_f32_e64 v166, -v170
	v_sub_f32_e32 v218, v218, v170
	v_sub_f32_e32 v219, v219, v170
	v_sub_f32_e32 v220, v220, v170
	v_sub_f32_e32 v221, v221, v170
	v_sub_f32_e32 v222, v222, v170
	v_sub_f32_e32 v223, v223, v170
	v_sub_f32_e32 v224, v224, v170
	v_sub_f32_e32 v225, v225, v170
	v_sub_f32_e32 v226, v226, v170
	v_sub_f32_e32 v227, v227, v170
	v_sub_f32_e32 v228, v228, v170
	v_sub_f32_e32 v229, v229, v170
	v_sub_f32_e32 v230, v230, v170
	v_sub_f32_e32 v231, v231, v170
	v_sub_f32_e32 v232, v232, v170
	v_sub_f32_e32 v233, v233, v170
	v_sub_f32_e32 v64, v64, v170
	v_sub_f32_e32 v65, v65, v170
	v_sub_f32_e32 v66, v66, v170
	v_sub_f32_e32 v67, v67, v170
	v_sub_f32_e32 v68, v68, v170
	v_sub_f32_e32 v69, v69, v170
	v_sub_f32_e32 v70, v70, v170
	v_sub_f32_e32 v71, v71, v170
	v_sub_f32_e32 v72, v72, v170
	v_sub_f32_e32 v73, v73, v170
	v_sub_f32_e32 v74, v74, v170
	v_sub_f32_e32 v75, v75, v170
	v_sub_f32_e32 v76, v76, v170
	v_sub_f32_e32 v77, v77, v170
	v_sub_f32_e32 v78, v78, v170
	v_sub_f32_e32 v79, v79, v170
	v_sub_f32_e32 v80, v80, v170
	v_sub_f32_e32 v81, v81, v170
	v_sub_f32_e32 v82, v82, v170
	v_sub_f32_e32 v83, v83, v170
	v_sub_f32_e32 v84, v84, v170
	v_sub_f32_e32 v85, v85, v170
	v_sub_f32_e32 v86, v86, v170
	v_sub_f32_e32 v87, v87, v170
	v_sub_f32_e32 v88, v88, v170
	v_sub_f32_e32 v89, v89, v170
	v_sub_f32_e32 v90, v90, v170
	v_sub_f32_e32 v91, v91, v170
	v_sub_f32_e32 v92, v92, v170
	v_sub_f32_e32 v93, v93, v170
	v_sub_f32_e32 v94, v94, v170
	v_sub_f32_e32 v95, v95, v170
	s_mov_b32 s9, 1
.Lamla_nors_10:
	v_exp_f32_e32 v64, v64
	v_exp_f32_e32 v80, v80
	s_waitcnt lgkmcnt(10)
	v_mfma_f32_32x32x16_bf16 v[0:15], v[184:187], v[104:107], v[0:15]
	v_exp_f32_e32 v65, v65
	v_exp_f32_e32 v81, v81
	v_exp_f32_e32 v66, v66
	v_exp_f32_e32 v82, v82
	s_waitcnt lgkmcnt(8)
	v_mfma_f32_32x32x16_bf16 v[16:31], v[188:191], v[104:107], v[16:31]
	v_cvt_pk_bf16_f32 v96, v64, v65
	v_exp_f32_e32 v67, v67
	v_exp_f32_e32 v83, v83
	v_exp_f32_e32 v68, v68
	v_exp_f32_e32 v84, v84
	v_mfma_f32_16x16x32_bf16 v[234:237], v[246:249], v[104:107], v[234:237]
	v_cvt_pk_bf16_f32 v104, v80, v81
	v_cvt_pk_bf16_f32 v97, v66, v67
	v_cvt_pk_bf16_f32 v105, v82, v83
	v_exp_f32_e32 v69, v69
	v_exp_f32_e32 v85, v85
	v_exp_f32_e32 v70, v70
	s_waitcnt lgkmcnt(6)
	v_mfma_f32_32x32x16_bf16 v[0:15], v[192:195], v[100:103], v[0:15]
	v_exp_f32_e32 v86, v86
	v_cvt_pk_bf16_f32 v98, v68, v69
	v_cvt_pk_bf16_f32 v106, v84, v85
	v_exp_f32_e32 v71, v71
	v_exp_f32_e32 v87, v87
	v_exp_f32_e32 v72, v72
	ds_read_b64_tr_b16 v[176:177], v162 offset:0
	ds_read_b64_tr_b16 v[178:179], v162 offset:1536
	s_waitcnt lgkmcnt(6)
	v_mfma_f32_32x32x16_bf16 v[16:31], v[196:199], v[100:103], v[16:31]
	v_exp_f32_e32 v88, v88
	v_cvt_pk_bf16_f32 v99, v70, v71
	v_cvt_pk_bf16_f32 v107, v86, v87
	v_exp_f32_e32 v73, v73
	v_exp_f32_e32 v89, v89
	ds_read_b64_tr_b16 v[180:181], v162 offset:64
	ds_read_b64_tr_b16 v[182:183], v162 offset:1600
	v_mfma_f32_16x16x32_bf16 v[234:237], v[246:249], v[100:103], v[234:237]
	v_exp_f32_e32 v74, v74
	v_exp_f32_e32 v90, v90
	v_cvt_pk_bf16_f32 v100, v72, v73
	v_exp_f32_e32 v75, v75
	v_exp_f32_e32 v91, v91
	ds_read_b64_tr_b16 v[184:185], v162 offset:6144
	ds_read_b64_tr_b16 v[186:187], v162 offset:7680
	s_waitcnt lgkmcnt(8)
	v_mfma_f32_32x32x16_bf16 v[0:15], v[200:203], v[108:111], v[0:15]
	v_exp_f32_e32 v76, v76
	v_exp_f32_e32 v92, v92
	v_cvt_pk_bf16_f32 v101, v74, v75
	v_exp_f32_e32 v77, v77
	ds_read_b64_tr_b16 v[188:189], v162 offset:6208
	ds_read_b64_tr_b16 v[190:191], v162 offset:7744
	s_waitcnt lgkmcnt(8)
	v_mfma_f32_32x32x16_bf16 v[16:31], v[204:207], v[108:111], v[16:31]
	v_exp_f32_e32 v93, v93
	v_exp_f32_e32 v78, v78
	v_exp_f32_e32 v94, v94
	v_cvt_pk_bf16_f32 v102, v76, v77
	v_exp_f32_e32 v79, v79
	v_mfma_f32_16x16x32_bf16 v[234:237], v[246:249], v[108:111], v[234:237]
	v_cvt_pk_bf16_f32 v108, v88, v89
	v_cvt_pk_bf16_f32 v109, v90, v91
	v_cvt_pk_bf16_f32 v110, v92, v93
	v_exp_f32_e32 v95, v95
	v_cvt_pk_bf16_f32 v103, v78, v79
	v_cvt_pk_bf16_f32 v111, v94, v95
	s_cmp_lg_u32 s9, 0
	s_cbranch_scc0 .Lamla_noresc_11
	s_nop 15
	v_mul_f32_e32 v0, v0, v166
	v_mul_f32_e32 v1, v1, v166
	v_mul_f32_e32 v2, v2, v166
	v_mul_f32_e32 v3, v3, v166
	v_mul_f32_e32 v4, v4, v166
	v_mul_f32_e32 v5, v5, v166
	v_mul_f32_e32 v6, v6, v166
	v_mul_f32_e32 v7, v7, v166
	v_mul_f32_e32 v8, v8, v166
	v_mul_f32_e32 v9, v9, v166
	v_mul_f32_e32 v10, v10, v166
	v_mul_f32_e32 v11, v11, v166
	v_mul_f32_e32 v12, v12, v166
	v_mul_f32_e32 v13, v13, v166
	v_mul_f32_e32 v14, v14, v166
	v_mul_f32_e32 v15, v15, v166
	v_mul_f32_e32 v16, v16, v166
	v_mul_f32_e32 v17, v17, v166
	v_mul_f32_e32 v18, v18, v166
	v_mul_f32_e32 v19, v19, v166
	v_mul_f32_e32 v20, v20, v166
	v_mul_f32_e32 v21, v21, v166
	v_mul_f32_e32 v22, v22, v166
	v_mul_f32_e32 v23, v23, v166
	v_mul_f32_e32 v24, v24, v166
	v_mul_f32_e32 v25, v25, v166
	v_mul_f32_e32 v26, v26, v166
	v_mul_f32_e32 v27, v27, v166
	v_mul_f32_e32 v28, v28, v166
	v_mul_f32_e32 v29, v29, v166
	v_mul_f32_e32 v30, v30, v166
	v_mul_f32_e32 v31, v31, v166
	v_add_u32_e32 v170, 64, v175
	ds_bpermute_b32 v173, v170, v166
	v_mul_f32_e32 v234, v234, v166
	s_waitcnt lgkmcnt(0)
	v_mul_f32_e32 v235, v235, v173
; #define AT_PK4(OX, jg) u32x2 { pk_bf16(OX[4 * (jg)] * inv, OX[4 * (jg) + 1] * inv), pk_bf16(OX[4 * (jg) + 2] * inv, OX[4 * (jg) + 3] * inv) }
; template <bool MLA>
; DI void attn_phase(const int TID, const int BID, LAS unsigned char* lds, const Params& p, bool need_ctx) {
;     ...
;         __builtin_amdgcn_s_setprio(0);
;         lsum = xsum32(lsum);
;         const float inv = 1.f / lsum;
;         bf16_t* op = O + (size_t)(row0 + wid * 32 + r) * 1024 + head * 64 + 8 * hh;
;     ...
; #pragma unroll
;         for (int k = 0; k < 2; ++k) {
;             const u32x2 a = AT_PK4(o0, 2 * k), b2 = AT_PK4(o0, 2 * k + 1), c = AT_PK4(o1, 2 * k), d = AT_PK4(o1, 2 * k + 1);
;             const u32x2 s0 = __builtin_amdgcn_permlane32_swap(a[0], b2[0], false, false), s1 = __builtin_amdgcn_permlane32_swap(a[1], b2[1], false, false);
;             const u32x2 t0 = __builtin_amdgcn_permlane32_swap(c[0], d[0], false, false), t1 = __builtin_amdgcn_permlane32_swap(c[1], d[1], false, false);
;             const u32x4 w0 = {s0[0], s1[0], s0[1], s1[1]}, w1 = {t0[0], t1[0], t0[1], t1[1]};
;             *(u32x4*)(op + 16 * k) = w0; *(u32x4*)(op + 32 + 16 * k) = w1;
;         }
.Lamla_noresc_11:
	s_barrier
	ds_read_b64_tr_b16 v[192:193], v162 offset:3072
	ds_read_b64_tr_b16 v[194:195], v162 offset:4608
	ds_read_b64_tr_b16 v[196:197], v162 offset:3136
	ds_read_b64_tr_b16 v[198:199], v162 offset:4672
	s_waitcnt lgkmcnt(10)
	v_mfma_f32_32x32x16_bf16 v[0:15], v[176:179], v[96:99], v[0:15]
	s_mov_b32 s55, s52
	s_mov_b32 s52, s53
	s_mov_b32 s53, s54
	s_mov_b32 s54, s55
	ds_read_b64_tr_b16 v[200:201], v162 offset:9216
	ds_read_b64_tr_b16 v[202:203], v162 offset:10752
	ds_read_b64_tr_b16 v[204:205], v162 offset:9280
	ds_read_b64_tr_b16 v[206:207], v162 offset:10816
	s_waitcnt lgkmcnt(12)
	v_mfma_f32_32x32x16_bf16 v[16:31], v[180:183], v[96:99], v[16:31]
	v_mfma_f32_16x16x32_bf16 v[234:237], v[246:249], v[96:99], v[234:237]
	s_waitcnt lgkmcnt(10)
	v_mfma_f32_32x32x16_bf16 v[0:15], v[184:187], v[104:107], v[0:15]
	s_waitcnt lgkmcnt(8)
	v_mfma_f32_32x32x16_bf16 v[16:31], v[188:191], v[104:107], v[16:31]
	v_mfma_f32_16x16x32_bf16 v[234:237], v[246:249], v[104:107], v[234:237]
	s_waitcnt lgkmcnt(6)
	v_mfma_f32_32x32x16_bf16 v[0:15], v[192:195], v[100:103], v[0:15]
	s_waitcnt lgkmcnt(4)
	v_mfma_f32_32x32x16_bf16 v[16:31], v[196:199], v[100:103], v[16:31]
	v_mfma_f32_16x16x32_bf16 v[234:237], v[246:249], v[100:103], v[234:237]
	s_waitcnt lgkmcnt(2)
	v_mfma_f32_32x32x16_bf16 v[0:15], v[200:203], v[108:111], v[0:15]
	s_waitcnt lgkmcnt(0)
	v_mfma_f32_32x32x16_bf16 v[16:31], v[204:207], v[108:111], v[16:31]
	v_mfma_f32_16x16x32_bf16 v[234:237], v[246:249], v[108:111], v[234:237]
	s_setprio 0
	s_nop 11
	ds_bpermute_b32 v173, v175, v234
	ds_bpermute_b32 v217, v175, v235
	s_mov_b32 s60, 0xffff0000
	s_mov_b32 s61, 0xffff0000
	s_waitcnt lgkmcnt(0)
	v_cndmask_b32_e64 v234, v173, v217, s[60:61]
	v_div_scale_f32 v148, s[60:61], v234, v234, 1.0
	v_rcp_f32_e32 v149, v148
	s_nop 0
	v_fma_f32 v150, -v148, v149, 1.0
	v_fmac_f32_e32 v149, v150, v149
	v_div_scale_f32 v150, vcc, 1.0, v234, 1.0
	v_mul_f32_e32 v151, v150, v149
	v_fma_f32 v173, -v148, v151, v150
	v_fmac_f32_e32 v151, v173, v149
	v_fma_f32 v148, -v148, v151, v150
	s_nop 1
	v_div_fmas_f32 v148, v148, v149, v151
	v_div_fixup_f32 v212, v148, v234, 1.0
	v_pk_mul_f32 v[0:1], v[0:1], v[212:213] op_sel_hi:[1,0]
	v_pk_mul_f32 v[2:3], v[2:3], v[212:213] op_sel_hi:[1,0]
	v_pk_mul_f32 v[4:5], v[4:5], v[212:213] op_sel_hi:[1,0]
	v_pk_mul_f32 v[6:7], v[6:7], v[212:213] op_sel_hi:[1,0]
	v_pk_mul_f32 v[8:9], v[8:9], v[212:213] op_sel_hi:[1,0]
	v_pk_mul_f32 v[10:11], v[10:11], v[212:213] op_sel_hi:[1,0]
	v_pk_mul_f32 v[12:13], v[12:13], v[212:213] op_sel_hi:[1,0]
	v_pk_mul_f32 v[14:15], v[14:15], v[212:213] op_sel_hi:[1,0]
	v_pk_mul_f32 v[16:17], v[16:17], v[212:213] op_sel_hi:[1,0]
	v_pk_mul_f32 v[18:19], v[18:19], v[212:213] op_sel_hi:[1,0]
	v_pk_mul_f32 v[20:21], v[20:21], v[212:213] op_sel_hi:[1,0]
	v_pk_mul_f32 v[22:23], v[22:23], v[212:213] op_sel_hi:[1,0]
	v_pk_mul_f32 v[24:25], v[24:25], v[212:213] op_sel_hi:[1,0]
	v_pk_mul_f32 v[26:27], v[26:27], v[212:213] op_sel_hi:[1,0]
	v_pk_mul_f32 v[28:29], v[28:29], v[212:213] op_sel_hi:[1,0]
	v_pk_mul_f32 v[30:31], v[30:31], v[212:213] op_sel_hi:[1,0]
	v_cvt_pk_bf16_f32 v96, v0, v1
	v_cvt_pk_bf16_f32 v97, v2, v3
	v_cvt_pk_bf16_f32 v98, v4, v5
	v_cvt_pk_bf16_f32 v99, v6, v7
	v_cvt_pk_bf16_f32 v100, v16, v17
	v_cvt_pk_bf16_f32 v101, v18, v19
	v_cvt_pk_bf16_f32 v102, v20, v21
	v_cvt_pk_bf16_f32 v103, v22, v23
	v_cvt_pk_bf16_f32 v104, v8, v9
	v_cvt_pk_bf16_f32 v105, v10, v11
	v_cvt_pk_bf16_f32 v106, v12, v13
	v_cvt_pk_bf16_f32 v107, v14, v15
	v_cvt_pk_bf16_f32 v108, v24, v25
	v_cvt_pk_bf16_f32 v109, v26, v27
	v_cvt_pk_bf16_f32 v110, v28, v29
	v_cvt_pk_bf16_f32 v111, v30, v31
	s_nop 1
	v_permlane32_swap_b32_e32 v96, v98
	v_permlane32_swap_b32_e32 v97, v99
	v_permlane32_swap_b32_e32 v100, v102
	v_permlane32_swap_b32_e32 v101, v103
	v_permlane32_swap_b32_e32 v104, v106
	v_permlane32_swap_b32_e32 v105, v107
	v_permlane32_swap_b32_e32 v108, v110
	v_permlane32_swap_b32_e32 v109, v111
	global_store_dwordx4 v172, v[96:99], s[16:17]
	global_store_dwordx4 v172, v[100:103], s[16:17] offset:64
	global_store_dwordx4 v172, v[104:107], s[16:17] offset:32
	global_store_dwordx4 v172, v[108:111], s[16:17] offset:96
	s_mov_b32 s6, s59
	s_mov_b64 s[16:17], s[62:63]
	s_cmp_ge_i32 s6, s8
	s_cbranch_scc0 .Lamla_item

; template <bool MLA>
; DI void attn_phase(const int TID, const int BID, LAS unsigned char* lds, const Params& p, bool need_ctx) {
;     ...
;     const int tid = TID, wid = tid >> 6, lane = tid & 63, r = lane & 31, hh = lane >> 5;
;     const int n_items = 1024 + (need_ctx ? 128 : 0);
;     bf16_t* O = P_WSB(OFF_H);
;     for (int item = BID; item < n_items; item += gridDim.x) {
;         int b, head, row0, nk;
;         if (item < 1024) {
;             const int rnd = item >> 8, w = item & 255, xcd = w & 7, slot = w >> 3, qb = slot & 7;
;             if (MLA) { const int grp = (rnd * 8 + xcd) * 4 + (slot >> 3); b = grp >> 4; head = grp & 15; }
;             else { const int grp = rnd * 8 + xcd; b = grp >> 2; head = (grp & 3) * 4 + (slot >> 3); }
;             row0 = b * 2048 + qb * 256; nk = NKEY;
;         }
;         else { const int it = item - 1024; b = it >> 4; head = it & 15; row0 = TL + b * 256; nk = 256; }
;         const int kvh = MLA ? head : (head >> 2);
;         const bf16_t* Kb = P_WSB(OFF_K) + (size_t)(b * NKV + kvh) * NKEY * 64;
;         const bf16_t* Vb = P_WSB(OFF_VT) + (size_t)(b * NKV + kvh) * NKEY * 64;
;         const bf16_t* Pb = P_WSB(OFF_KPE) + (size_t)b * NKEY * 32;
.LBB0_318:
	s_andn2_b64 vcc, exec, s[4:5]
	s_cbranch_vccnz .LBB0_339
	s_and_b64 vcc, exec, s[2:3]
	s_cbranch_vccnz .LBB0_339
	v_and_b32_e32 v208, 31, v174
	v_bfe_u32 v209, v174, 5, 1
	v_lshrrev_b32_e32 v210, 6, v174
	v_lshrrev_b32_e32 v211, 3, v174
	v_and_b32_e32 v212, 7, v174
	v_mov_b32_e32 v213, s23
	s_movk_i32 s15, 0x90
	v_mad_u32_u24 v243, v208, s15, v213
	v_lshl_add_u32 v243, v209, 4, v243
	v_mad_u32_u24 v238, v211, s15, v213
	v_lshl_add_u32 v238, v212, 4, v238
	s_movk_i32 s15, 0xc0
	v_bfe_u32 v214, v174, 2, 2
	v_lshl_add_u32 v214, v209, 2, v214
	v_mad_u32_u24 v240, v214, s15, v213
	v_bfe_u32 v215, v174, 4, 1
	v_and_b32_e32 v216, 3, v174
	v_lshlrev_b32_e32 v215, 5, v215
	v_lshl_add_u32 v215, v216, 3, v215
	v_add_u32_e32 v240, v240, v215
	v_add_u32_e32 v240, 0x4800, v240
	v_mad_u32_u24 v241, v211, s15, v213
	v_lshl_add_u32 v241, v212, 4, v241
	v_add_u32_e32 v241, 0x4800, v241
	v_lshlrev_b32_e32 v167, 7, v211
	v_lshl_add_u32 v167, v212, 4, v167
	v_lshl_add_u32 v217, v210, 5, v208
	s_movk_i32 s15, 0x800
	v_mul_u32_u24_e32 v171, s15, v217
	v_lshl_add_u32 v171, v209, 4, v171
	v_lshlrev_b32_e32 v172, 11, v217
	v_lshl_add_u32 v172, v209, 4, v172
	v_and_b32_e32 v214, 15, v174
	v_bfe_u32 v215, v174, 4, 1
	v_cmp_eq_u32_e32 vcc, v214, v215
	v_mov_b32_e32 v216, 0x3f803f80
	s_nop 1
	v_cndmask_b32_e32 v246, 0, v216, vcc
	v_cndmask_b32_e32 v247, 0, v216, vcc
	v_cndmask_b32_e32 v248, 0, v216, vcc
	v_cndmask_b32_e32 v249, 0, v216, vcc
	v_lshlrev_b32_e32 v175, 2, v214
	v_readfirstlane_b32 s58, v210
	s_mov_b32 s6, s83
	s_lshr_b32 s58, s58, 2
	s_cmpk_gt_i32 s6, 0x3ff
	s_cbranch_scc0 .Lagqa_mainitem_first
	s_add_i32 s21, s6, 0xfffffc00
	s_lshr_b32 s15, s21, 4
	s_and_b32 s18, s21, 15
	s_lshl_b32 s20, s15, 8
	s_add_i32 s20, s20, 0x4000
	s_mov_b32 s7, 0
	s_branch .Lagqa_decoded_first

; #define AT_GLOADK(k0) do { kreg = *(const u32x4*)(Kb + (size_t)((k0) + (tid >> 3)) * 64 + (tid & 7) * 8); \
;             if (MLA) preg = *(const u32x2*)(Pb + (size_t)((k0) + (tid >> 3)) * 32 + (tid & 7) * 4); } while (0)
; #define AT_GLOADV(k0) do { vreg = *(const u32x4*)(Vb + (size_t)((k0) + (tid >> 3)) * 64 + (tid & 7) * 8); } while (0)
; #define AT_WRITEK(buf) do { *(LAS u32x4*)(lds + (buf) * KBUF + (tid >> 3) * KSTR + (tid & 7) * 16) = kreg; \
;             if (MLA) *(LAS u32x2*)(lds + (buf) * KBUF + (tid >> 3) * KSTR + 128 + (tid & 7) * 8) = preg; } while (0)
; #define AT_WRITEV(buf) do { *(LAS u32x4*)(lds + 2 * KBUF + (buf) * VBUF + (tid >> 3) * VSTR + (tid & 7) * 16) = vreg; } while (0)
; template <bool MLA>
; DI void attn_phase(const int TID, const int BID, LAS unsigned char* lds, const Params& p, bool need_ctx) {
;     ...
;         f32x16 o0, o1, sa0, sa1, sb0, sb1;
; #pragma unroll
;         for (int j = 0; j < 16; ++j) { o0[j] = 0.f; o1[j] = 0.f; }
;         float mrun = -1e30f, lsum = 0.f;
;         if (wid >= 4) __builtin_amdgcn_s_setprio(1);
;         const int ntile = nk >> 6;
;         AT_GLOADK(0); AT_GLOADV(0); AT_WRITEK(0); AT_WRITEV(0);
;         AT_GLOADK(64); AT_WRITEK(1);
;         __syncthreads();
;         AT_QK(sa0, sa1, 0);
;         __syncthreads();
.Lagqa_decoded_first:
	s_lshr_b32 s19, s18, 2
	s_lshl_b32 s21, s15, 2
	s_add_i32 s21, s21, s19
	s_mul_i32 s21, s21, 0x48000
	s_add_u32 s2, s26, s21
	s_addc_u32 s3, s27, 0
	v_readlane_b32 s60, v254, 36
	v_readlane_b32 s61, v254, 37
	s_add_u32 s4, s60, s21
	s_addc_u32 s5, s61, 0
	v_readlane_b32 s60, v254, 27
	v_readlane_b32 s61, v254, 28
	s_mul_i32 s21, s20, 0x800
	s_mul_i32 s55, s18, 0x80
	s_add_i32 s21, s21, s55
	s_add_u32 s12, s60, s21
	s_addc_u32 s13, s61, 0
	v_readlane_b32 s60, v254, 34
	v_readlane_b32 s61, v254, 35
	s_lshl_b32 s21, s20, 11
	s_lshl_b32 s55, s18, 7
	s_add_i32 s21, s21, s55
	s_add_u32 s16, s60, s21
	s_addc_u32 s17, s61, 0
	global_load_dwordx4 v[112:115], v171, s[12:13]
	global_load_dwordx4 v[116:119], v171, s[12:13] offset:32
	global_load_dwordx4 v[120:123], v171, s[12:13] offset:64
	global_load_dwordx4 v[124:127], v171, s[12:13] offset:96
	global_load_dwordx4 v[136:139], v167, s[2:3]
	s_add_u32 s2, s2, 0x2000
	s_addc_u32 s3, s3, 0
	global_load_dwordx4 v[140:143], v167, s[2:3]
	s_add_u32 s2, s2, 0x2000
	s_addc_u32 s3, s3, 0
	global_load_dwordx4 v[144:147], v167, s[4:5]
	s_add_u32 s4, s4, 0x2000
	s_addc_u32 s5, s5, 0
	global_load_dwordx4 v[152:155], v167, s[2:3]
	s_add_u32 s2, s2, 0x2000
	s_addc_u32 s3, s3, 0
	global_load_dwordx4 v[156:159], v167, s[4:5]
	s_add_u32 s4, s4, 0x2000
	s_addc_u32 s5, s5, 0
.Lagqa_item:
	s_mov_b32 s52, 0x3000
	s_mov_b32 s53, 0x6000
	s_mov_b32 s54, 0
	v_mov_b64_e32 v[0:1], 0
	v_mov_b64_e32 v[2:3], 0
	v_mov_b64_e32 v[4:5], 0
	v_mov_b64_e32 v[6:7], 0
	v_mov_b64_e32 v[8:9], 0
	v_mov_b64_e32 v[10:11], 0
	v_mov_b64_e32 v[12:13], 0
	v_mov_b64_e32 v[14:15], 0
	v_mov_b64_e32 v[16:17], 0
	v_mov_b64_e32 v[18:19], 0
	v_mov_b64_e32 v[20:21], 0
	v_mov_b64_e32 v[22:23], 0
	v_mov_b64_e32 v[24:25], 0
	v_mov_b64_e32 v[26:27], 0
	v_mov_b64_e32 v[28:29], 0
	v_mov_b64_e32 v[30:31], 0
	v_mov_b64_e32 v[218:219], 0
	v_mov_b64_e32 v[220:221], 0
	v_mov_b64_e32 v[222:223], 0
	v_mov_b64_e32 v[224:225], 0
	v_mov_b64_e32 v[226:227], 0
	v_mov_b64_e32 v[228:229], 0
	v_mov_b64_e32 v[230:231], 0
	v_mov_b64_e32 v[232:233], 0
	v_mov_b64_e32 v[234:235], 0
	v_mov_b64_e32 v[236:237], 0
	s_barrier
	s_waitcnt vmcnt(4)
	ds_write_b128 v238, v[136:139]
	s_waitcnt vmcnt(3)
	ds_write_b128 v238, v[140:143] offset:9216
	s_waitcnt vmcnt(2)
	ds_write_b128 v241, v[144:147]
	s_waitcnt lgkmcnt(0)
	s_barrier
	s_cmp_eq_u32 s58, 0
	s_cbranch_scc1 .Lagqa_prio
	s_setprio 1
.Lagqa_prio:
	ds_read_b128 v[136:139], v243 offset:0
	ds_read_b128 v[140:143], v243 offset:4608
	ds_read_b128 v[144:147], v243 offset:32
	ds_read_b128 v[148:151], v243 offset:4640
	s_waitcnt lgkmcnt(3)
	v_mfma_f32_32x32x16_bf16 v[32:47], v[136:139], v[112:115], 0
	ds_read_b128 v[136:139], v243 offset:64
	s_waitcnt lgkmcnt(3)
	v_mfma_f32_32x32x16_bf16 v[48:63], v[140:143], v[112:115], 0
	ds_read_b128 v[140:143], v243 offset:4672
	s_waitcnt lgkmcnt(3)
	v_mfma_f32_32x32x16_bf16 v[32:47], v[144:147], v[116:119], v[32:47]
	ds_read_b128 v[144:147], v243 offset:96
	s_waitcnt lgkmcnt(3)
	v_mfma_f32_32x32x16_bf16 v[48:63], v[148:151], v[116:119], v[48:63]
	ds_read_b128 v[148:151], v243 offset:4704
	s_waitcnt lgkmcnt(3)
	v_mfma_f32_32x32x16_bf16 v[32:47], v[136:139], v[120:123], v[32:47]
	s_waitcnt lgkmcnt(2)
	v_mfma_f32_32x32x16_bf16 v[48:63], v[140:143], v[120:123], v[48:63]
	s_waitcnt lgkmcnt(1)
	v_mfma_f32_32x32x16_bf16 v[32:47], v[144:147], v[124:127], v[32:47]
	s_waitcnt lgkmcnt(0)
	v_mfma_f32_32x32x16_bf16 v[48:63], v[148:151], v[124:127], v[48:63]
	s_waitcnt lgkmcnt(0)
	s_nop 7
	s_barrier
	ds_read_b128 v[136:139], v243 offset:9216
	ds_read_b128 v[140:143], v243 offset:13824
	ds_read_b128 v[144:147], v243 offset:9248
	ds_read_b128 v[148:151], v243 offset:13856
	v_max3_f32 v168, v32, v33, v34
	v_max3_f32 v170, v48, v49, v50
	v_max3_f32 v168, v168, v35, v36
	v_max3_f32 v170, v170, v51, v52
	v_max3_f32 v168, v168, v37, v38
	v_max3_f32 v170, v170, v53, v54
	v_max3_f32 v168, v168, v39, v40
	v_max3_f32 v170, v170, v55, v56
	v_max3_f32 v168, v168, v41, v42
	v_max3_f32 v170, v170, v57, v58
	v_max3_f32 v168, v168, v43, v44
	v_max3_f32 v170, v170, v59, v60
	v_max3_f32 v168, v168, v45, v46
	v_max3_f32 v170, v170, v61, v62
	v_max_f32_e32 v168, v168, v47
	v_max_f32_e32 v170, v170, v63
	v_max_f32_e32 v168, v168, v170
	v_mov_b32_e32 v170, v168
	s_nop 1
	v_permlane32_swap_b32_e32 v168, v170
	v_max_f32_e32 v168, v168, v170
	v_mov_b32_e32 v170, v168
	v_sub_f32_e32 v218, v218, v170
	v_sub_f32_e32 v219, v219, v170
	v_sub_f32_e32 v220, v220, v170
	v_sub_f32_e32 v221, v221, v170
	v_sub_f32_e32 v222, v222, v170
	v_sub_f32_e32 v223, v223, v170
	v_sub_f32_e32 v224, v224, v170
	v_sub_f32_e32 v225, v225, v170
	v_sub_f32_e32 v226, v226, v170
	v_sub_f32_e32 v227, v227, v170
	v_sub_f32_e32 v228, v228, v170
	v_sub_f32_e32 v229, v229, v170
	v_sub_f32_e32 v230, v230, v170
	v_sub_f32_e32 v231, v231, v170
	v_sub_f32_e32 v232, v232, v170
	v_sub_f32_e32 v233, v233, v170
	v_sub_f32_e32 v32, v32, v170
	v_sub_f32_e32 v33, v33, v170
	v_sub_f32_e32 v34, v34, v170
	v_sub_f32_e32 v35, v35, v170
	v_sub_f32_e32 v36, v36, v170
	v_sub_f32_e32 v37, v37, v170
	v_sub_f32_e32 v38, v38, v170
	v_sub_f32_e32 v39, v39, v170
	v_sub_f32_e32 v40, v40, v170
	v_sub_f32_e32 v41, v41, v170
	v_sub_f32_e32 v42, v42, v170
	v_sub_f32_e32 v43, v43, v170
	v_sub_f32_e32 v44, v44, v170
	v_sub_f32_e32 v45, v45, v170
	v_sub_f32_e32 v46, v46, v170
	v_sub_f32_e32 v47, v47, v170
	v_sub_f32_e32 v48, v48, v170
	v_sub_f32_e32 v49, v49, v170
	v_sub_f32_e32 v50, v50, v170
	v_sub_f32_e32 v51, v51, v170
	v_sub_f32_e32 v52, v52, v170
	v_sub_f32_e32 v53, v53, v170
	v_sub_f32_e32 v54, v54, v170
	v_sub_f32_e32 v55, v55, v170
	v_sub_f32_e32 v56, v56, v170
	v_sub_f32_e32 v57, v57, v170
	v_sub_f32_e32 v58, v58, v170
	v_sub_f32_e32 v59, v59, v170
	v_sub_f32_e32 v60, v60, v170
	v_sub_f32_e32 v61, v61, v170
	v_sub_f32_e32 v62, v62, v170
	v_sub_f32_e32 v63, v63, v170
	s_waitcnt lgkmcnt(3)
	v_mfma_f32_32x32x16_bf16 v[64:79], v[136:139], v[112:115], v[218:233]
	v_exp_f32_e32 v32, v32
	v_exp_f32_e32 v48, v48
	v_exp_f32_e32 v33, v33
	v_exp_f32_e32 v49, v49
	v_exp_f32_e32 v34, v34
	v_exp_f32_e32 v50, v50
	v_cvt_pk_bf16_f32 v96, v32, v33
	ds_read_b128 v[136:139], v243 offset:9280
	s_mov_b32 s55, s52
	s_mov_b32 s52, s53
	s_mov_b32 s53, s54
	s_mov_b32 s54, s55
	s_mov_b32 s9, 0
	s_waitcnt lgkmcnt(3)
	v_mfma_f32_32x32x16_bf16 v[80:95], v[140:143], v[112:115], v[218:233]
	v_cvt_pk_bf16_f32 v104, v48, v49
	v_exp_f32_e32 v35, v35
	v_exp_f32_e32 v51, v51
	v_exp_f32_e32 v36, v36
	v_exp_f32_e32 v52, v52
	v_cvt_pk_bf16_f32 v97, v34, v35
	v_cvt_pk_bf16_f32 v105, v50, v51
	v_exp_f32_e32 v37, v37
	ds_read_b128 v[140:143], v243 offset:13888
	global_load_dwordx4 v[208:211], v167, s[2:3]
	global_load_dwordx4 v[212:215], v167, s[4:5]
	s_add_u32 s2, s2, 0x2000
	s_addc_u32 s3, s3, 0
	s_add_u32 s4, s4, 0x2000
	s_addc_u32 s5, s5, 0
	v_add_u32_e32 v163, s53, v240
	v_add_u32_e32 v164, s54, v241
	s_waitcnt lgkmcnt(3)
	v_mfma_f32_32x32x16_bf16 v[64:79], v[144:147], v[116:119], v[64:79]
	v_exp_f32_e32 v53, v53
	v_exp_f32_e32 v38, v38
	v_exp_f32_e32 v54, v54
	v_cvt_pk_bf16_f32 v98, v36, v37
	v_cvt_pk_bf16_f32 v106, v52, v53
	v_exp_f32_e32 v39, v39
	v_exp_f32_e32 v55, v55
	v_exp_f32_e32 v40, v40
	ds_read_b128 v[144:147], v243 offset:9312
	ds_read_b64_tr_b16 v[176:177], v163 offset:0
	ds_read_b64_tr_b16 v[178:179], v163 offset:1536
	s_waitcnt lgkmcnt(5)
	v_mfma_f32_32x32x16_bf16 v[80:95], v[148:151], v[116:119], v[80:95]
	v_exp_f32_e32 v56, v56
	v_cvt_pk_bf16_f32 v99, v38, v39
	v_cvt_pk_bf16_f32 v107, v54, v55
	v_exp_f32_e32 v41, v41
	v_exp_f32_e32 v57, v57
	v_exp_f32_e32 v42, v42
	v_exp_f32_e32 v58, v58
	ds_read_b128 v[148:151], v243 offset:13920
	ds_read_b64_tr_b16 v[180:181], v163 offset:64
	ds_read_b64_tr_b16 v[182:183], v163 offset:1600
	s_waitcnt lgkmcnt(7)
	v_mfma_f32_32x32x16_bf16 v[64:79], v[136:139], v[120:123], v[64:79]
	v_cvt_pk_bf16_f32 v100, v40, v41
	v_cvt_pk_bf16_f32 v108, v56, v57
	v_exp_f32_e32 v43, v43
	v_exp_f32_e32 v59, v59
	v_exp_f32_e32 v44, v44
	v_exp_f32_e32 v60, v60
	v_cvt_pk_bf16_f32 v101, v42, v43
	v_cvt_pk_bf16_f32 v109, v58, v59
	ds_read_b64_tr_b16 v[184:185], v163 offset:6144
	ds_read_b64_tr_b16 v[186:187], v163 offset:7680
	s_waitcnt vmcnt(3)
	ds_write_b128 v238, v[152:155]
	s_waitcnt vmcnt(2)
	ds_write_b128 v164, v[156:159]
	s_waitcnt lgkmcnt(10)
	v_mfma_f32_32x32x16_bf16 v[80:95], v[140:143], v[120:123], v[80:95]
	v_exp_f32_e32 v45, v45
	v_exp_f32_e32 v61, v61
	v_exp_f32_e32 v46, v46
	v_exp_f32_e32 v62, v62
	v_cvt_pk_bf16_f32 v102, v44, v45
	v_cvt_pk_bf16_f32 v110, v60, v61
	v_exp_f32_e32 v47, v47
	v_exp_f32_e32 v63, v63
	ds_read_b64_tr_b16 v[188:189], v163 offset:6208
	ds_read_b64_tr_b16 v[190:191], v163 offset:7744
	s_waitcnt lgkmcnt(11)
	v_mfma_f32_32x32x16_bf16 v[64:79], v[144:147], v[124:127], v[64:79]
	v_cvt_pk_bf16_f32 v103, v46, v47
	v_cvt_pk_bf16_f32 v111, v62, v63
	s_waitcnt lgkmcnt(8)
	v_mfma_f32_32x32x16_bf16 v[80:95], v[148:151], v[124:127], v[80:95]
	s_nop 13
	s_waitcnt lgkmcnt(2)
	s_waitcnt lgkmcnt(0)
	s_barrier
	s_cmp_eq_u32 s7, 0
	s_cbranch_scc1 .Lagqa_tail
.Lagqa_loop:
	ds_read_b128 v[136:139], v243 offset:0
	ds_read_b128 v[140:143], v243 offset:4608
	ds_read_b128 v[144:147], v243 offset:32
	ds_read_b128 v[148:151], v243 offset:4640
	s_waitcnt lgkmcnt(10)
	v_mfma_f32_32x32x16_bf16 v[0:15], v[176:179], v[96:99], v[0:15]
	v_max3_f32 v168, v64, v65, v66
	v_max3_f32 v170, v80, v81, v82
	v_max3_f32 v168, v168, v67, v68
	v_max3_f32 v170, v170, v83, v84
	v_max3_f32 v168, v168, v69, v70
	v_max3_f32 v170, v170, v85, v86
	s_mov_b32 s55, s52
	s_mov_b32 s52, s53
	s_mov_b32 s53, s54
	s_mov_b32 s54, s55
	s_mov_b32 s9, 0
	s_waitcnt lgkmcnt(8)
	v_mfma_f32_32x32x16_bf16 v[16:31], v[180:183], v[96:99], v[16:31]
	v_max3_f32 v168, v168, v71, v72
	v_max3_f32 v170, v170, v87, v88
	v_max3_f32 v168, v168, v73, v74
	v_max3_f32 v170, v170, v89, v90
	v_max3_f32 v168, v168, v75, v76
	global_load_dwordx4 v[152:155], v167, s[2:3]
	global_load_dwordx4 v[156:159], v167, s[4:5]
	s_add_u32 s2, s2, 0x2000
	s_addc_u32 s3, s3, 0
	s_add_u32 s4, s4, 0x2000
	s_addc_u32 s5, s5, 0
	v_add_u32_e32 v162, s53, v240
	v_add_u32_e32 v164, s54, v241
	v_mfma_f32_16x16x32_bf16 v[234:237], v[246:249], v[96:99], v[234:237]
	v_max3_f32 v170, v170, v91, v92
	v_max3_f32 v168, v168, v77, v78
	v_max3_f32 v170, v170, v93, v94
	v_max_f32_e32 v168, v168, v79
	v_max_f32_e32 v170, v170, v95
	v_max_f32_e32 v168, v168, v170
	v_mov_b32_e32 v170, v168
	s_nop 1
	v_permlane32_swap_b32_e32 v168, v170
	v_max_f32_e32 v168, v168, v170
	v_cmp_lt_f32_e32 vcc, 0x41000000, v168
	s_cbranch_vccz .Lagqa_nors_2
	v_max_f32_e32 v170, 0, v168
	v_exp_f32_e64 v166, -v170
	v_sub_f32_e32 v218, v218, v170
	v_sub_f32_e32 v219, v219, v170
	v_sub_f32_e32 v220, v220, v170
	v_sub_f32_e32 v221, v221, v170
	v_sub_f32_e32 v222, v222, v170
	v_sub_f32_e32 v223, v223, v170
	v_sub_f32_e32 v224, v224, v170
	v_sub_f32_e32 v225, v225, v170
	v_sub_f32_e32 v226, v226, v170
	v_sub_f32_e32 v227, v227, v170
	v_sub_f32_e32 v228, v228, v170
	v_sub_f32_e32 v229, v229, v170
	v_sub_f32_e32 v230, v230, v170
	v_sub_f32_e32 v231, v231, v170
	v_sub_f32_e32 v232, v232, v170
	v_sub_f32_e32 v233, v233, v170
	v_sub_f32_e32 v64, v64, v170
	v_sub_f32_e32 v65, v65, v170
	v_sub_f32_e32 v66, v66, v170
	v_sub_f32_e32 v67, v67, v170
	v_sub_f32_e32 v68, v68, v170
	v_sub_f32_e32 v69, v69, v170
	v_sub_f32_e32 v70, v70, v170
	v_sub_f32_e32 v71, v71, v170
	v_sub_f32_e32 v72, v72, v170
	v_sub_f32_e32 v73, v73, v170
	v_sub_f32_e32 v74, v74, v170
	v_sub_f32_e32 v75, v75, v170
	v_sub_f32_e32 v76, v76, v170
	v_sub_f32_e32 v77, v77, v170
	v_sub_f32_e32 v78, v78, v170
	v_sub_f32_e32 v79, v79, v170
	v_sub_f32_e32 v80, v80, v170
	v_sub_f32_e32 v81, v81, v170
	v_sub_f32_e32 v82, v82, v170
	v_sub_f32_e32 v83, v83, v170
	v_sub_f32_e32 v84, v84, v170
	v_sub_f32_e32 v85, v85, v170
	v_sub_f32_e32 v86, v86, v170
	v_sub_f32_e32 v87, v87, v170
	v_sub_f32_e32 v88, v88, v170
	v_sub_f32_e32 v89, v89, v170
	v_sub_f32_e32 v90, v90, v170
	v_sub_f32_e32 v91, v91, v170
	v_sub_f32_e32 v92, v92, v170
	v_sub_f32_e32 v93, v93, v170
	v_sub_f32_e32 v94, v94, v170
	v_sub_f32_e32 v95, v95, v170
	s_mov_b32 s9, 1
.Lagqa_nors_2:
	s_waitcnt lgkmcnt(3)
	v_mfma_f32_32x32x16_bf16 v[32:47], v[136:139], v[112:115], v[218:233]
	v_exp_f32_e32 v64, v64
	v_exp_f32_e32 v80, v80
	v_exp_f32_e32 v65, v65
	ds_read_b128 v[136:139], v243 offset:64
	ds_read_b64_tr_b16 v[192:193], v163 offset:3072
	ds_read_b64_tr_b16 v[194:195], v163 offset:4608
	v_mfma_f32_32x32x16_bf16 v[0:15], v[184:187], v[104:107], v[0:15]
	v_exp_f32_e32 v81, v81
	v_exp_f32_e32 v66, v66
	ds_read_b64_tr_b16 v[196:197], v163 offset:3136
	ds_read_b64_tr_b16 v[198:199], v163 offset:4672
	s_waitcnt lgkmcnt(7)
	v_mfma_f32_32x32x16_bf16 v[48:63], v[140:143], v[112:115], v[218:233]
	v_exp_f32_e32 v82, v82
	v_cvt_pk_bf16_f32 v96, v64, v65
	v_exp_f32_e32 v67, v67
	ds_read_b128 v[140:143], v243 offset:4672
	ds_read_b64_tr_b16 v[200:201], v163 offset:9216
	ds_read_b64_tr_b16 v[202:203], v163 offset:10752
	v_mfma_f32_32x32x16_bf16 v[16:31], v[188:191], v[104:107], v[16:31]
	v_exp_f32_e32 v83, v83
	v_exp_f32_e32 v68, v68
	v_exp_f32_e32 v84, v84
	ds_read_b64_tr_b16 v[204:205], v163 offset:9280
	ds_read_b64_tr_b16 v[206:207], v163 offset:10816
	s_waitcnt lgkmcnt(11)
	v_mfma_f32_32x32x16_bf16 v[32:47], v[144:147], v[116:119], v[32:47]
	v_cvt_pk_bf16_f32 v97, v66, v67
	v_exp_f32_e32 v69, v69
	v_exp_f32_e32 v85, v85
	ds_read_b128 v[144:147], v243 offset:96
	v_mfma_f32_16x16x32_bf16 v[234:237], v[246:249], v[104:107], v[234:237]
	v_cvt_pk_bf16_f32 v104, v80, v81
	v_cvt_pk_bf16_f32 v105, v82, v83
	v_exp_f32_e32 v70, v70
	v_exp_f32_e32 v86, v86
	s_waitcnt lgkmcnt(11)
	v_mfma_f32_32x32x16_bf16 v[48:63], v[148:151], v[116:119], v[48:63]
	v_cvt_pk_bf16_f32 v98, v68, v69
	v_cvt_pk_bf16_f32 v106, v84, v85
	v_exp_f32_e32 v71, v71
	v_exp_f32_e32 v87, v87
	ds_read_b128 v[148:151], v243 offset:4704
	s_waitcnt lgkmcnt(9)
	v_mfma_f32_32x32x16_bf16 v[0:15], v[192:195], v[100:103], v[0:15]
	v_exp_f32_e32 v72, v72
	v_exp_f32_e32 v88, v88
	v_cvt_pk_bf16_f32 v99, v70, v71
	v_mfma_f32_32x32x16_bf16 v[32:47], v[136:139], v[120:123], v[32:47]
	v_cvt_pk_bf16_f32 v107, v86, v87
	v_exp_f32_e32 v73, v73
	v_exp_f32_e32 v89, v89
	s_waitcnt vmcnt(3)
	ds_write_b128 v238, v[208:211] offset:9216
	s_waitcnt vmcnt(2)
	ds_write_b128 v164, v[212:215]
	s_waitcnt lgkmcnt(9)
	v_mfma_f32_32x32x16_bf16 v[16:31], v[196:199], v[100:103], v[16:31]
	v_exp_f32_e32 v74, v74
	v_exp_f32_e32 v90, v90
	v_exp_f32_e32 v75, v75
	s_waitcnt lgkmcnt(8)
	v_mfma_f32_32x32x16_bf16 v[48:63], v[140:143], v[120:123], v[48:63]
	v_exp_f32_e32 v91, v91
	v_exp_f32_e32 v76, v76
	v_mfma_f32_16x16x32_bf16 v[234:237], v[246:249], v[100:103], v[234:237]
	v_cvt_pk_bf16_f32 v100, v72, v73
	v_exp_f32_e32 v92, v92
	v_cvt_pk_bf16_f32 v101, v74, v75
	v_exp_f32_e32 v77, v77
	ds_read_b64_tr_b16 v[176:177], v162 offset:0
	ds_read_b64_tr_b16 v[178:179], v162 offset:1536
	s_waitcnt lgkmcnt(5)
	v_mfma_f32_32x32x16_bf16 v[32:47], v[144:147], v[124:127], v[32:47]
	v_exp_f32_e32 v93, v93
	v_exp_f32_e32 v78, v78
	v_exp_f32_e32 v94, v94
	ds_read_b64_tr_b16 v[180:181], v162 offset:64
	ds_read_b64_tr_b16 v[182:183], v162 offset:1600
	v_mfma_f32_32x32x16_bf16 v[0:15], v[200:203], v[108:111], v[0:15]
	v_cvt_pk_bf16_f32 v102, v76, v77
	v_exp_f32_e32 v79, v79
	v_exp_f32_e32 v95, v95
	ds_read_b64_tr_b16 v[184:185], v162 offset:6144
	ds_read_b64_tr_b16 v[186:187], v162 offset:7680
	s_waitcnt lgkmcnt(8)
	v_mfma_f32_32x32x16_bf16 v[48:63], v[148:151], v[124:127], v[48:63]
	v_cvt_pk_bf16_f32 v103, v78, v79
	ds_read_b64_tr_b16 v[188:189], v162 offset:6208
	ds_read_b64_tr_b16 v[190:191], v162 offset:7744
	v_mfma_f32_32x32x16_bf16 v[16:31], v[204:207], v[108:111], v[16:31]
	v_mfma_f32_16x16x32_bf16 v[234:237], v[246:249], v[108:111], v[234:237]
	v_cvt_pk_bf16_f32 v108, v88, v89
	v_cvt_pk_bf16_f32 v109, v90, v91
	v_cvt_pk_bf16_f32 v110, v92, v93
	v_cvt_pk_bf16_f32 v111, v94, v95
	s_cmp_lg_u32 s9, 0
	s_cbranch_scc0 .Lagqa_noresc_3
	s_nop 15
	v_mul_f32_e32 v0, v0, v166
	v_mul_f32_e32 v1, v1, v166
	v_mul_f32_e32 v2, v2, v166
	v_mul_f32_e32 v3, v3, v166
	v_mul_f32_e32 v4, v4, v166
	v_mul_f32_e32 v5, v5, v166
	v_mul_f32_e32 v6, v6, v166
	v_mul_f32_e32 v7, v7, v166
	v_mul_f32_e32 v8, v8, v166
	v_mul_f32_e32 v9, v9, v166
	v_mul_f32_e32 v10, v10, v166
	v_mul_f32_e32 v11, v11, v166
	v_mul_f32_e32 v12, v12, v166
	v_mul_f32_e32 v13, v13, v166
	v_mul_f32_e32 v14, v14, v166
	v_mul_f32_e32 v15, v15, v166
	v_mul_f32_e32 v16, v16, v166
	v_mul_f32_e32 v17, v17, v166
	v_mul_f32_e32 v18, v18, v166
	v_mul_f32_e32 v19, v19, v166
	v_mul_f32_e32 v20, v20, v166
	v_mul_f32_e32 v21, v21, v166
	v_mul_f32_e32 v22, v22, v166
	v_mul_f32_e32 v23, v23, v166
	v_mul_f32_e32 v24, v24, v166
	v_mul_f32_e32 v25, v25, v166
	v_mul_f32_e32 v26, v26, v166
	v_mul_f32_e32 v27, v27, v166
	v_mul_f32_e32 v28, v28, v166
	v_mul_f32_e32 v29, v29, v166
	v_mul_f32_e32 v30, v30, v166
	v_mul_f32_e32 v31, v31, v166
	v_add_u32_e32 v170, 64, v175
	ds_bpermute_b32 v173, v170, v166
	v_mul_f32_e32 v234, v234, v166
	s_waitcnt lgkmcnt(0)
	v_mul_f32_e32 v235, v235, v173
.Lagqa_noresc_3:
	s_nop 2
	s_waitcnt lgkmcnt(8)
	s_barrier
	ds_read_b128 v[136:139], v243 offset:9216
	ds_read_b128 v[140:143], v243 offset:13824
	ds_read_b128 v[144:147], v243 offset:9248
	ds_read_b128 v[148:151], v243 offset:13856
	s_waitcnt lgkmcnt(10)
	v_mfma_f32_32x32x16_bf16 v[0:15], v[176:179], v[96:99], v[0:15]
	v_max3_f32 v168, v32, v33, v34
	v_max3_f32 v170, v48, v49, v50
	v_max3_f32 v168, v168, v35, v36
	v_max3_f32 v170, v170, v51, v52
	v_max3_f32 v168, v168, v37, v38
	v_max3_f32 v170, v170, v53, v54
	s_mov_b32 s55, s52
	s_mov_b32 s52, s53
	s_mov_b32 s53, s54
	s_mov_b32 s54, s55
	s_mov_b32 s9, 0
	s_waitcnt lgkmcnt(8)
	v_mfma_f32_32x32x16_bf16 v[16:31], v[180:183], v[96:99], v[16:31]
	v_max3_f32 v168, v168, v39, v40
	v_max3_f32 v170, v170, v55, v56
	v_max3_f32 v168, v168, v41, v42
	v_max3_f32 v170, v170, v57, v58
	v_max3_f32 v168, v168, v43, v44
	global_load_dwordx4 v[208:211], v167, s[2:3]
	global_load_dwordx4 v[212:215], v167, s[4:5]
	s_add_u32 s2, s2, 0x2000
	s_addc_u32 s3, s3, 0
	s_add_u32 s4, s4, 0x2000
	s_addc_u32 s5, s5, 0
	v_add_u32_e32 v163, s53, v240
	v_add_u32_e32 v164, s54, v241
	v_mfma_f32_16x16x32_bf16 v[234:237], v[246:249], v[96:99], v[234:237]
	v_max3_f32 v170, v170, v59, v60
	v_max3_f32 v168, v168, v45, v46
	v_max3_f32 v170, v170, v61, v62
	v_max_f32_e32 v168, v168, v47
	v_max_f32_e32 v170, v170, v63
	v_max_f32_e32 v168, v168, v170
	v_mov_b32_e32 v170, v168
	s_nop 1
	v_permlane32_swap_b32_e32 v168, v170
	v_max_f32_e32 v168, v168, v170
	v_cmp_lt_f32_e32 vcc, 0x41000000, v168
	s_cbranch_vccz .Lagqa_nors_4
	v_max_f32_e32 v170, 0, v168
	v_exp_f32_e64 v166, -v170
	v_sub_f32_e32 v218, v218, v170
	v_sub_f32_e32 v219, v219, v170
	v_sub_f32_e32 v220, v220, v170
	v_sub_f32_e32 v221, v221, v170
	v_sub_f32_e32 v222, v222, v170
	v_sub_f32_e32 v223, v223, v170
	v_sub_f32_e32 v224, v224, v170
	v_sub_f32_e32 v225, v225, v170
	v_sub_f32_e32 v226, v226, v170
	v_sub_f32_e32 v227, v227, v170
	v_sub_f32_e32 v228, v228, v170
	v_sub_f32_e32 v229, v229, v170
	v_sub_f32_e32 v230, v230, v170
	v_sub_f32_e32 v231, v231, v170
	v_sub_f32_e32 v232, v232, v170
	v_sub_f32_e32 v233, v233, v170
	v_sub_f32_e32 v32, v32, v170
	v_sub_f32_e32 v33, v33, v170
	v_sub_f32_e32 v34, v34, v170
	v_sub_f32_e32 v35, v35, v170
	v_sub_f32_e32 v36, v36, v170
	v_sub_f32_e32 v37, v37, v170
	v_sub_f32_e32 v38, v38, v170
	v_sub_f32_e32 v39, v39, v170
	v_sub_f32_e32 v40, v40, v170
	v_sub_f32_e32 v41, v41, v170
	v_sub_f32_e32 v42, v42, v170
	v_sub_f32_e32 v43, v43, v170
	v_sub_f32_e32 v44, v44, v170
	v_sub_f32_e32 v45, v45, v170
	v_sub_f32_e32 v46, v46, v170
	v_sub_f32_e32 v47, v47, v170
	v_sub_f32_e32 v48, v48, v170
	v_sub_f32_e32 v49, v49, v170
	v_sub_f32_e32 v50, v50, v170
	v_sub_f32_e32 v51, v51, v170
	v_sub_f32_e32 v52, v52, v170
	v_sub_f32_e32 v53, v53, v170
	v_sub_f32_e32 v54, v54, v170
	v_sub_f32_e32 v55, v55, v170
	v_sub_f32_e32 v56, v56, v170
	v_sub_f32_e32 v57, v57, v170
	v_sub_f32_e32 v58, v58, v170
	v_sub_f32_e32 v59, v59, v170
	v_sub_f32_e32 v60, v60, v170
	v_sub_f32_e32 v61, v61, v170
	v_sub_f32_e32 v62, v62, v170
	v_sub_f32_e32 v63, v63, v170
	s_mov_b32 s9, 1
.Lagqa_nors_4:
	s_waitcnt lgkmcnt(3)
	v_mfma_f32_32x32x16_bf16 v[64:79], v[136:139], v[112:115], v[218:233]
	v_exp_f32_e32 v32, v32
	v_exp_f32_e32 v48, v48
	v_exp_f32_e32 v33, v33
	ds_read_b128 v[136:139], v243 offset:9280
	ds_read_b64_tr_b16 v[192:193], v162 offset:3072
	ds_read_b64_tr_b16 v[194:195], v162 offset:4608
	v_mfma_f32_32x32x16_bf16 v[0:15], v[184:187], v[104:107], v[0:15]
	v_exp_f32_e32 v49, v49
	v_exp_f32_e32 v34, v34
	ds_read_b64_tr_b16 v[196:197], v162 offset:3136
	ds_read_b64_tr_b16 v[198:199], v162 offset:4672
	s_waitcnt lgkmcnt(7)
	v_mfma_f32_32x32x16_bf16 v[80:95], v[140:143], v[112:115], v[218:233]
	v_exp_f32_e32 v50, v50
	v_cvt_pk_bf16_f32 v96, v32, v33
	v_exp_f32_e32 v35, v35
	ds_read_b128 v[140:143], v243 offset:13888
	ds_read_b64_tr_b16 v[200:201], v162 offset:9216
	ds_read_b64_tr_b16 v[202:203], v162 offset:10752
	v_mfma_f32_32x32x16_bf16 v[16:31], v[188:191], v[104:107], v[16:31]
	v_exp_f32_e32 v51, v51
	v_exp_f32_e32 v36, v36
	v_exp_f32_e32 v52, v52
	ds_read_b64_tr_b16 v[204:205], v162 offset:9280
	ds_read_b64_tr_b16 v[206:207], v162 offset:10816
	s_waitcnt lgkmcnt(11)
	v_mfma_f32_32x32x16_bf16 v[64:79], v[144:147], v[116:119], v[64:79]
	v_cvt_pk_bf16_f32 v97, v34, v35
	v_exp_f32_e32 v37, v37
	v_exp_f32_e32 v53, v53
	ds_read_b128 v[144:147], v243 offset:9312
	v_mfma_f32_16x16x32_bf16 v[234:237], v[246:249], v[104:107], v[234:237]
	v_cvt_pk_bf16_f32 v104, v48, v49
	v_cvt_pk_bf16_f32 v105, v50, v51
	v_exp_f32_e32 v38, v38
	v_exp_f32_e32 v54, v54
	s_waitcnt lgkmcnt(11)
	v_mfma_f32_32x32x16_bf16 v[80:95], v[148:151], v[116:119], v[80:95]
	v_cvt_pk_bf16_f32 v98, v36, v37
	v_cvt_pk_bf16_f32 v106, v52, v53
	v_exp_f32_e32 v39, v39
	v_exp_f32_e32 v55, v55
	ds_read_b128 v[148:151], v243 offset:13920
	s_waitcnt lgkmcnt(9)
	v_mfma_f32_32x32x16_bf16 v[0:15], v[192:195], v[100:103], v[0:15]
	v_exp_f32_e32 v40, v40
	v_exp_f32_e32 v56, v56
	v_cvt_pk_bf16_f32 v99, v38, v39
	v_mfma_f32_32x32x16_bf16 v[64:79], v[136:139], v[120:123], v[64:79]
	v_cvt_pk_bf16_f32 v107, v54, v55
	v_exp_f32_e32 v41, v41
	v_exp_f32_e32 v57, v57
	s_waitcnt vmcnt(3)
	ds_write_b128 v238, v[152:155]
	s_waitcnt vmcnt(2)
	ds_write_b128 v164, v[156:159]
	s_waitcnt lgkmcnt(9)
	v_mfma_f32_32x32x16_bf16 v[16:31], v[196:199], v[100:103], v[16:31]
	v_exp_f32_e32 v42, v42
	v_exp_f32_e32 v58, v58
	v_exp_f32_e32 v43, v43
	s_waitcnt lgkmcnt(8)
	v_mfma_f32_32x32x16_bf16 v[80:95], v[140:143], v[120:123], v[80:95]
	v_exp_f32_e32 v59, v59
	v_exp_f32_e32 v44, v44
	v_mfma_f32_16x16x32_bf16 v[234:237], v[246:249], v[100:103], v[234:237]
	v_cvt_pk_bf16_f32 v100, v40, v41
	v_exp_f32_e32 v60, v60
	v_cvt_pk_bf16_f32 v101, v42, v43
	v_exp_f32_e32 v45, v45
	ds_read_b64_tr_b16 v[176:177], v163 offset:0
	ds_read_b64_tr_b16 v[178:179], v163 offset:1536
	s_waitcnt lgkmcnt(5)
	v_mfma_f32_32x32x16_bf16 v[64:79], v[144:147], v[124:127], v[64:79]
	v_exp_f32_e32 v61, v61
	v_exp_f32_e32 v46, v46
	v_exp_f32_e32 v62, v62
	ds_read_b64_tr_b16 v[180:181], v163 offset:64
	ds_read_b64_tr_b16 v[182:183], v163 offset:1600
	v_mfma_f32_32x32x16_bf16 v[0:15], v[200:203], v[108:111], v[0:15]
	v_cvt_pk_bf16_f32 v102, v44, v45
	v_exp_f32_e32 v47, v47
	v_exp_f32_e32 v63, v63
	ds_read_b64_tr_b16 v[184:185], v163 offset:6144
	ds_read_b64_tr_b16 v[186:187], v163 offset:7680
	s_waitcnt lgkmcnt(8)
	v_mfma_f32_32x32x16_bf16 v[80:95], v[148:151], v[124:127], v[80:95]
	v_cvt_pk_bf16_f32 v103, v46, v47
	ds_read_b64_tr_b16 v[188:189], v163 offset:6208
	ds_read_b64_tr_b16 v[190:191], v163 offset:7744
	v_mfma_f32_32x32x16_bf16 v[16:31], v[204:207], v[108:111], v[16:31]
	v_mfma_f32_16x16x32_bf16 v[234:237], v[246:249], v[108:111], v[234:237]
	v_cvt_pk_bf16_f32 v108, v56, v57
	v_cvt_pk_bf16_f32 v109, v58, v59
	v_cvt_pk_bf16_f32 v110, v60, v61
	v_cvt_pk_bf16_f32 v111, v62, v63
	s_cmp_lg_u32 s9, 0
	s_cbranch_scc0 .Lagqa_noresc_5
	s_nop 15
	v_mul_f32_e32 v0, v0, v166
	v_mul_f32_e32 v1, v1, v166
	v_mul_f32_e32 v2, v2, v166
	v_mul_f32_e32 v3, v3, v166
	v_mul_f32_e32 v4, v4, v166
	v_mul_f32_e32 v5, v5, v166
	v_mul_f32_e32 v6, v6, v166
	v_mul_f32_e32 v7, v7, v166
	v_mul_f32_e32 v8, v8, v166
	v_mul_f32_e32 v9, v9, v166
	v_mul_f32_e32 v10, v10, v166
	v_mul_f32_e32 v11, v11, v166
	v_mul_f32_e32 v12, v12, v166
	v_mul_f32_e32 v13, v13, v166
	v_mul_f32_e32 v14, v14, v166
	v_mul_f32_e32 v15, v15, v166
	v_mul_f32_e32 v16, v16, v166
	v_mul_f32_e32 v17, v17, v166
	v_mul_f32_e32 v18, v18, v166
	v_mul_f32_e32 v19, v19, v166
	v_mul_f32_e32 v20, v20, v166
	v_mul_f32_e32 v21, v21, v166
	v_mul_f32_e32 v22, v22, v166
	v_mul_f32_e32 v23, v23, v166
	v_mul_f32_e32 v24, v24, v166
	v_mul_f32_e32 v25, v25, v166
	v_mul_f32_e32 v26, v26, v166
	v_mul_f32_e32 v27, v27, v166
	v_mul_f32_e32 v28, v28, v166
	v_mul_f32_e32 v29, v29, v166
	v_mul_f32_e32 v30, v30, v166
	v_mul_f32_e32 v31, v31, v166
	v_add_u32_e32 v170, 64, v175
	ds_bpermute_b32 v173, v170, v166
	v_mul_f32_e32 v234, v234, v166
	s_waitcnt lgkmcnt(0)
	v_mul_f32_e32 v235, v235, v173
.Lagqa_noresc_5:
	s_nop 2
	s_waitcnt lgkmcnt(8)
	s_barrier
	s_add_i32 s7, s7, -1
	s_cmp_lg_u32 s7, 0
	s_cbranch_scc1 .Lagqa_loop
.Lagqa_tail:
	ds_read_b128 v[136:139], v243 offset:0
	ds_read_b128 v[140:143], v243 offset:4608
	ds_read_b128 v[144:147], v243 offset:32
	ds_read_b128 v[148:151], v243 offset:4640
	s_waitcnt lgkmcnt(10)
	v_mfma_f32_32x32x16_bf16 v[0:15], v[176:179], v[96:99], v[0:15]
	v_max3_f32 v168, v64, v65, v66
	v_max3_f32 v170, v80, v81, v82
	v_max3_f32 v168, v168, v67, v68
	v_max3_f32 v170, v170, v83, v84
	v_max3_f32 v168, v168, v69, v70
	v_max3_f32 v170, v170, v85, v86
	s_mov_b32 s55, s52
	s_mov_b32 s52, s53
	s_mov_b32 s53, s54
	s_mov_b32 s54, s55
	s_mov_b32 s9, 0
	s_waitcnt lgkmcnt(8)
	v_mfma_f32_32x32x16_bf16 v[16:31], v[180:183], v[96:99], v[16:31]
	v_max3_f32 v168, v168, v71, v72
	v_max3_f32 v170, v170, v87, v88
	v_max3_f32 v168, v168, v73, v74
	v_max3_f32 v170, v170, v89, v90
	v_max3_f32 v168, v168, v75, v76
	global_load_dwordx4 v[156:159], v167, s[4:5]
	s_add_u32 s4, s4, 0x2000
	s_addc_u32 s5, s5, 0
	v_add_u32_e32 v162, s53, v240
	v_add_u32_e32 v164, s54, v241
	v_mfma_f32_16x16x32_bf16 v[234:237], v[246:249], v[96:99], v[234:237]
	v_max3_f32 v170, v170, v91, v92
	v_max3_f32 v168, v168, v77, v78
	v_max3_f32 v170, v170, v93, v94
	v_max_f32_e32 v168, v168, v79
	v_max_f32_e32 v170, v170, v95
	v_max_f32_e32 v168, v168, v170
	v_mov_b32_e32 v170, v168
	s_nop 1
	v_permlane32_swap_b32_e32 v168, v170
	v_max_f32_e32 v168, v168, v170
	v_cmp_lt_f32_e32 vcc, 0x41000000, v168
	s_cbranch_vccz .Lagqa_nors_6
	v_max_f32_e32 v170, 0, v168
	v_exp_f32_e64 v166, -v170
	v_sub_f32_e32 v218, v218, v170
	v_sub_f32_e32 v219, v219, v170
	v_sub_f32_e32 v220, v220, v170
	v_sub_f32_e32 v221, v221, v170
	v_sub_f32_e32 v222, v222, v170
	v_sub_f32_e32 v223, v223, v170
	v_sub_f32_e32 v224, v224, v170
	v_sub_f32_e32 v225, v225, v170
	v_sub_f32_e32 v226, v226, v170
	v_sub_f32_e32 v227, v227, v170
	v_sub_f32_e32 v228, v228, v170
	v_sub_f32_e32 v229, v229, v170
	v_sub_f32_e32 v230, v230, v170
	v_sub_f32_e32 v231, v231, v170
	v_sub_f32_e32 v232, v232, v170
	v_sub_f32_e32 v233, v233, v170
	v_sub_f32_e32 v64, v64, v170
	v_sub_f32_e32 v65, v65, v170
	v_sub_f32_e32 v66, v66, v170
	v_sub_f32_e32 v67, v67, v170
	v_sub_f32_e32 v68, v68, v170
	v_sub_f32_e32 v69, v69, v170
	v_sub_f32_e32 v70, v70, v170
	v_sub_f32_e32 v71, v71, v170
	v_sub_f32_e32 v72, v72, v170
	v_sub_f32_e32 v73, v73, v170
	v_sub_f32_e32 v74, v74, v170
	v_sub_f32_e32 v75, v75, v170
	v_sub_f32_e32 v76, v76, v170
	v_sub_f32_e32 v77, v77, v170
	v_sub_f32_e32 v78, v78, v170
	v_sub_f32_e32 v79, v79, v170
	v_sub_f32_e32 v80, v80, v170
	v_sub_f32_e32 v81, v81, v170
	v_sub_f32_e32 v82, v82, v170
	v_sub_f32_e32 v83, v83, v170
	v_sub_f32_e32 v84, v84, v170
	v_sub_f32_e32 v85, v85, v170
	v_sub_f32_e32 v86, v86, v170
	v_sub_f32_e32 v87, v87, v170
	v_sub_f32_e32 v88, v88, v170
	v_sub_f32_e32 v89, v89, v170
	v_sub_f32_e32 v90, v90, v170
	v_sub_f32_e32 v91, v91, v170
	v_sub_f32_e32 v92, v92, v170
	v_sub_f32_e32 v93, v93, v170
	v_sub_f32_e32 v94, v94, v170
	v_sub_f32_e32 v95, v95, v170
	s_mov_b32 s9, 1
.Lagqa_nors_6:
	s_waitcnt lgkmcnt(3)
	v_mfma_f32_32x32x16_bf16 v[32:47], v[136:139], v[112:115], v[218:233]
	v_exp_f32_e32 v64, v64
	v_exp_f32_e32 v80, v80
	v_exp_f32_e32 v65, v65
	ds_read_b128 v[136:139], v243 offset:64
	ds_read_b64_tr_b16 v[192:193], v163 offset:3072
	ds_read_b64_tr_b16 v[194:195], v163 offset:4608
	v_mfma_f32_32x32x16_bf16 v[0:15], v[184:187], v[104:107], v[0:15]
	v_exp_f32_e32 v81, v81
	v_exp_f32_e32 v66, v66
	ds_read_b64_tr_b16 v[196:197], v163 offset:3136
	ds_read_b64_tr_b16 v[198:199], v163 offset:4672
	s_waitcnt lgkmcnt(7)
	v_mfma_f32_32x32x16_bf16 v[48:63], v[140:143], v[112:115], v[218:233]
	v_exp_f32_e32 v82, v82
	v_cvt_pk_bf16_f32 v96, v64, v65
	v_exp_f32_e32 v67, v67
	ds_read_b128 v[140:143], v243 offset:4672
	ds_read_b64_tr_b16 v[200:201], v163 offset:9216
	ds_read_b64_tr_b16 v[202:203], v163 offset:10752
	v_mfma_f32_32x32x16_bf16 v[16:31], v[188:191], v[104:107], v[16:31]
	v_exp_f32_e32 v83, v83
	v_exp_f32_e32 v68, v68
	v_exp_f32_e32 v84, v84
	ds_read_b64_tr_b16 v[204:205], v163 offset:9280
	ds_read_b64_tr_b16 v[206:207], v163 offset:10816
	s_waitcnt lgkmcnt(11)
	v_mfma_f32_32x32x16_bf16 v[32:47], v[144:147], v[116:119], v[32:47]
	v_cvt_pk_bf16_f32 v97, v66, v67
	v_exp_f32_e32 v69, v69
	v_exp_f32_e32 v85, v85
	ds_read_b128 v[144:147], v243 offset:96
	v_mfma_f32_16x16x32_bf16 v[234:237], v[246:249], v[104:107], v[234:237]
	v_cvt_pk_bf16_f32 v104, v80, v81
	v_cvt_pk_bf16_f32 v105, v82, v83
	v_exp_f32_e32 v70, v70
	v_exp_f32_e32 v86, v86
	s_waitcnt lgkmcnt(11)
	v_mfma_f32_32x32x16_bf16 v[48:63], v[148:151], v[116:119], v[48:63]
	v_cvt_pk_bf16_f32 v98, v68, v69
	v_cvt_pk_bf16_f32 v106, v84, v85
	v_exp_f32_e32 v71, v71
	v_exp_f32_e32 v87, v87
	ds_read_b128 v[148:151], v243 offset:4704
	s_waitcnt lgkmcnt(9)
	v_mfma_f32_32x32x16_bf16 v[0:15], v[192:195], v[100:103], v[0:15]
	v_exp_f32_e32 v72, v72
	v_exp_f32_e32 v88, v88
	v_cvt_pk_bf16_f32 v99, v70, v71
	v_mfma_f32_32x32x16_bf16 v[32:47], v[136:139], v[120:123], v[32:47]
	v_cvt_pk_bf16_f32 v107, v86, v87
	v_exp_f32_e32 v73, v73
	v_exp_f32_e32 v89, v89
	s_waitcnt vmcnt(2)
	ds_write_b128 v238, v[208:211] offset:9216
	s_waitcnt vmcnt(1)
	ds_write_b128 v164, v[212:215]
	s_waitcnt lgkmcnt(9)
	v_mfma_f32_32x32x16_bf16 v[16:31], v[196:199], v[100:103], v[16:31]
	v_exp_f32_e32 v74, v74
	v_exp_f32_e32 v90, v90
	v_exp_f32_e32 v75, v75
	s_waitcnt lgkmcnt(8)
	v_mfma_f32_32x32x16_bf16 v[48:63], v[140:143], v[120:123], v[48:63]
	v_exp_f32_e32 v91, v91
	v_exp_f32_e32 v76, v76
	v_mfma_f32_16x16x32_bf16 v[234:237], v[246:249], v[100:103], v[234:237]
	v_cvt_pk_bf16_f32 v100, v72, v73
	v_exp_f32_e32 v92, v92
	v_cvt_pk_bf16_f32 v101, v74, v75
	v_exp_f32_e32 v77, v77
	ds_read_b64_tr_b16 v[176:177], v162 offset:0
	ds_read_b64_tr_b16 v[178:179], v162 offset:1536
	s_waitcnt lgkmcnt(5)
	v_mfma_f32_32x32x16_bf16 v[32:47], v[144:147], v[124:127], v[32:47]
	v_exp_f32_e32 v93, v93
	v_exp_f32_e32 v78, v78
	v_exp_f32_e32 v94, v94
	ds_read_b64_tr_b16 v[180:181], v162 offset:64
	ds_read_b64_tr_b16 v[182:183], v162 offset:1600
	v_mfma_f32_32x32x16_bf16 v[0:15], v[200:203], v[108:111], v[0:15]
	v_cvt_pk_bf16_f32 v102, v76, v77
	v_exp_f32_e32 v79, v79
	v_exp_f32_e32 v95, v95
	ds_read_b64_tr_b16 v[184:185], v162 offset:6144
	ds_read_b64_tr_b16 v[186:187], v162 offset:7680
	s_waitcnt lgkmcnt(8)
	v_mfma_f32_32x32x16_bf16 v[48:63], v[148:151], v[124:127], v[48:63]
	v_cvt_pk_bf16_f32 v103, v78, v79
	ds_read_b64_tr_b16 v[188:189], v162 offset:6208
	ds_read_b64_tr_b16 v[190:191], v162 offset:7744
	v_mfma_f32_32x32x16_bf16 v[16:31], v[204:207], v[108:111], v[16:31]
	v_mfma_f32_16x16x32_bf16 v[234:237], v[246:249], v[108:111], v[234:237]
	v_cvt_pk_bf16_f32 v108, v88, v89
	v_cvt_pk_bf16_f32 v109, v90, v91
	v_cvt_pk_bf16_f32 v110, v92, v93
	v_cvt_pk_bf16_f32 v111, v94, v95
	s_cmp_lg_u32 s9, 0
	s_cbranch_scc0 .Lagqa_noresc_7
	s_nop 15
	v_mul_f32_e32 v0, v0, v166
	v_mul_f32_e32 v1, v1, v166
	v_mul_f32_e32 v2, v2, v166
	v_mul_f32_e32 v3, v3, v166
	v_mul_f32_e32 v4, v4, v166
	v_mul_f32_e32 v5, v5, v166
	v_mul_f32_e32 v6, v6, v166
	v_mul_f32_e32 v7, v7, v166
	v_mul_f32_e32 v8, v8, v166
	v_mul_f32_e32 v9, v9, v166
	v_mul_f32_e32 v10, v10, v166
	v_mul_f32_e32 v11, v11, v166
	v_mul_f32_e32 v12, v12, v166
	v_mul_f32_e32 v13, v13, v166
	v_mul_f32_e32 v14, v14, v166
	v_mul_f32_e32 v15, v15, v166
	v_mul_f32_e32 v16, v16, v166
	v_mul_f32_e32 v17, v17, v166
	v_mul_f32_e32 v18, v18, v166
	v_mul_f32_e32 v19, v19, v166
	v_mul_f32_e32 v20, v20, v166
	v_mul_f32_e32 v21, v21, v166
	v_mul_f32_e32 v22, v22, v166
	v_mul_f32_e32 v23, v23, v166
	v_mul_f32_e32 v24, v24, v166
	v_mul_f32_e32 v25, v25, v166
	v_mul_f32_e32 v26, v26, v166
	v_mul_f32_e32 v27, v27, v166
	v_mul_f32_e32 v28, v28, v166
	v_mul_f32_e32 v29, v29, v166
	v_mul_f32_e32 v30, v30, v166
	v_mul_f32_e32 v31, v31, v166
	v_add_u32_e32 v170, 64, v175
	ds_bpermute_b32 v173, v170, v166
	v_mul_f32_e32 v234, v234, v166
	s_waitcnt lgkmcnt(0)
	v_mul_f32_e32 v235, v235, v173
.Lagqa_noresc_7:
	s_nop 2
	s_waitcnt lgkmcnt(8)
	s_barrier
	ds_read_b128 v[136:139], v243 offset:9216
	ds_read_b128 v[140:143], v243 offset:13824
	ds_read_b128 v[144:147], v243 offset:9248
	ds_read_b128 v[148:151], v243 offset:13856
	s_waitcnt lgkmcnt(10)
	v_mfma_f32_32x32x16_bf16 v[0:15], v[176:179], v[96:99], v[0:15]
	v_max3_f32 v168, v32, v33, v34
	v_max3_f32 v170, v48, v49, v50
	v_max3_f32 v168, v168, v35, v36
	v_max3_f32 v170, v170, v51, v52
	v_max3_f32 v168, v168, v37, v38
	v_max3_f32 v170, v170, v53, v54
	s_mov_b32 s55, s52
	s_mov_b32 s52, s53
	s_mov_b32 s53, s54
	s_mov_b32 s54, s55
	s_mov_b32 s9, 0
	s_waitcnt lgkmcnt(8)
	v_mfma_f32_32x32x16_bf16 v[16:31], v[180:183], v[96:99], v[16:31]
	v_max3_f32 v168, v168, v39, v40
	v_max3_f32 v170, v170, v55, v56
	v_max3_f32 v168, v168, v41, v42
	v_max3_f32 v170, v170, v57, v58
	v_max3_f32 v168, v168, v43, v44
	v_add_u32_e32 v163, s53, v240
	v_add_u32_e32 v164, s54, v241
	v_mfma_f32_16x16x32_bf16 v[234:237], v[246:249], v[96:99], v[234:237]
	v_max3_f32 v170, v170, v59, v60
	v_max3_f32 v168, v168, v45, v46
	v_max3_f32 v170, v170, v61, v62
	v_max_f32_e32 v168, v168, v47
	v_max_f32_e32 v170, v170, v63
	v_max_f32_e32 v168, v168, v170
	v_mov_b32_e32 v170, v168
	s_nop 1
	v_permlane32_swap_b32_e32 v168, v170
	v_max_f32_e32 v168, v168, v170
	v_cmp_lt_f32_e32 vcc, 0x41000000, v168
	s_cbranch_vccz .Lagqa_nors_8
	v_max_f32_e32 v170, 0, v168
	v_exp_f32_e64 v166, -v170
	v_sub_f32_e32 v218, v218, v170
	v_sub_f32_e32 v219, v219, v170
	v_sub_f32_e32 v220, v220, v170
	v_sub_f32_e32 v221, v221, v170
	v_sub_f32_e32 v222, v222, v170
	v_sub_f32_e32 v223, v223, v170
	v_sub_f32_e32 v224, v224, v170
	v_sub_f32_e32 v225, v225, v170
	v_sub_f32_e32 v226, v226, v170
	v_sub_f32_e32 v227, v227, v170
	v_sub_f32_e32 v228, v228, v170
	v_sub_f32_e32 v229, v229, v170
	v_sub_f32_e32 v230, v230, v170
	v_sub_f32_e32 v231, v231, v170
	v_sub_f32_e32 v232, v232, v170
	v_sub_f32_e32 v233, v233, v170
	v_sub_f32_e32 v32, v32, v170
	v_sub_f32_e32 v33, v33, v170
	v_sub_f32_e32 v34, v34, v170
	v_sub_f32_e32 v35, v35, v170
	v_sub_f32_e32 v36, v36, v170
	v_sub_f32_e32 v37, v37, v170
	v_sub_f32_e32 v38, v38, v170
	v_sub_f32_e32 v39, v39, v170
	v_sub_f32_e32 v40, v40, v170
	v_sub_f32_e32 v41, v41, v170
	v_sub_f32_e32 v42, v42, v170
	v_sub_f32_e32 v43, v43, v170
	v_sub_f32_e32 v44, v44, v170
	v_sub_f32_e32 v45, v45, v170
	v_sub_f32_e32 v46, v46, v170
	v_sub_f32_e32 v47, v47, v170
	v_sub_f32_e32 v48, v48, v170
	v_sub_f32_e32 v49, v49, v170
	v_sub_f32_e32 v50, v50, v170
	v_sub_f32_e32 v51, v51, v170
	v_sub_f32_e32 v52, v52, v170
	v_sub_f32_e32 v53, v53, v170
	v_sub_f32_e32 v54, v54, v170
	v_sub_f32_e32 v55, v55, v170
	v_sub_f32_e32 v56, v56, v170
	v_sub_f32_e32 v57, v57, v170
	v_sub_f32_e32 v58, v58, v170
	v_sub_f32_e32 v59, v59, v170
	v_sub_f32_e32 v60, v60, v170
	v_sub_f32_e32 v61, v61, v170
	v_sub_f32_e32 v62, v62, v170
	v_sub_f32_e32 v63, v63, v170
	s_mov_b32 s9, 1
; template <bool MLA>
; DI void attn_phase(const int TID, const int BID, LAS unsigned char* lds, const Params& p, bool need_ctx) {
;     ...
;     for (int item = BID; item < n_items; item += gridDim.x) {
;         int b, head, row0, nk;
;         if (item < 1024) {
;             const int rnd = item >> 8, w = item & 255, xcd = w & 7, slot = w >> 3, qb = slot & 7;
;             if (MLA) { const int grp = (rnd * 8 + xcd) * 4 + (slot >> 3); b = grp >> 4; head = grp & 15; }
;             else { const int grp = rnd * 8 + xcd; b = grp >> 2; head = (grp & 3) * 4 + (slot >> 3); }
;             row0 = b * 2048 + qb * 256; nk = NKEY;
;         }
;         else { const int it = item - 1024; b = it >> 4; head = it & 15; row0 = TL + b * 256; nk = 256; }
.Lagqa_nors_8:
	s_waitcnt lgkmcnt(3)
	v_mfma_f32_32x32x16_bf16 v[64:79], v[136:139], v[112:115], v[218:233]
	v_exp_f32_e32 v32, v32
	v_exp_f32_e32 v48, v48
	v_exp_f32_e32 v33, v33
	ds_read_b128 v[136:139], v243 offset:9280
	ds_read_b64_tr_b16 v[192:193], v162 offset:3072
	ds_read_b64_tr_b16 v[194:195], v162 offset:4608
	v_mfma_f32_32x32x16_bf16 v[0:15], v[184:187], v[104:107], v[0:15]
	v_exp_f32_e32 v49, v49
	v_exp_f32_e32 v34, v34
	ds_read_b64_tr_b16 v[196:197], v162 offset:3136
	ds_read_b64_tr_b16 v[198:199], v162 offset:4672
	s_waitcnt lgkmcnt(7)
	v_mfma_f32_32x32x16_bf16 v[80:95], v[140:143], v[112:115], v[218:233]
	v_exp_f32_e32 v50, v50
	v_cvt_pk_bf16_f32 v96, v32, v33
	v_exp_f32_e32 v35, v35
	ds_read_b128 v[140:143], v243 offset:13888
	ds_read_b64_tr_b16 v[200:201], v162 offset:9216
	ds_read_b64_tr_b16 v[202:203], v162 offset:10752
	v_mfma_f32_32x32x16_bf16 v[16:31], v[188:191], v[104:107], v[16:31]
	v_exp_f32_e32 v51, v51
	v_exp_f32_e32 v36, v36
	v_exp_f32_e32 v52, v52
	ds_read_b64_tr_b16 v[204:205], v162 offset:9280
	ds_read_b64_tr_b16 v[206:207], v162 offset:10816
	s_waitcnt lgkmcnt(11)
	v_mfma_f32_32x32x16_bf16 v[64:79], v[144:147], v[116:119], v[64:79]
	v_cvt_pk_bf16_f32 v97, v34, v35
	v_exp_f32_e32 v37, v37
	v_exp_f32_e32 v53, v53
	ds_read_b128 v[144:147], v243 offset:9312
	v_mfma_f32_16x16x32_bf16 v[234:237], v[246:249], v[104:107], v[234:237]
	v_cvt_pk_bf16_f32 v104, v48, v49
	v_cvt_pk_bf16_f32 v105, v50, v51
	v_exp_f32_e32 v38, v38
	v_exp_f32_e32 v54, v54
	s_waitcnt lgkmcnt(11)
	v_mfma_f32_32x32x16_bf16 v[80:95], v[148:151], v[116:119], v[80:95]
	v_cvt_pk_bf16_f32 v98, v36, v37
	v_cvt_pk_bf16_f32 v106, v52, v53
	v_exp_f32_e32 v39, v39
	v_exp_f32_e32 v55, v55
	ds_read_b128 v[148:151], v243 offset:13920
	s_waitcnt lgkmcnt(9)
	v_mfma_f32_32x32x16_bf16 v[0:15], v[192:195], v[100:103], v[0:15]
	v_exp_f32_e32 v40, v40
	v_exp_f32_e32 v56, v56
	v_cvt_pk_bf16_f32 v99, v38, v39
	v_mfma_f32_32x32x16_bf16 v[64:79], v[136:139], v[120:123], v[64:79]
	v_cvt_pk_bf16_f32 v107, v54, v55
	v_exp_f32_e32 v41, v41
	v_exp_f32_e32 v57, v57
	s_waitcnt vmcnt(0)
	ds_write_b128 v164, v[156:159]
	s_waitcnt lgkmcnt(8)
	v_mfma_f32_32x32x16_bf16 v[16:31], v[196:199], v[100:103], v[16:31]
	v_exp_f32_e32 v42, v42
	v_exp_f32_e32 v58, v58
	v_exp_f32_e32 v43, v43
	s_waitcnt lgkmcnt(7)
	v_mfma_f32_32x32x16_bf16 v[80:95], v[140:143], v[120:123], v[80:95]
	v_exp_f32_e32 v59, v59
	v_exp_f32_e32 v44, v44
	v_mfma_f32_16x16x32_bf16 v[234:237], v[246:249], v[100:103], v[234:237]
	v_cvt_pk_bf16_f32 v100, v40, v41
	v_exp_f32_e32 v60, v60
	v_cvt_pk_bf16_f32 v101, v42, v43
	v_exp_f32_e32 v45, v45
	ds_read_b64_tr_b16 v[176:177], v163 offset:0
	ds_read_b64_tr_b16 v[178:179], v163 offset:1536
	s_waitcnt lgkmcnt(4)
	v_mfma_f32_32x32x16_bf16 v[64:79], v[144:147], v[124:127], v[64:79]
	v_exp_f32_e32 v61, v61
	v_exp_f32_e32 v46, v46
	v_exp_f32_e32 v62, v62
	ds_read_b64_tr_b16 v[180:181], v163 offset:64
	ds_read_b64_tr_b16 v[182:183], v163 offset:1600
	v_mfma_f32_32x32x16_bf16 v[0:15], v[200:203], v[108:111], v[0:15]
	v_cvt_pk_bf16_f32 v102, v44, v45
	v_exp_f32_e32 v47, v47
	v_exp_f32_e32 v63, v63
	ds_read_b64_tr_b16 v[184:185], v163 offset:6144
	ds_read_b64_tr_b16 v[186:187], v163 offset:7680
	s_waitcnt lgkmcnt(7)
	v_mfma_f32_32x32x16_bf16 v[80:95], v[148:151], v[124:127], v[80:95]
	v_cvt_pk_bf16_f32 v103, v46, v47
	ds_read_b64_tr_b16 v[188:189], v163 offset:6208
	ds_read_b64_tr_b16 v[190:191], v163 offset:7744
	v_mfma_f32_32x32x16_bf16 v[16:31], v[204:207], v[108:111], v[16:31]
	v_mfma_f32_16x16x32_bf16 v[234:237], v[246:249], v[108:111], v[234:237]
	v_cvt_pk_bf16_f32 v108, v56, v57
	v_cvt_pk_bf16_f32 v109, v58, v59
	v_cvt_pk_bf16_f32 v110, v60, v61
	v_cvt_pk_bf16_f32 v111, v62, v63
	s_cmp_lg_u32 s9, 0
	s_cbranch_scc0 .Lagqa_noresc_9
	s_nop 15
	v_mul_f32_e32 v0, v0, v166
	v_mul_f32_e32 v1, v1, v166
	v_mul_f32_e32 v2, v2, v166
	v_mul_f32_e32 v3, v3, v166
	v_mul_f32_e32 v4, v4, v166
	v_mul_f32_e32 v5, v5, v166
	v_mul_f32_e32 v6, v6, v166
	v_mul_f32_e32 v7, v7, v166
	v_mul_f32_e32 v8, v8, v166
	v_mul_f32_e32 v9, v9, v166
	v_mul_f32_e32 v10, v10, v166
	v_mul_f32_e32 v11, v11, v166
	v_mul_f32_e32 v12, v12, v166
	v_mul_f32_e32 v13, v13, v166
	v_mul_f32_e32 v14, v14, v166
	v_mul_f32_e32 v15, v15, v166
	v_mul_f32_e32 v16, v16, v166
	v_mul_f32_e32 v17, v17, v166
	v_mul_f32_e32 v18, v18, v166
	v_mul_f32_e32 v19, v19, v166
	v_mul_f32_e32 v20, v20, v166
	v_mul_f32_e32 v21, v21, v166
	v_mul_f32_e32 v22, v22, v166
	v_mul_f32_e32 v23, v23, v166
	v_mul_f32_e32 v24, v24, v166
	v_mul_f32_e32 v25, v25, v166
	v_mul_f32_e32 v26, v26, v166
	v_mul_f32_e32 v27, v27, v166
	v_mul_f32_e32 v28, v28, v166
	v_mul_f32_e32 v29, v29, v166
	v_mul_f32_e32 v30, v30, v166
	v_mul_f32_e32 v31, v31, v166
	v_add_u32_e32 v170, 64, v175
	ds_bpermute_b32 v173, v170, v166
	v_mul_f32_e32 v234, v234, v166
	s_waitcnt lgkmcnt(0)
	v_mul_f32_e32 v235, v235, v173
.Lagqa_noresc_9:
	s_nop 2
	s_waitcnt lgkmcnt(8)
	s_barrier
	s_add_i32 s59, s6, s31
	s_cmp_ge_i32 s59, s8
	s_cbranch_scc1 .Lagqa_nonext
	s_cmpk_gt_i32 s59, 0x3ff
	s_cbranch_scc0 .Lagqa_mainitem_next
	s_add_i32 s21, s59, 0xfffffc00
	s_lshr_b32 s15, s21, 4
	s_and_b32 s18, s21, 15
	s_lshl_b32 s20, s15, 8
	s_add_i32 s20, s20, 0x4000
	s_mov_b32 s7, 0
	s_branch .Lagqa_decoded_next

; template <bool MLA>
; DI void attn_phase(const int TID, const int BID, LAS unsigned char* lds, const Params& p, bool need_ctx) {
;     ...
;     for (int item = BID; item < n_items; item += gridDim.x) {
;         int b, head, row0, nk;
;         if (item < 1024) {
;             const int rnd = item >> 8, w = item & 255, xcd = w & 7, slot = w >> 3, qb = slot & 7;
;             if (MLA) { const int grp = (rnd * 8 + xcd) * 4 + (slot >> 3); b = grp >> 4; head = grp & 15; }
;             else { const int grp = rnd * 8 + xcd; b = grp >> 2; head = (grp & 3) * 4 + (slot >> 3); }
;             row0 = b * 2048 + qb * 256; nk = NKEY;
;         }
;         else { const int it = item - 1024; b = it >> 4; head = it & 15; row0 = TL + b * 256; nk = 256; }
;         const int kvh = MLA ? head : (head >> 2);
;         const bf16_t* Kb = P_WSB(OFF_K) + (size_t)(b * NKV + kvh) * NKEY * 64;
;         const bf16_t* Vb = P_WSB(OFF_VT) + (size_t)(b * NKV + kvh) * NKEY * 64;
;         const bf16_t* Pb = P_WSB(OFF_KPE) + (size_t)b * NKEY * 32;
;         bf16x8 qf[NKS];
;         {
;             const bf16_t* qp = P_WSB(OFF_Q) + (size_t)(row0 + wid * 32 + r) * QS + head * DK + hh * 8;
; #pragma unroll
;             for (int ks = 0; ks < NKS; ++ks) qf[ks] = *(const bf16x8*)(qp + ks * 16);
;         }
;         u32x4 kreg, vreg; u32x2 preg = {0u, 0u};
.Lagqa_decoded_next:
	s_lshr_b32 s19, s18, 2
	s_lshl_b32 s21, s15, 2
	s_add_i32 s21, s21, s19
	s_mul_i32 s21, s21, 0x48000
	s_add_u32 s2, s26, s21
	s_addc_u32 s3, s27, 0
	v_readlane_b32 s60, v254, 36
	v_readlane_b32 s61, v254, 37
	s_add_u32 s4, s60, s21
	s_addc_u32 s5, s61, 0
	v_readlane_b32 s60, v254, 27
	v_readlane_b32 s61, v254, 28
	s_mul_i32 s21, s20, 0x800
	s_mul_i32 s55, s18, 0x80
	s_add_i32 s21, s21, s55
	s_add_u32 s12, s60, s21
	s_addc_u32 s13, s61, 0
	v_readlane_b32 s60, v254, 34
	v_readlane_b32 s61, v254, 35
	s_lshl_b32 s21, s20, 11
	s_lshl_b32 s55, s18, 7
	s_add_i32 s21, s21, s55
	s_add_u32 s62, s60, s21
	s_addc_u32 s63, s61, 0
	global_load_dwordx4 v[112:115], v171, s[12:13]
	global_load_dwordx4 v[116:119], v171, s[12:13] offset:32
	global_load_dwordx4 v[120:123], v171, s[12:13] offset:64
	global_load_dwordx4 v[124:127], v171, s[12:13] offset:96
	global_load_dwordx4 v[136:139], v167, s[2:3]
	s_add_u32 s2, s2, 0x2000
	s_addc_u32 s3, s3, 0
	global_load_dwordx4 v[140:143], v167, s[2:3]
	s_add_u32 s2, s2, 0x2000
	s_addc_u32 s3, s3, 0
	global_load_dwordx4 v[144:147], v167, s[4:5]
	s_add_u32 s4, s4, 0x2000
	s_addc_u32 s5, s5, 0
	global_load_dwordx4 v[152:155], v167, s[2:3]
	s_add_u32 s2, s2, 0x2000
	s_addc_u32 s3, s3, 0
	global_load_dwordx4 v[156:159], v167, s[4:5]
	s_add_u32 s4, s4, 0x2000
	s_addc_u32 s5, s5, 0

; #define LAS __attribute__((address_space(3)))
; DI float shx(float v, int m, int lane) { return __builtin_bit_cast(float, __builtin_amdgcn_ds_bpermute((lane ^ m) << 2, __builtin_bit_cast(int, v))); }
;     DI void operator()(const Acc& acc, const Unit& u, int wr, int wc, int fr, int fq) const {
;     ...
;         if (tile <= 4) {
;             const float* gn = tile < 4 ? qn : kn;
;             f32x4 g[2][2];
; #pragma unroll
;             for (int bj = 0; bj < 2; ++bj)
; #pragma unroll
;                 for (int n = 0; n < 2; ++n) g[bj][n] = *(const f32x4*)(gn + dbase + 16 * bj + 4 * n);
; #pragma unroll
;             for (int ai = 0; ai < 2; ++ai)
; #pragma unroll
;                 for (int m = 0; m < 4; ++m) {
;                     const int rl = ai * HALF + wr * 64 + m * 16 + fr, r = rowb + rl;
;                     float ss = 0.f;
; #pragma unroll
;                     for (int bj = 0; bj < 2; ++bj)
; #pragma unroll
;                         for (int n = 0; n < 2; ++n) { const f32x4 a = acc[ai][bj][m][n]; ss += a[0] * a[0] + a[1] * a[1] + a[2] * a[2] + a[3] * a[3]; }
;                     ss += shx(ss, 16, 16 * fq + fr); ss += shx(ss, 32, 16 * fq + fr);
;                     const float rstd = rsqrtf(ss * (1.f / 64.f) + LN_EPS);
;                     f32x4 v[2][2];
; #pragma unroll
;                     for (int bj = 0; bj < 2; ++bj)
; #pragma unroll
;                         for (int n = 0; n < 2; ++n) v[bj][n] = acc[ai][bj][m][n] * rstd * g[bj][n];
;                     if (latent) {
;                         const int s = s0 + rl, pos = (fq >> 1) ? (s & 63) : (s >> 6);
; #pragma unroll
;                         for (int n = 0; n < 2; ++n) {
;                             const LAS float* tp = tab + (pos * 16 + 8 * (fq & 1) + 4 * n) * 2;
;                             const f32x4 t0 = *(const LAS f32x4*)tp, t1 = *(const LAS f32x4*)(tp + 4);
;                             const f32x4 cs = {t0[0], t0[2], t1[0], t1[2]}, sn = {t0[1], t0[3], t1[1], t1[3]};
;                             const f32x4 x1 = v[0][n], x2 = v[1][n];
;                             v[0][n] = x1 * cs - x2 * sn; v[1][n] = x2 * cs + x1 * sn;
.LBB0_750:
	s_andn2_b64 vcc, exec, s[2:3]
	s_cbranch_vccnz .LBB0_732
	v_writelane_b32 v255, s16, 27
	s_cmp_eq_u32 s21, 4
	s_mov_b64 s[60:61], s[44:45]
	v_writelane_b32 v255, s17, 28
	s_mov_b64 s[16:17], s[42:43]
	s_mov_b32 s24, s39
	s_mov_b32 s25, s38
	s_mov_b64 s[52:53], s[36:37]
	s_cselect_b64 s[2:3], -1, 0
	v_readlane_b32 s36, v254, 11
	s_and_b64 s[4:5], s[2:3], exec
	v_readlane_b32 s37, v254, 12
	v_readlane_b32 s42, v254, 17
	v_readlane_b32 s44, v254, 19
	v_readlane_b32 s43, v254, 18
	v_readlane_b32 s45, v254, 20
	s_cselect_b32 s4, s44, s42
	v_readlane_b32 s36, v255, 19
	s_cselect_b32 s5, s45, s43
	v_readlane_b32 s37, v255, 20
	s_add_u32 s4, s4, s36
	s_addc_u32 s5, s5, s37
	v_lshlrev_b32_e32 v72, 2, v150
	global_load_dwordx4 v[68:71], v72, s[4:5] offset:16
	global_load_dwordx4 v[76:79], v72, s[4:5]
	global_load_dwordx4 v[64:67], v72, s[4:5] offset:80
	s_nop 0
	global_load_dwordx4 v[72:75], v72, s[4:5] offset:64
	v_mov_b32_e32 v172, v137
	v_mov_b32_e32 v173, v141
	v_mov_b32_e32 v170, v136
	v_mov_b32_e32 v171, v140
	v_pk_mul_f32 v[172:173], v[172:173], v[172:173]
	v_mov_b32_e32 v188, v129
	v_pk_fma_f32 v[170:171], v[170:171], v[170:171], v[172:173]
	v_mov_b32_e32 v172, v138
	v_mov_b32_e32 v173, v142
	v_pk_fma_f32 v[170:171], v[172:173], v[172:173], v[170:171]
	v_mov_b32_e32 v172, v139
	v_mov_b32_e32 v173, v143
	v_mov_b32_e32 v189, v133
	v_pk_fma_f32 v[170:171], v[172:173], v[172:173], v[170:171]
	v_mov_b32_e32 v172, v128
	v_mov_b32_e32 v173, v132
	v_pk_mul_f32 v[188:189], v[188:189], v[188:189]
	v_add_f32_e32 v170, v170, v171
	v_pk_fma_f32 v[172:173], v[172:173], v[172:173], v[188:189]
	v_mov_b32_e32 v188, v130
	v_mov_b32_e32 v189, v134
	v_pk_fma_f32 v[172:173], v[188:189], v[188:189], v[172:173]
	v_mov_b32_e32 v188, v131
	v_mov_b32_e32 v189, v135
	v_pk_fma_f32 v[172:173], v[188:189], v[188:189], v[172:173]
	s_mov_b32 s4, 0x800000
	v_add_f32_e32 v170, v173, v170
	v_add_f32_e32 v170, v172, v170
	ds_bpermute_b32 v171, v180, v170
	v_readlane_b32 s38, v254, 13
	v_readlane_b32 s39, v254, 14
	v_readlane_b32 s40, v254, 15
	v_readlane_b32 s41, v254, 16
	s_waitcnt lgkmcnt(0)
	v_add_f32_e32 v170, v170, v171
	ds_bpermute_b32 v171, v181, v170
	v_readlane_b32 s46, v254, 21
	v_readlane_b32 s47, v254, 22
	v_readlane_b32 s48, v254, 23
	v_readlane_b32 s49, v254, 24
	s_waitcnt lgkmcnt(0)
	v_add_f32_e32 v170, v170, v171
	v_fmamk_f32 v170, v170, 0x3c800000, v250
	v_cmp_gt_f32_e32 vcc, s4, v170
	v_mul_f32_e32 v171, 0x4b800000, v170
	v_readlane_b32 s50, v254, 25
	v_cndmask_b32_e32 v170, v170, v171, vcc
	v_rsq_f32_e32 v170, v170
	v_readlane_b32 s51, v254, 26
	v_mul_f32_e32 v171, 0x45800000, v170
	v_cndmask_b32_e32 v170, v170, v171, vcc
	v_pk_mul_f32 v[172:173], v[132:133], v[170:171] op_sel_hi:[1,0]
	v_pk_mul_f32 v[140:141], v[140:141], v[170:171] op_sel_hi:[1,0]
	v_pk_mul_f32 v[142:143], v[142:143], v[170:171] op_sel_hi:[1,0]
	v_pk_mul_f32 v[136:137], v[136:137], v[170:171] op_sel_hi:[1,0]
	v_pk_mul_f32 v[138:139], v[138:139], v[170:171] op_sel_hi:[1,0]
	v_pk_mul_f32 v[132:133], v[134:135], v[170:171] op_sel_hi:[1,0]
	s_andn2_b64 vcc, exec, s[58:59]
	s_waitcnt vmcnt(0)
	v_mul_f32_e32 v64, 0x3ed96d27, v64
	v_mul_f32_e32 v65, 0x3ed96d27, v65
	v_mul_f32_e32 v66, 0x3ed96d27, v66
	v_mul_f32_e32 v67, 0x3ed96d27, v67
	v_mul_f32_e32 v68, 0x3ed96d27, v68
	v_mul_f32_e32 v69, 0x3ed96d27, v69
	v_mul_f32_e32 v70, 0x3ed96d27, v70
	v_mul_f32_e32 v71, 0x3ed96d27, v71
	v_mul_f32_e32 v72, 0x3ed96d27, v72
	v_mul_f32_e32 v73, 0x3ed96d27, v73
	v_mul_f32_e32 v74, 0x3ed96d27, v74
	v_mul_f32_e32 v75, 0x3ed96d27, v75
	v_mul_f32_e32 v76, 0x3ed96d27, v76
	v_mul_f32_e32 v77, 0x3ed96d27, v77
	v_mul_f32_e32 v78, 0x3ed96d27, v78
	v_mul_f32_e32 v79, 0x3ed96d27, v79
	v_pk_mul_f32 v[138:139], v[70:71], v[138:139]
	v_pk_mul_f32 v[142:143], v[78:79], v[142:143]
	v_pk_mul_f32 v[140:141], v[76:77], v[140:141]
	v_pk_mul_f32 v[134:135], v[72:73], v[172:173]
	v_pk_mul_f32 v[172:173], v[128:129], v[170:171] op_sel_hi:[1,0]
	v_pk_mul_f32 v[128:129], v[130:131], v[170:171] op_sel_hi:[1,0]
	v_cndmask_b32_e64 v170, 0, 1, s[58:59]
	v_pk_mul_f32 v[136:137], v[68:69], v[136:137]
	v_pk_mul_f32 v[132:133], v[74:75], v[132:133]
	v_pk_mul_f32 v[128:129], v[66:67], v[128:129]
	v_pk_mul_f32 v[130:131], v[64:65], v[172:173]
	v_cmp_ne_u32_e64 s[4:5], 1, v170
	s_cbranch_vccnz .LBB0_753
	s_mov_b32 s39, s24
	s_add_i32 s24, s20, s24
	s_lshr_b32 s24, s24, 6
	v_mov_b32_e32 v170, s24
	s_mov_b64 s[44:45], s[60:61]
	v_cndmask_b32_e64 v170, v151, v170, s[44:45]
	v_lshlrev_b32_e32 v200, 7, v170
	v_add_u32_e32 v170, v185, v200
	ds_read_b128 v[188:191], v170
	ds_read_b128 v[192:195], v170 offset:16
	s_mov_b32 s38, s25
	s_waitcnt lgkmcnt(1)
	v_mov_b32_e32 v170, v189
	v_mov_b32_e32 v171, v191
	v_mov_b32_e32 v189, v190
	v_pk_mul_f32 v[172:173], v[134:135], v[170:171]
	s_waitcnt lgkmcnt(0)
	v_mov_b32_e32 v198, v193
	v_mov_b32_e32 v199, v195
	v_mov_b32_e32 v193, v194
	v_pk_mul_f32 v[134:135], v[134:135], v[188:189]
	v_pk_mul_f32 v[196:197], v[132:133], v[198:199]
	v_pk_mul_f32 v[132:133], v[132:133], v[192:193]
	v_pk_fma_f32 v[134:135], v[140:141], v[170:171], v[134:135]
	v_add_u32_e32 v170, v186, v200
	v_pk_fma_f32 v[196:197], v[142:143], v[192:193], v[196:197] neg_lo:[0,0,1] neg_hi:[0,0,1]
	v_pk_fma_f32 v[194:195], v[140:141], v[188:189], v[172:173] neg_lo:[0,0,1] neg_hi:[0,0,1]
	v_pk_fma_f32 v[132:133], v[142:143], v[198:199], v[132:133]
	ds_read_b128 v[140:143], v170
	ds_read_b128 v[188:191], v170 offset:16
	s_waitcnt lgkmcnt(1)
	v_mov_b32_e32 v170, v141
	v_mov_b32_e32 v171, v143
	v_pk_mul_f32 v[172:173], v[130:131], v[170:171]
	s_waitcnt lgkmcnt(0)
	v_mov_b32_e32 v198, v189
	v_mov_b32_e32 v199, v191
	v_mov_b32_e32 v189, v190
	v_mov_b32_e32 v141, v142
	v_pk_mul_f32 v[192:193], v[128:129], v[198:199]
	v_pk_fma_f32 v[190:191], v[136:137], v[140:141], v[172:173] neg_lo:[0,0,1] neg_hi:[0,0,1]
	v_pk_mul_f32 v[130:131], v[130:131], v[140:141]
	v_pk_mul_f32 v[128:129], v[128:129], v[188:189]
	v_pk_fma_f32 v[192:193], v[138:139], v[188:189], v[192:193] neg_lo:[0,0,1] neg_hi:[0,0,1]
	v_pk_fma_f32 v[128:129], v[138:139], v[198:199], v[128:129]
	v_pk_fma_f32 v[130:131], v[136:137], v[170:171], v[130:131]
	v_mov_b64_e32 v[136:137], v[190:191]
	v_mov_b64_e32 v[140:141], v[194:195]
	v_mov_b64_e32 v[138:139], v[192:193]
	v_mov_b64_e32 v[142:143], v[196:197]
	s_branch .LBB0_754

; DI void transpose_job(const int TID, const int BID, LAS unsigned char* lds, const float* W, int K, int Nsrc, int Npad, bf16_t* Bt, int mode, const float* kscale) {
;     ...
;     for (int t = BID; t < ntile; t += gridDim.x) {
;         const int n0 = (t / nkt) << 6, k0 = (t % nkt) << 6;
;         const int sc = srccol(mode, n0 + 4 * dq);
;         f32x4 va = {0.f, 0.f, 0.f, 0.f}, vb = va;
;         if (sc >= 0) {
;             va = *(const f32x4*)(W + (size_t)(k0 + 2 * kp) * Nsrc + sc); vb = *(const f32x4*)(W + (size_t)(k0 + 2 * kp + 1) * Nsrc + sc);
;             if (kscale) { va *= kscale[k0 + 2 * kp]; vb *= kscale[k0 + 2 * kp + 1]; }
;         }
; #pragma unroll
;         for (int e = 0; e < 4; ++e) tl[(4 * dq + e) * 33 + kp] = pk_bf16(va[e], vb[e]);
.LBB0_882:
	s_mul_hi_i32 s19, s18, 0x2aaaaaab
	s_lshr_b32 s20, s19, 31
	s_add_i32 s20, s19, s20
	s_lshl_b32 s19, s20, 6
	s_cmp_lt_i32 s19, 0
	s_mulk_i32 s20, 0xfe80
	s_cbranch_scc1 .LBB0_880
	v_or_b32_e32 v0, s19, v79
	v_lshrrev_b32_e32 v2, 5, v0
	s_mov_b32 s21, 0xaaaaaaab
	v_mul_lo_u32 v2, v2, s21
	v_add_u32_e32 v2, 0xaaaaaaaa, v2
	s_mov_b32 s21, 0x55555555
	v_cmp_gt_u32_e32 vcc, s21, v2
	v_mov_b32_e32 v1, 0x7fffffe0
	v_bitop3_b32 v1, s19, v1, v79 bitop3:0xc8
	v_cndmask_b32_e64 v4, 2, 1, vcc
	v_cndmask_b32_e64 v2, 2, 4, vcc
	v_cndmask_b32_e64 v3, 24, 16, vcc
	v_lshrrev_b32_e32 v0, v4, v0
	v_cndmask_b32_e64 v4, 4, 8, vcc
	s_add_i32 s21, s20, s16
	v_and_b32_e32 v3, v3, v10
	v_and_b32_e32 v0, v0, v4
	v_and_or_b32 v1, v2, v78, v1
	v_add_u32_e32 v8, s21, v11
	v_or3_b32 v0, v1, v3, v0
	v_mov_b64_e32 v[2:3], s[54:55]
	v_mov_b32_e32 v1, v169
	v_add_u32_e32 v6, 1, v8
	v_mad_i64_i32 v[4:5], s[22:23], v8, s95, v[2:3]
	v_lshlrev_b64 v[0:1], 2, v[0:1]
	v_mad_i64_i32 v[2:3], s[22:23], v6, s95, v[2:3]
	v_lshl_add_u64 v[4:5], v[4:5], 0, v[0:1]
	v_lshl_add_u64 v[6:7], v[2:3], 0, v[0:1]
	global_load_dwordx4 v[0:3], v[4:5], off
	s_nop 0
	global_load_dwordx4 v[4:7], v[6:7], off
	s_andn2_b64 vcc, exec, s[88:89]
	s_cbranch_vccnz .LBB0_881
	v_ashrrev_i32_e32 v9, 31, v8
	v_lshl_add_u64 v[8:9], v[8:9], 2, s[58:59]
	global_load_dwordx2 v[8:9], v[8:9], off
	s_waitcnt vmcnt(0)
	v_mul_f32_e32 v8, 0x3e16c740, v8
	v_mul_f32_e32 v9, 0x3e16c740, v9
	v_pk_mul_f32 v[2:3], v[2:3], v[8:9] op_sel_hi:[1,0]
	v_pk_mul_f32 v[0:1], v[0:1], v[8:9] op_sel_hi:[1,0]
	v_pk_mul_f32 v[6:7], v[6:7], v[8:9] op_sel:[0,1]
	v_pk_mul_f32 v[4:5], v[4:5], v[8:9] op_sel:[0,1]
	s_branch .LBB0_881
